# gridbar + scan step LDS pipelining + tile remap ph6/13 + fsub LDS read hoisting
# speedup vs baseline: 1.0062x; 1.0062x over previous
.LBB0_360:
	s_or_b64 exec, exec, s[0:1]
	ds_write_b32 v74, v2 offset:53440
	v_mul_f32_e32 v2, v5, v3
	s_movk_i32 s0, 0x80
	v_bfe_u32 v3, v2, 16, 1
	v_cmp_gt_i32_e32 vcc, s0, v68
	s_add_i32 s0, 0, 0x11000
	s_add_i32 s1, 0, 0x11300
	v_add3_u32 v2, v2, v3, s52
	v_lshl_add_u32 v6, v68, 1, 0
	v_mov_b32_e32 v4, s1
	v_mov_b32_e32 v5, s0
	flat_store_short_d16_hi v[36:37], v2 offset:8
	v_add_u32_e32 v2, 0x8800, v6
	v_add_u32_e32 v3, 0x4300, v6
	v_cndmask_b32_e32 v4, v4, v5, vcc
	v_cndmask_b32_e32 v5, v114, v115, vcc
	v_cndmask_b32_e32 v80, v3, v2, vcc
	v_add_u32_e32 v2, v6, v5
	s_waitcnt lgkmcnt(0)
	s_barrier
	ds_read_u16 v160, v2
	ds_read_b32 v164, v65 offset:53504
	v_readlane_b32 s0, v247, 11
	ds_read_b128 v[168:171], v4
	ds_read_u16 v172, v80 offset:272
	ds_read_u16 v176, v80 offset:544
	ds_read_b64 v[180:181], v65 offset:53760
	ds_read_u16 v184, v80 offset:816
	ds_read_b96 v[188:190], v65 offset:54016
	ds_read_u16 v192, v80 offset:1088
	s_waitcnt lgkmcnt(8)
	v_lshlrev_b32_e32 v7, 16, v160
	s_waitcnt lgkmcnt(6)
	v_mul_f32_e32 v7, v168, v7
	v_mul_f32_e32 v8, v164, v7
	s_waitcnt lgkmcnt(5)
	v_lshlrev_b32_e32 v2, 16, v172
	v_fma_f32 v8, v169, v2, -v8
	s_waitcnt lgkmcnt(4)
	v_lshlrev_b32_e32 v9, 16, v176
	s_waitcnt lgkmcnt(3)
	v_mul_f32_e32 v2, v7, v180
	v_fma_f32 v2, v170, v9, -v2
	v_fma_f32 v9, -v181, v8, v2
	s_waitcnt lgkmcnt(2)
	v_lshlrev_b32_e32 v10, 16, v184
	s_waitcnt lgkmcnt(1)
	v_mul_f32_e32 v2, v7, v188
	v_fma_f32 v2, v171, v10, -v2
	v_fma_f32 v2, -v8, v189, v2
	v_fma_f32 v10, -v9, v190, v2
	s_waitcnt lgkmcnt(0)
	v_lshlrev_b32_e32 v11, 16, v192
	v_mov_b32_e32 v2, s0
	v_readlane_b32 s0, v247, 10
	s_nop 1
	v_mov_b32_e32 v3, s0
	v_cndmask_b32_e32 v2, v2, v3, vcc
	ds_read_b128 v[196:199], v2
	ds_read_b128 v[200:203], v65 offset:54272
	ds_read_u16 v204, v80 offset:1360
	ds_read_b128 v[208:211], v65 offset:54528
	ds_read_b32 v212, v65 offset:54544
	ds_read_b128 v[216:219], v65 offset:54784
	ds_read_u16 v220, v80 offset:1632
	ds_read_b64 v[160:161], v65 offset:54800
	ds_read_b128 v[164:167], v65 offset:55040
	ds_read_u16 v172, v80 offset:1904
	v_readlane_b32 s0, v247, 13
	s_waitcnt lgkmcnt(8)
	v_mul_f32_e32 v12, v7, v200
	ds_read_b96 v[176:178], v65 offset:55056
	ds_read_u16 v180, v80 offset:2176
	v_fma_f32 v2, v196, v11, -v12
	v_fma_f32 v2, -v8, v201, v2
	v_fma_f32 v2, -v9, v202, v2
	v_fma_f32 v11, -v10, v203, v2
	s_waitcnt lgkmcnt(9)
	v_lshlrev_b32_e32 v2, 16, v204
	s_waitcnt lgkmcnt(8)
	v_mul_f32_e32 v12, v7, v208
	v_fma_f32 v2, v197, v2, -v12
	v_fma_f32 v2, -v8, v209, v2
	v_fma_f32 v2, -v9, v210, v2
	v_fma_f32 v2, -v10, v211, v2
	s_waitcnt lgkmcnt(7)
	v_fma_f32 v12, -v11, v212, v2
	s_waitcnt lgkmcnt(6)
	v_mul_f32_e32 v3, v7, v216
	s_waitcnt lgkmcnt(5)
	v_lshlrev_b32_e32 v2, 16, v220
	v_fma_f32 v2, v198, v2, -v3
	v_fma_f32 v2, -v8, v217, v2
	v_fma_f32 v2, -v9, v218, v2
	v_fma_f32 v4, -v10, v219, v2
	s_waitcnt lgkmcnt(4)
	v_fma_f32 v2, -v11, v160, v4
	v_fma_f32 v13, -v12, v161, v2
	s_waitcnt lgkmcnt(3)
	v_mul_f32_e32 v3, v7, v164
	s_waitcnt lgkmcnt(2)
	v_lshlrev_b32_e32 v2, 16, v172
	v_fma_f32 v2, v199, v2, -v3
	v_fma_f32 v2, -v8, v165, v2
	v_fma_f32 v2, -v9, v166, v2
	v_fma_f32 v5, -v10, v167, v2
	s_waitcnt lgkmcnt(1)
	v_fma_f32 v2, -v11, v176, v5
	v_fma_f32 v2, -v12, v177, v2
	v_fma_f32 v14, -v13, v178, v2
	s_waitcnt lgkmcnt(0)
	v_lshlrev_b32_e32 v15, 16, v180
	v_mov_b32_e32 v2, s0
	v_readlane_b32 s0, v247, 12
	s_nop 1
	v_mov_b32_e32 v3, s0
	v_cndmask_b32_e32 v2, v2, v3, vcc
	ds_read_b128 v[184:187], v2
	ds_read_b128 v[168:171], v65 offset:55296
	ds_read_b128 v[188:191], v65 offset:55312
	ds_read_u16 v192, v80 offset:2448
	ds_read_b128 v[200:203], v65 offset:55552
	ds_read_b128 v[204:207], v65 offset:55568
	ds_read_b32 v208, v65 offset:55584
	ds_read_u16 v212, v80 offset:2720
	ds_read_b128 v[220:223], v65 offset:55808
	ds_read_b128 v[216:219], v65 offset:55824
	v_readlane_b32 s0, v247, 15
	s_waitcnt lgkmcnt(8)
	v_mul_f32_e32 v16, v7, v168
	ds_read_b64 v[160:161], v65 offset:55840
	ds_read_b128 v[172:175], v65 offset:56064
	v_fma_f32 v2, v184, v15, -v16
	v_fma_f32 v2, -v8, v169, v2
	v_fma_f32 v2, -v9, v170, v2
	v_fma_f32 v2, -v10, v171, v2
	s_waitcnt lgkmcnt(9)
	v_fma_f32 v2, -v11, v188, v2
	ds_read_u16 v196, v80 offset:2992
	v_fma_f32 v2, -v12, v189, v2
	v_fma_f32 v2, -v13, v190, v2
	v_fma_f32 v15, -v14, v191, v2
	s_waitcnt lgkmcnt(9)
	v_lshlrev_b32_e32 v2, 16, v192
	ds_read_b128 v[164:167], v65 offset:56080
	s_waitcnt lgkmcnt(9)
	v_mul_f32_e32 v16, v7, v200
	ds_read_b96 v[176:178], v65 offset:56096
	v_fma_f32 v2, v185, v2, -v16
	v_fma_f32 v2, -v8, v201, v2
	v_fma_f32 v2, -v9, v202, v2
	v_fma_f32 v2, -v10, v203, v2
	s_waitcnt lgkmcnt(9)
	v_fma_f32 v2, -v11, v204, v2
	ds_read_u16 v180, v80 offset:3264
	v_fma_f32 v2, -v12, v205, v2
	v_fma_f32 v2, -v13, v206, v2
	v_fma_f32 v2, -v14, v207, v2
	s_waitcnt lgkmcnt(9)
	v_fma_f32 v16, -v15, v208, v2
	v_bfe_u32 v86, v16, 16, 1
	s_waitcnt lgkmcnt(8)
	v_lshlrev_b32_e32 v2, 16, v212
	s_waitcnt lgkmcnt(7)
	v_mul_f32_e32 v3, v7, v220
	v_fma_f32 v2, v186, v2, -v3
	v_fma_f32 v2, -v8, v221, v2
	v_fma_f32 v2, -v9, v222, v2
	v_fma_f32 v2, -v10, v223, v2
	s_waitcnt lgkmcnt(6)
	v_fma_f32 v2, -v11, v216, v2
	v_fma_f32 v2, -v12, v217, v2
	v_fma_f32 v2, -v13, v218, v2
	v_fma_f32 v4, -v14, v219, v2
	s_waitcnt lgkmcnt(5)
	v_fma_f32 v2, -v15, v160, v4
	v_fma_f32 v17, -v16, v161, v2
	s_waitcnt lgkmcnt(4)
	v_mul_f32_e32 v3, v7, v172
	v_bfe_u32 v87, v17, 16, 1
	s_waitcnt lgkmcnt(3)
	v_lshlrev_b32_e32 v2, 16, v196
	v_fma_f32 v2, v187, v2, -v3
	v_fma_f32 v2, -v8, v173, v2
	v_fma_f32 v2, -v9, v174, v2
	v_fma_f32 v18, -v10, v175, v2
	s_waitcnt lgkmcnt(2)
	v_fma_f32 v2, -v11, v164, v18
	v_fma_f32 v2, -v12, v165, v2
	v_fma_f32 v2, -v13, v166, v2
	v_fma_f32 v5, -v14, v167, v2
	s_waitcnt lgkmcnt(1)
	v_fma_f32 v2, -v15, v176, v5
	v_fma_f32 v2, -v16, v177, v2
	v_fma_f32 v18, -v17, v178, v2
	v_bfe_u32 v88, v18, 16, 1
	s_waitcnt lgkmcnt(0)
	v_lshlrev_b32_e32 v19, 16, v180
	v_mov_b32_e32 v2, s0
	v_readlane_b32 s0, v247, 14
	s_nop 1
	v_mov_b32_e32 v3, s0
	v_cndmask_b32_e32 v2, v2, v3, vcc
	ds_read_b128 v[168:171], v2
	ds_read_b128 v[188:191], v65 offset:56320
	ds_read_b128 v[192:195], v65 offset:56336
	ds_read_b128 v[200:203], v65 offset:56352
	ds_read_u16 v204, v80 offset:3536
	ds_read_b128 v[208:211], v65 offset:56576
	ds_read_b128 v[212:215], v65 offset:56592
	ds_read_b32 v220, v65 offset:56624
	ds_read_b128 v[216:219], v65 offset:56608
	ds_read_u16 v160, v80 offset:3808
	v_readlane_b32 s0, v247, 18
	s_waitcnt lgkmcnt(8)
	v_mul_f32_e32 v20, v7, v188
	ds_read_b128 v[196:199], v65 offset:56832
	ds_read_b128 v[184:187], v65 offset:56848
	v_fma_f32 v2, v168, v19, -v20
	v_fma_f32 v2, -v8, v189, v2
	v_fma_f32 v2, -v9, v190, v2
	v_fma_f32 v2, -v10, v191, v2
	s_waitcnt lgkmcnt(9)
	v_fma_f32 v2, -v11, v192, v2
	ds_read_b128 v[172:175], v65 offset:56864
	v_fma_f32 v2, -v12, v193, v2
	v_fma_f32 v2, -v13, v194, v2
	v_fma_f32 v2, -v14, v195, v2
	s_waitcnt lgkmcnt(9)
	v_fma_f32 v2, -v15, v200, v2
	ds_read_b64 v[164:165], v65 offset:56880
	v_fma_f32 v2, -v16, v201, v2
	v_fma_f32 v2, -v17, v202, v2
	v_fma_f32 v19, -v18, v203, v2
	v_bfe_u32 v89, v19, 16, 1
	s_waitcnt lgkmcnt(9)
	v_lshlrev_b32_e32 v2, 16, v204
	ds_read_b128 v[176:179], v65 offset:57088
	s_waitcnt lgkmcnt(9)
	v_mul_f32_e32 v20, v7, v208
	ds_read_u16 v180, v80 offset:4080
	v_fma_f32 v2, v169, v2, -v20
	v_fma_f32 v2, -v8, v209, v2
	v_fma_f32 v2, -v9, v210, v2
	v_fma_f32 v2, -v10, v211, v2
	s_waitcnt lgkmcnt(9)
	v_fma_f32 v2, -v11, v212, v2
	ds_read_b128 v[188:191], v65 offset:57104
	v_fma_f32 v2, -v12, v213, v2
	v_fma_f32 v2, -v13, v214, v2
	v_fma_f32 v2, -v14, v215, v2
	s_waitcnt lgkmcnt(8)
	v_fma_f32 v2, -v15, v216, v2
	ds_read_b128 v[192:195], v65 offset:57120
	ds_read_b96 v[200:202], v65 offset:57136
	v_fma_f32 v2, -v16, v217, v2
	v_fma_f32 v2, -v17, v218, v2
	v_fma_f32 v2, -v18, v219, v2
	v_fma_f32 v20, -v19, v220, v2
	v_bfe_u32 v90, v20, 16, 1
	s_waitcnt lgkmcnt(9)
	v_lshlrev_b32_e32 v2, 16, v160
	ds_read_u16 v204, v80 offset:4352
	s_waitcnt lgkmcnt(9)
	v_mul_f32_e32 v3, v7, v196
	v_fma_f32 v2, v170, v2, -v3
	v_fma_f32 v2, -v8, v197, v2
	v_fma_f32 v2, -v9, v198, v2
	v_fma_f32 v2, -v10, v199, v2
	s_waitcnt lgkmcnt(8)
	v_fma_f32 v2, -v11, v184, v2
	v_fma_f32 v2, -v12, v185, v2
	v_fma_f32 v2, -v13, v186, v2
	v_fma_f32 v2, -v14, v187, v2
	s_waitcnt lgkmcnt(7)
	v_fma_f32 v2, -v15, v172, v2
	v_fma_f32 v2, -v16, v173, v2
	v_fma_f32 v2, -v17, v174, v2
	v_fma_f32 v4, -v18, v175, v2
	s_waitcnt lgkmcnt(6)
	v_fma_f32 v2, -v19, v164, v4
	v_fma_f32 v21, -v20, v165, v2
	s_waitcnt lgkmcnt(5)
	v_mul_f32_e32 v3, v7, v176
	v_bfe_u32 v91, v21, 16, 1
	s_waitcnt lgkmcnt(4)
	v_lshlrev_b32_e32 v2, 16, v180
	v_fma_f32 v2, v171, v2, -v3
	v_fma_f32 v2, -v8, v177, v2
	v_fma_f32 v2, -v9, v178, v2
	v_fma_f32 v22, -v10, v179, v2
	s_waitcnt lgkmcnt(3)
	v_fma_f32 v2, -v11, v188, v22
	v_fma_f32 v2, -v12, v189, v2
	v_fma_f32 v2, -v13, v190, v2
	v_fma_f32 v22, -v14, v191, v2
	s_waitcnt lgkmcnt(2)
	v_fma_f32 v2, -v15, v192, v22
	v_fma_f32 v2, -v16, v193, v2
	v_fma_f32 v2, -v17, v194, v2
	v_fma_f32 v5, -v18, v195, v2
	s_waitcnt lgkmcnt(1)
	v_fma_f32 v2, -v19, v200, v5
	v_fma_f32 v2, -v20, v201, v2
	v_fma_f32 v22, -v21, v202, v2
	v_bfe_u32 v92, v22, 16, 1
	s_waitcnt lgkmcnt(0)
	v_lshlrev_b32_e32 v23, 16, v204
	v_mov_b32_e32 v2, s0
	v_readlane_b32 s0, v247, 16
	s_nop 1
	v_mov_b32_e32 v3, s0
	v_cndmask_b32_e32 v2, v2, v3, vcc
	ds_read_b128 v[208:211], v2
	ds_read_b128 v[212:215], v65 offset:57344
	ds_read_b128 v[216:219], v65 offset:57360
	ds_read_b128 v[220:223], v65 offset:57376
	ds_read_b128 v[160:163], v65 offset:57392
	ds_read_u16 v196, v80 offset:4624
	ds_read_b128 v[184:187], v65 offset:57600
	ds_read_b128 v[172:175], v65 offset:57616
	ds_read_b32 v164, v65 offset:57664
	ds_read_b128 v[180:183], v65 offset:57632
	v_readlane_b32 s0, v247, 20
	s_waitcnt lgkmcnt(8)
	v_mul_f32_e32 v24, v7, v212
	ds_read_b128 v[168:171], v65 offset:57648
	ds_read_u16 v176, v80 offset:4896
	v_fma_f32 v2, v208, v23, -v24
	v_fma_f32 v2, -v8, v213, v2
	v_fma_f32 v2, -v9, v214, v2
	v_fma_f32 v2, -v10, v215, v2
	s_waitcnt lgkmcnt(9)
	v_fma_f32 v2, -v11, v216, v2
	ds_read_b128 v[188:191], v65 offset:57856
	v_fma_f32 v2, -v12, v217, v2
	v_fma_f32 v2, -v13, v218, v2
	v_fma_f32 v2, -v14, v219, v2
	s_waitcnt lgkmcnt(9)
	v_fma_f32 v2, -v15, v220, v2
	ds_read_b128 v[192:195], v65 offset:57872
	v_fma_f32 v2, -v16, v221, v2
	v_fma_f32 v2, -v17, v222, v2
	v_fma_f32 v2, -v18, v223, v2
	s_waitcnt lgkmcnt(9)
	v_fma_f32 v2, -v19, v160, v2
	ds_read_b128 v[200:203], v65 offset:57888
	v_fma_f32 v2, -v20, v161, v2
	v_fma_f32 v2, -v21, v162, v2
	v_fma_f32 v23, -v22, v163, v2
	v_bfe_u32 v93, v23, 16, 1
	s_waitcnt lgkmcnt(9)
	v_lshlrev_b32_e32 v2, 16, v196
	ds_read_b128 v[204:207], v65 offset:57904
	s_waitcnt lgkmcnt(9)
	v_mul_f32_e32 v24, v7, v184
	ds_read_b64 v[212:213], v65 offset:57920
	v_fma_f32 v2, v209, v2, -v24
	v_fma_f32 v2, -v8, v185, v2
	v_fma_f32 v2, -v9, v186, v2
	v_fma_f32 v2, -v10, v187, v2
	s_waitcnt lgkmcnt(9)
	v_fma_f32 v2, -v11, v172, v2
	ds_read_b128 v[216:219], v65 offset:58112
	v_fma_f32 v2, -v12, v173, v2
	v_fma_f32 v2, -v13, v174, v2
	v_fma_f32 v2, -v14, v175, v2
	s_waitcnt lgkmcnt(8)
	v_fma_f32 v2, -v15, v180, v2
	ds_read_u16 v220, v80 offset:5168
	ds_read_b128 v[160:163], v65 offset:58128
	v_fma_f32 v2, -v16, v181, v2
	v_fma_f32 v2, -v17, v182, v2
	v_fma_f32 v2, -v18, v183, v2
	s_waitcnt lgkmcnt(9)
	v_fma_f32 v2, -v19, v168, v2
	ds_read_b128 v[196:199], v65 offset:58144
	v_fma_f32 v2, -v20, v169, v2
	v_fma_f32 v2, -v21, v170, v2
	v_fma_f32 v2, -v22, v171, v2
	v_fma_f32 v24, -v23, v164, v2
	v_bfe_u32 v94, v24, 16, 1
	s_waitcnt lgkmcnt(9)
	v_lshlrev_b32_e32 v2, 16, v176
	ds_read_b128 v[184:187], v65 offset:58160
	s_waitcnt lgkmcnt(9)
	v_mul_f32_e32 v3, v7, v188
	ds_read_b96 v[172:174], v65 offset:58176
	v_fma_f32 v2, v210, v2, -v3
	v_fma_f32 v2, -v8, v189, v2
	v_fma_f32 v2, -v9, v190, v2
	v_fma_f32 v2, -v10, v191, v2
	s_waitcnt lgkmcnt(9)
	v_fma_f32 v2, -v11, v192, v2
	ds_read_u16 v180, v80 offset:5440
	v_fma_f32 v2, -v12, v193, v2
	v_fma_f32 v2, -v13, v194, v2
	v_fma_f32 v2, -v14, v195, v2
	s_waitcnt lgkmcnt(9)
	v_fma_f32 v2, -v15, v200, v2
	v_fma_f32 v2, -v16, v201, v2
	v_fma_f32 v2, -v17, v202, v2
	v_fma_f32 v2, -v18, v203, v2
	s_waitcnt lgkmcnt(8)
	v_fma_f32 v2, -v19, v204, v2
	v_fma_f32 v2, -v20, v205, v2
	v_fma_f32 v2, -v21, v206, v2
	v_fma_f32 v4, -v22, v207, v2
	s_waitcnt lgkmcnt(7)
	v_fma_f32 v2, -v23, v212, v4
	v_fma_f32 v25, -v24, v213, v2
	s_waitcnt lgkmcnt(6)
	v_mul_f32_e32 v3, v7, v216
	v_bfe_u32 v95, v25, 16, 1
	s_waitcnt lgkmcnt(5)
	v_lshlrev_b32_e32 v2, 16, v220
	v_fma_f32 v2, v211, v2, -v3
	v_fma_f32 v2, -v8, v217, v2
	v_fma_f32 v2, -v9, v218, v2
	v_fma_f32 v26, -v10, v219, v2
	s_waitcnt lgkmcnt(4)
	v_fma_f32 v2, -v11, v160, v26
	v_fma_f32 v2, -v12, v161, v2
	v_fma_f32 v2, -v13, v162, v2
	v_fma_f32 v26, -v14, v163, v2
	s_waitcnt lgkmcnt(3)
	v_fma_f32 v2, -v15, v196, v26
	v_fma_f32 v2, -v16, v197, v2
	v_fma_f32 v2, -v17, v198, v2
	v_fma_f32 v26, -v18, v199, v2
	s_waitcnt lgkmcnt(2)
	v_fma_f32 v2, -v19, v184, v26
	v_fma_f32 v2, -v20, v185, v2
	v_fma_f32 v2, -v21, v186, v2
	v_fma_f32 v5, -v22, v187, v2
	s_waitcnt lgkmcnt(1)
	v_fma_f32 v2, -v23, v172, v5
	v_fma_f32 v2, -v24, v173, v2
	v_fma_f32 v26, -v25, v174, v2
	v_bfe_u32 v96, v26, 16, 1
	s_waitcnt lgkmcnt(0)
	v_lshlrev_b32_e32 v27, 16, v180
	v_mov_b32_e32 v2, s0
	v_readlane_b32 s0, v247, 19
	s_nop 1
	v_mov_b32_e32 v3, s0
	v_cndmask_b32_e32 v2, v2, v3, vcc
	ds_read_b128 v[168:171], v2
	ds_read_b128 v[164:167], v65 offset:58368
	ds_read_b128 v[176:179], v65 offset:58384
	ds_read_b128 v[188:191], v65 offset:58400
	ds_read_b128 v[192:195], v65 offset:58416
	ds_read_b128 v[200:203], v65 offset:58432
	ds_read_u16 v204, v80 offset:5712
	ds_read_b128 v[212:215], v65 offset:58624
	ds_read_b128 v[220:223], v65 offset:58640
	ds_read_b32 v208, v65 offset:58704
	v_readlane_b32 s0, v247, 22
	s_waitcnt lgkmcnt(8)
	v_mul_f32_e32 v28, v7, v164
	ds_read_b128 v[216:219], v65 offset:58656
	ds_read_b128 v[160:163], v65 offset:58672
	v_fma_f32 v2, v168, v27, -v28
	v_fma_f32 v2, -v8, v165, v2
	v_fma_f32 v2, -v9, v166, v2
	v_fma_f32 v2, -v10, v167, v2
	s_waitcnt lgkmcnt(9)
	v_fma_f32 v2, -v11, v176, v2
	ds_read_b128 v[196:199], v65 offset:58688
	v_fma_f32 v2, -v12, v177, v2
	v_fma_f32 v2, -v13, v178, v2
	v_fma_f32 v2, -v14, v179, v2
	s_waitcnt lgkmcnt(9)
	v_fma_f32 v2, -v15, v188, v2
	ds_read_u16 v184, v80 offset:5984
	v_fma_f32 v2, -v16, v189, v2
	v_fma_f32 v2, -v17, v190, v2
	v_fma_f32 v2, -v18, v191, v2
	s_waitcnt lgkmcnt(9)
	v_fma_f32 v2, -v19, v192, v2
	ds_read_b128 v[172:175], v65 offset:58880
	v_fma_f32 v2, -v20, v193, v2
	v_fma_f32 v2, -v21, v194, v2
	v_fma_f32 v2, -v22, v195, v2
	s_waitcnt lgkmcnt(9)
	v_fma_f32 v2, -v23, v200, v2
	ds_read_b128 v[180:183], v65 offset:58896
	v_fma_f32 v2, -v24, v201, v2
	v_fma_f32 v2, -v25, v202, v2
	v_fma_f32 v27, -v26, v203, v2
	v_bfe_u32 v97, v27, 16, 1
	s_waitcnt lgkmcnt(9)
	v_lshlrev_b32_e32 v2, 16, v204
	ds_read_b128 v[164:167], v65 offset:58912
	s_waitcnt lgkmcnt(9)
	v_mul_f32_e32 v28, v7, v212
	ds_read_b128 v[176:179], v65 offset:58928
	v_fma_f32 v2, v169, v2, -v28
	v_fma_f32 v2, -v8, v213, v2
	v_fma_f32 v2, -v9, v214, v2
	v_fma_f32 v2, -v10, v215, v2
	s_waitcnt lgkmcnt(9)
	v_fma_f32 v2, -v11, v220, v2
	ds_read_b128 v[188:191], v65 offset:58944
	v_fma_f32 v2, -v12, v221, v2
	v_fma_f32 v2, -v13, v222, v2
	v_fma_f32 v2, -v14, v223, v2
	s_waitcnt lgkmcnt(8)
	v_fma_f32 v2, -v15, v216, v2
	ds_read_b64 v[192:193], v65 offset:58960
	ds_read_b128 v[200:203], v65 offset:59136
	v_fma_f32 v2, -v16, v217, v2
	v_fma_f32 v2, -v17, v218, v2
	v_fma_f32 v2, -v18, v219, v2
	s_waitcnt lgkmcnt(9)
	v_fma_f32 v2, -v19, v160, v2
	ds_read_u16 v204, v80 offset:6256
	v_fma_f32 v2, -v20, v161, v2
	v_fma_f32 v2, -v21, v162, v2
	v_fma_f32 v2, -v22, v163, v2
	s_waitcnt lgkmcnt(9)
	v_fma_f32 v2, -v23, v196, v2
	ds_read_b128 v[212:215], v65 offset:59152
	v_fma_f32 v2, -v24, v197, v2
	v_fma_f32 v2, -v25, v198, v2
	v_fma_f32 v2, -v26, v199, v2
	v_fma_f32 v28, -v27, v208, v2
	v_bfe_u32 v98, v28, 16, 1
	s_waitcnt lgkmcnt(9)
	v_lshlrev_b32_e32 v2, 16, v184
	ds_read_b128 v[220:223], v65 offset:59168
	s_waitcnt lgkmcnt(9)
	v_mul_f32_e32 v3, v7, v172
	ds_read_b128 v[216:219], v65 offset:59184
	v_fma_f32 v2, v170, v2, -v3
	v_fma_f32 v2, -v8, v173, v2
	v_fma_f32 v2, -v9, v174, v2
	v_fma_f32 v2, -v10, v175, v2
	s_waitcnt lgkmcnt(9)
	v_fma_f32 v2, -v11, v180, v2
	ds_read_b128 v[160:163], v65 offset:59200
	v_fma_f32 v2, -v12, v181, v2
	v_fma_f32 v2, -v13, v182, v2
	v_fma_f32 v2, -v14, v183, v2
	s_waitcnt lgkmcnt(9)
	v_fma_f32 v2, -v15, v164, v2
	ds_read_b96 v[196:198], v65 offset:59216
	v_fma_f32 v2, -v16, v165, v2
	v_fma_f32 v2, -v17, v166, v2
	v_fma_f32 v2, -v18, v167, v2
	s_waitcnt lgkmcnt(9)
	v_fma_f32 v2, -v19, v176, v2
	ds_read_u16 v208, v80 offset:6528
	v_fma_f32 v2, -v20, v177, v2
	v_fma_f32 v2, -v21, v178, v2
	v_fma_f32 v2, -v22, v179, v2
	s_waitcnt lgkmcnt(9)
	v_fma_f32 v2, -v23, v188, v2
	v_fma_f32 v2, -v24, v189, v2
	v_fma_f32 v2, -v25, v190, v2
	v_fma_f32 v4, -v26, v191, v2
	s_waitcnt lgkmcnt(8)
	v_fma_f32 v2, -v27, v192, v4
	v_fma_f32 v29, -v28, v193, v2
	s_waitcnt lgkmcnt(7)
	v_mul_f32_e32 v3, v7, v200
	v_bfe_u32 v116, v29, 16, 1
	s_waitcnt lgkmcnt(6)
	v_lshlrev_b32_e32 v2, 16, v204
	v_fma_f32 v2, v171, v2, -v3
	v_fma_f32 v2, -v8, v201, v2
	v_fma_f32 v2, -v9, v202, v2
	v_fma_f32 v30, -v10, v203, v2
	s_waitcnt lgkmcnt(5)
	v_fma_f32 v2, -v11, v212, v30
	v_fma_f32 v2, -v12, v213, v2
	v_fma_f32 v2, -v13, v214, v2
	v_fma_f32 v30, -v14, v215, v2
	s_waitcnt lgkmcnt(4)
	v_fma_f32 v2, -v15, v220, v30
	v_fma_f32 v2, -v16, v221, v2
	v_fma_f32 v2, -v17, v222, v2
	v_fma_f32 v30, -v18, v223, v2
	s_waitcnt lgkmcnt(3)
	v_fma_f32 v2, -v19, v216, v30
	v_fma_f32 v2, -v20, v217, v2
	v_fma_f32 v2, -v21, v218, v2
	v_fma_f32 v30, -v22, v219, v2
	s_waitcnt lgkmcnt(2)
	v_fma_f32 v2, -v23, v160, v30
	v_fma_f32 v2, -v24, v161, v2
	v_fma_f32 v2, -v25, v162, v2
	v_fma_f32 v5, -v26, v163, v2
	s_waitcnt lgkmcnt(1)
	v_fma_f32 v2, -v27, v196, v5
	v_fma_f32 v2, -v28, v197, v2
	v_fma_f32 v30, -v29, v198, v2
	v_bfe_u32 v117, v30, 16, 1
	s_waitcnt lgkmcnt(0)
	v_lshlrev_b32_e32 v31, 16, v208
	v_mov_b32_e32 v2, s0
	v_readlane_b32 s0, v247, 21
	s_nop 1
	v_mov_b32_e32 v3, s0
	v_cndmask_b32_e32 v2, v2, v3, vcc
	ds_read_b128 v[184:187], v2
	ds_read_b128 v[172:175], v65 offset:59392
	ds_read_b128 v[180:183], v65 offset:59408
	ds_read_b128 v[164:167], v65 offset:59424
	ds_read_b128 v[176:179], v65 offset:59440
	ds_read_b128 v[188:191], v65 offset:59456
	ds_read_b128 v[192:195], v65 offset:59472
	ds_read_u16 v204, v80 offset:6800
	ds_read_b128 v[168:171], v65 offset:59648
	ds_read_b128 v[200:203], v65 offset:59664
	v_readlane_b32 s0, v247, 24
	s_waitcnt lgkmcnt(8)
	v_mul_f32_e32 v32, v7, v172
	ds_read_b32 v212, v65 offset:59744
	ds_read_b128 v[220:223], v65 offset:59680
	v_fma_f32 v2, v184, v31, -v32
	v_fma_f32 v2, -v8, v173, v2
	v_fma_f32 v2, -v9, v174, v2
	v_fma_f32 v2, -v10, v175, v2
	s_waitcnt lgkmcnt(9)
	v_fma_f32 v2, -v11, v180, v2
	ds_read_b128 v[216:219], v65 offset:59696
	v_fma_f32 v2, -v12, v181, v2
	v_fma_f32 v2, -v13, v182, v2
	v_fma_f32 v2, -v14, v183, v2
	s_waitcnt lgkmcnt(9)
	v_fma_f32 v2, -v15, v164, v2
	ds_read_b128 v[160:163], v65 offset:59712
	v_fma_f32 v2, -v16, v165, v2
	v_fma_f32 v2, -v17, v166, v2
	v_fma_f32 v2, -v18, v167, v2
	s_waitcnt lgkmcnt(9)
	v_fma_f32 v2, -v19, v176, v2
	ds_read_b128 v[196:199], v65 offset:59728
	v_fma_f32 v2, -v20, v177, v2
	v_fma_f32 v2, -v21, v178, v2
	v_fma_f32 v2, -v22, v179, v2
	s_waitcnt lgkmcnt(9)
	v_fma_f32 v2, -v23, v188, v2
	ds_read_u16 v208, v80 offset:7072
	v_fma_f32 v2, -v24, v189, v2
	v_fma_f32 v2, -v25, v190, v2
	v_fma_f32 v2, -v26, v191, v2
	s_waitcnt lgkmcnt(9)
	v_fma_f32 v2, -v27, v192, v2
	ds_read_b128 v[172:175], v65 offset:59904
	v_fma_f32 v2, -v28, v193, v2
	v_fma_f32 v2, -v29, v194, v2
	v_fma_f32 v31, -v30, v195, v2
	v_bfe_u32 v118, v31, 16, 1
	s_waitcnt lgkmcnt(9)
	v_lshlrev_b32_e32 v2, 16, v204
	ds_read_b128 v[180:183], v65 offset:59920
	s_waitcnt lgkmcnt(9)
	v_mul_f32_e32 v32, v7, v168
	ds_read_b128 v[164:167], v65 offset:59936
	v_fma_f32 v2, v185, v2, -v32
	v_fma_f32 v2, -v8, v169, v2
	v_fma_f32 v2, -v9, v170, v2
	v_fma_f32 v2, -v10, v171, v2
	s_waitcnt lgkmcnt(9)
	v_fma_f32 v2, -v11, v200, v2
	ds_read_b128 v[176:179], v65 offset:59952
	v_fma_f32 v2, -v12, v201, v2
	v_fma_f32 v2, -v13, v202, v2
	v_fma_f32 v2, -v14, v203, v2
	s_waitcnt lgkmcnt(8)
	v_fma_f32 v2, -v15, v220, v2
	ds_read_b128 v[188:191], v65 offset:59968
	ds_read_b128 v[192:195], v65 offset:59984
	v_fma_f32 v2, -v16, v221, v2
	v_fma_f32 v2, -v17, v222, v2
	v_fma_f32 v2, -v18, v223, v2
	s_waitcnt lgkmcnt(9)
	v_fma_f32 v2, -v19, v216, v2
	ds_read_b64 v[204:205], v65 offset:60000
	v_fma_f32 v2, -v20, v217, v2
	v_fma_f32 v2, -v21, v218, v2
	v_fma_f32 v2, -v22, v219, v2
	s_waitcnt lgkmcnt(9)
	v_fma_f32 v2, -v23, v160, v2
	ds_read_b128 v[168:171], v65 offset:60160
	v_fma_f32 v2, -v24, v161, v2
	v_fma_f32 v2, -v25, v162, v2
	v_fma_f32 v2, -v26, v163, v2
	s_waitcnt lgkmcnt(9)
	v_fma_f32 v2, -v27, v196, v2
	ds_read_u16 v200, v80 offset:7344
	v_fma_f32 v2, -v28, v197, v2
	v_fma_f32 v2, -v29, v198, v2
	v_fma_f32 v2, -v30, v199, v2
	v_fma_f32 v32, -v31, v212, v2
	v_bfe_u32 v119, v32, 16, 1
	s_waitcnt lgkmcnt(9)
	v_lshlrev_b32_e32 v2, 16, v208
	ds_read_b128 v[220:223], v65 offset:60176
	s_waitcnt lgkmcnt(9)
	v_mul_f32_e32 v3, v7, v172
	ds_read_b128 v[216:219], v65 offset:60192
	v_fma_f32 v2, v186, v2, -v3
	v_fma_f32 v2, -v8, v173, v2
	v_fma_f32 v2, -v9, v174, v2
	v_fma_f32 v2, -v10, v175, v2
	s_waitcnt lgkmcnt(9)
	v_fma_f32 v2, -v11, v180, v2
	ds_read_b128 v[160:163], v65 offset:60208
	v_fma_f32 v2, -v12, v181, v2
	v_fma_f32 v2, -v13, v182, v2
	v_fma_f32 v2, -v14, v183, v2
	s_waitcnt lgkmcnt(9)
	v_fma_f32 v2, -v15, v164, v2
	ds_read_b128 v[196:199], v65 offset:60224
	v_fma_f32 v2, -v16, v165, v2
	v_fma_f32 v2, -v17, v166, v2
	v_fma_f32 v2, -v18, v167, v2
	s_waitcnt lgkmcnt(9)
	v_fma_f32 v2, -v19, v176, v2
	ds_read_b128 v[212:215], v65 offset:60240
	v_fma_f32 v2, -v20, v177, v2
	v_fma_f32 v2, -v21, v178, v2
	v_fma_f32 v2, -v22, v179, v2
	s_waitcnt lgkmcnt(9)
	v_fma_f32 v2, -v23, v188, v2
	ds_read_b96 v[208:210], v65 offset:60256
	v_fma_f32 v2, -v24, v189, v2
	v_fma_f32 v2, -v25, v190, v2
	v_fma_f32 v2, -v26, v191, v2
	s_waitcnt lgkmcnt(9)
	v_fma_f32 v2, -v27, v192, v2
	ds_read_u16 v172, v80 offset:7616
	v_fma_f32 v2, -v28, v193, v2
	v_fma_f32 v2, -v29, v194, v2
	v_fma_f32 v4, -v30, v195, v2
	s_waitcnt lgkmcnt(9)
	v_fma_f32 v2, -v31, v204, v4
	v_fma_f32 v33, -v32, v205, v2
	s_waitcnt lgkmcnt(8)
	v_mul_f32_e32 v3, v7, v168
	v_bfe_u32 v120, v33, 16, 1
	s_waitcnt lgkmcnt(7)
	v_lshlrev_b32_e32 v2, 16, v200
	v_fma_f32 v2, v187, v2, -v3
	v_fma_f32 v2, -v8, v169, v2
	v_fma_f32 v2, -v9, v170, v2
	v_fma_f32 v34, -v10, v171, v2
	s_waitcnt lgkmcnt(6)
	v_fma_f32 v2, -v11, v220, v34
	v_fma_f32 v2, -v12, v221, v2
	v_fma_f32 v2, -v13, v222, v2
	v_fma_f32 v34, -v14, v223, v2
	s_waitcnt lgkmcnt(5)
	v_fma_f32 v2, -v15, v216, v34
	v_fma_f32 v2, -v16, v217, v2
	v_fma_f32 v2, -v17, v218, v2
	v_fma_f32 v34, -v18, v219, v2
	s_waitcnt lgkmcnt(4)
	v_fma_f32 v2, -v19, v160, v34
	v_fma_f32 v2, -v20, v161, v2
	v_fma_f32 v2, -v21, v162, v2
	v_fma_f32 v34, -v22, v163, v2
	s_waitcnt lgkmcnt(3)
	v_fma_f32 v2, -v23, v196, v34
	v_fma_f32 v2, -v24, v197, v2
	v_fma_f32 v2, -v25, v198, v2
	v_fma_f32 v34, -v26, v199, v2
	s_waitcnt lgkmcnt(2)
	v_fma_f32 v2, -v27, v212, v34
	v_fma_f32 v2, -v28, v213, v2
	v_fma_f32 v2, -v29, v214, v2
	v_fma_f32 v5, -v30, v215, v2
	s_waitcnt lgkmcnt(1)
	v_fma_f32 v2, -v31, v208, v5
	v_fma_f32 v2, -v32, v209, v2
	v_fma_f32 v34, -v33, v210, v2
	v_bfe_u32 v121, v34, 16, 1
	s_waitcnt lgkmcnt(0)
	v_lshlrev_b32_e32 v35, 16, v172
	v_mov_b32_e32 v2, s0
	v_readlane_b32 s0, v247, 23
	s_nop 1
	v_mov_b32_e32 v3, s0
	v_cndmask_b32_e32 v2, v2, v3, vcc
	ds_read_b128 v[180:183], v2
	ds_read_b128 v[164:167], v65 offset:60416
	ds_read_b128 v[176:179], v65 offset:60432
	ds_read_b128 v[188:191], v65 offset:60448
	ds_read_b128 v[192:195], v65 offset:60464
	ds_read_b128 v[204:207], v65 offset:60480
	ds_read_b128 v[200:203], v65 offset:60496
	ds_read_b128 v[184:187], v65 offset:60512
	ds_read_u16 v168, v80 offset:7888
	ds_read_b128 v[220:223], v65 offset:60672
	v_readlane_b32 s0, v247, 26
	s_waitcnt lgkmcnt(8)
	v_mul_f32_e32 v36, v7, v164
	ds_read_b128 v[216:219], v65 offset:60688
	ds_read_b32 v160, v65 offset:60784
	v_fma_f32 v2, v180, v35, -v36
	v_fma_f32 v2, -v8, v165, v2
	v_fma_f32 v2, -v9, v166, v2
	v_fma_f32 v2, -v10, v167, v2
	s_waitcnt lgkmcnt(9)
	v_fma_f32 v2, -v11, v176, v2
	ds_read_b128 v[196:199], v65 offset:60704
	v_fma_f32 v2, -v12, v177, v2
	v_fma_f32 v2, -v13, v178, v2
	v_fma_f32 v2, -v14, v179, v2
	s_waitcnt lgkmcnt(9)
	v_fma_f32 v2, -v15, v188, v2
	ds_read_b128 v[212:215], v65 offset:60720
	v_fma_f32 v2, -v16, v189, v2
	v_fma_f32 v2, -v17, v190, v2
	v_fma_f32 v2, -v18, v191, v2
	s_waitcnt lgkmcnt(9)
	v_fma_f32 v2, -v19, v192, v2
	ds_read_b128 v[208:211], v65 offset:60736
	v_fma_f32 v2, -v20, v193, v2
	v_fma_f32 v2, -v21, v194, v2
	v_fma_f32 v2, -v22, v195, v2
	s_waitcnt lgkmcnt(9)
	v_fma_f32 v2, -v23, v204, v2
	ds_read_b128 v[172:175], v65 offset:60752
	v_fma_f32 v2, -v24, v205, v2
	v_fma_f32 v2, -v25, v206, v2
	v_fma_f32 v2, -v26, v207, v2
	s_waitcnt lgkmcnt(9)
	v_fma_f32 v2, -v27, v200, v2
	ds_read_b128 v[164:167], v65 offset:60768
	v_fma_f32 v2, -v28, v201, v2
	v_fma_f32 v2, -v29, v202, v2
	v_fma_f32 v2, -v30, v203, v2
	s_waitcnt lgkmcnt(9)
	v_fma_f32 v2, -v31, v184, v2
	ds_read_u16 v176, v80 offset:8160
	v_fma_f32 v2, -v32, v185, v2
	v_fma_f32 v2, -v33, v186, v2
	v_fma_f32 v35, -v34, v187, v2
	v_bfe_u32 v122, v35, 16, 1
	s_waitcnt lgkmcnt(9)
	v_lshlrev_b32_e32 v2, 16, v168
	ds_read_b128 v[188:191], v65 offset:60928
	s_waitcnt lgkmcnt(9)
	v_mul_f32_e32 v36, v7, v220
	ds_read_b128 v[192:195], v65 offset:60944
	v_fma_f32 v2, v181, v2, -v36
	v_fma_f32 v2, -v8, v221, v2
	v_fma_f32 v2, -v9, v222, v2
	v_fma_f32 v2, -v10, v223, v2
	s_waitcnt lgkmcnt(9)
	v_fma_f32 v2, -v11, v216, v2
	ds_read_b128 v[204:207], v65 offset:60960
	v_fma_f32 v2, -v12, v217, v2
	v_fma_f32 v2, -v13, v218, v2
	v_fma_f32 v2, -v14, v219, v2
	s_waitcnt lgkmcnt(8)
	v_fma_f32 v2, -v15, v196, v2
	ds_read_b128 v[200:203], v65 offset:60976
	ds_read_b128 v[184:187], v65 offset:60992
	v_fma_f32 v2, -v16, v197, v2
	v_fma_f32 v2, -v17, v198, v2
	v_fma_f32 v2, -v18, v199, v2
	s_waitcnt lgkmcnt(9)
	v_fma_f32 v2, -v19, v212, v2
	ds_read_b128 v[168:171], v65 offset:61008
	v_fma_f32 v2, -v20, v213, v2
	v_fma_f32 v2, -v21, v214, v2
	v_fma_f32 v2, -v22, v215, v2
	s_waitcnt lgkmcnt(9)
	v_fma_f32 v2, -v23, v208, v2
	ds_read_b128 v[220:223], v65 offset:61024
	v_fma_f32 v2, -v24, v209, v2
	v_fma_f32 v2, -v25, v210, v2
	v_fma_f32 v2, -v26, v211, v2
	s_waitcnt lgkmcnt(9)
	v_fma_f32 v2, -v27, v172, v2
	ds_read_b64 v[216:217], v65 offset:61040
	v_fma_f32 v2, -v28, v173, v2
	v_fma_f32 v2, -v29, v174, v2
	v_fma_f32 v2, -v30, v175, v2
	s_waitcnt lgkmcnt(9)
	v_fma_f32 v2, -v31, v164, v2
	ds_read_b128 v[196:199], v65 offset:61184
	v_fma_f32 v2, -v32, v165, v2
	v_fma_f32 v2, -v33, v166, v2
	v_fma_f32 v2, -v34, v167, v2
	v_fma_f32 v36, -v35, v160, v2
	v_bfe_u32 v123, v36, 16, 1
	s_waitcnt lgkmcnt(9)
	v_lshlrev_b32_e32 v2, 16, v176
	ds_read_u16 v212, v80 offset:8432
	s_waitcnt lgkmcnt(9)
	v_mul_f32_e32 v3, v7, v188
	ds_read_b128 v[208:211], v65 offset:61200
	v_fma_f32 v2, v182, v2, -v3
	v_fma_f32 v2, -v8, v189, v2
	v_fma_f32 v2, -v9, v190, v2
	v_fma_f32 v2, -v10, v191, v2
	s_waitcnt lgkmcnt(9)
	v_fma_f32 v2, -v11, v192, v2
	ds_read_b128 v[172:175], v65 offset:61216
	v_fma_f32 v2, -v12, v193, v2
	v_fma_f32 v2, -v13, v194, v2
	v_fma_f32 v2, -v14, v195, v2
	s_waitcnt lgkmcnt(9)
	v_fma_f32 v2, -v15, v204, v2
	ds_read_b128 v[164:167], v65 offset:61232
	v_fma_f32 v2, -v16, v205, v2
	v_fma_f32 v2, -v17, v206, v2
	v_fma_f32 v2, -v18, v207, v2
	s_waitcnt lgkmcnt(9)
	v_fma_f32 v2, -v19, v200, v2
	ds_read_b128 v[160:163], v65 offset:61248
	v_fma_f32 v2, -v20, v201, v2
	v_fma_f32 v2, -v21, v202, v2
	v_fma_f32 v2, -v22, v203, v2
	s_waitcnt lgkmcnt(9)
	v_fma_f32 v2, -v23, v184, v2
	ds_read_b128 v[176:179], v65 offset:61264
	v_fma_f32 v2, -v24, v185, v2
	v_fma_f32 v2, -v25, v186, v2
	v_fma_f32 v2, -v26, v187, v2
	s_waitcnt lgkmcnt(9)
	v_fma_f32 v2, -v27, v168, v2
	ds_read_b128 v[188:191], v65 offset:61280
	v_fma_f32 v2, -v28, v169, v2
	v_fma_f32 v2, -v29, v170, v2
	v_fma_f32 v2, -v30, v171, v2
	s_waitcnt lgkmcnt(9)
	v_fma_f32 v2, -v31, v220, v2
	ds_read_b96 v[192:194], v65 offset:61296
	v_fma_f32 v2, -v32, v221, v2
	v_fma_f32 v2, -v33, v222, v2
	v_fma_f32 v4, -v34, v223, v2
	s_waitcnt lgkmcnt(9)
	v_fma_f32 v2, -v35, v216, v4
	ds_read_u16 v204, v80 offset:8704
	v_fma_f32 v37, -v36, v217, v2
	s_waitcnt lgkmcnt(9)
	v_mul_f32_e32 v3, v7, v196
	v_bfe_u32 v124, v37, 16, 1
	s_waitcnt lgkmcnt(8)
	v_lshlrev_b32_e32 v2, 16, v212
	v_fma_f32 v2, v183, v2, -v3
	v_fma_f32 v2, -v8, v197, v2
	v_fma_f32 v2, -v9, v198, v2
	v_fma_f32 v38, -v10, v199, v2
	s_waitcnt lgkmcnt(7)
	v_fma_f32 v2, -v11, v208, v38
	v_fma_f32 v2, -v12, v209, v2
	v_fma_f32 v2, -v13, v210, v2
	v_fma_f32 v38, -v14, v211, v2
	s_waitcnt lgkmcnt(6)
	v_fma_f32 v2, -v15, v172, v38
	v_fma_f32 v2, -v16, v173, v2
	v_fma_f32 v2, -v17, v174, v2
	v_fma_f32 v38, -v18, v175, v2
	s_waitcnt lgkmcnt(5)
	v_fma_f32 v2, -v19, v164, v38
	v_fma_f32 v2, -v20, v165, v2
	v_fma_f32 v2, -v21, v166, v2
	v_fma_f32 v38, -v22, v167, v2
	s_waitcnt lgkmcnt(4)
	v_fma_f32 v2, -v23, v160, v38
	v_fma_f32 v2, -v24, v161, v2
	v_fma_f32 v2, -v25, v162, v2
	v_fma_f32 v38, -v26, v163, v2
	s_waitcnt lgkmcnt(3)
	v_fma_f32 v2, -v27, v176, v38
	v_fma_f32 v2, -v28, v177, v2
	v_fma_f32 v2, -v29, v178, v2
	v_fma_f32 v38, -v30, v179, v2
	s_waitcnt lgkmcnt(2)
	v_fma_f32 v2, -v31, v188, v38
	v_fma_f32 v2, -v32, v189, v2
	v_fma_f32 v2, -v33, v190, v2
	v_fma_f32 v5, -v34, v191, v2
	s_waitcnt lgkmcnt(1)
	v_fma_f32 v2, -v35, v192, v5
	v_fma_f32 v2, -v36, v193, v2
	v_fma_f32 v38, -v37, v194, v2
	v_bfe_u32 v125, v38, 16, 1
	s_waitcnt lgkmcnt(0)
	v_lshlrev_b32_e32 v39, 16, v204
	v_mov_b32_e32 v2, s0
	v_readlane_b32 s0, v247, 25
	s_nop 1
	v_mov_b32_e32 v3, s0
	v_cndmask_b32_e32 v2, v2, v3, vcc
	ds_read_b128 v[200:203], v2
	ds_read_b128 v[184:187], v65 offset:61440
	ds_read_b128 v[168:171], v65 offset:61456
	ds_read_b128 v[220:223], v65 offset:61472
	ds_read_b128 v[216:219], v65 offset:61488
	ds_read_b128 v[212:215], v65 offset:61504
	ds_read_b128 v[180:183], v65 offset:61520
	ds_read_b128 v[196:199], v65 offset:61536
	ds_read_b128 v[208:211], v65 offset:61552
	ds_read_u16 v172, v80 offset:8976
	v_readlane_b32 s0, v247, 28
	s_waitcnt lgkmcnt(8)
	v_mul_f32_e32 v40, v7, v184
	ds_read_b128 v[164:167], v65 offset:61696
	ds_read_b128 v[160:163], v65 offset:61712
	v_fma_f32 v2, v200, v39, -v40
	v_fma_f32 v2, -v8, v185, v2
	v_fma_f32 v2, -v9, v186, v2
	v_fma_f32 v2, -v10, v187, v2
	s_waitcnt lgkmcnt(9)
	v_fma_f32 v2, -v11, v168, v2
	ds_read_b32 v176, v65 offset:61824
	v_fma_f32 v2, -v12, v169, v2
	v_fma_f32 v2, -v13, v170, v2
	v_fma_f32 v2, -v14, v171, v2
	s_waitcnt lgkmcnt(9)
	v_fma_f32 v2, -v15, v220, v2
	ds_read_b128 v[188:191], v65 offset:61728
	v_fma_f32 v2, -v16, v221, v2
	v_fma_f32 v2, -v17, v222, v2
	v_fma_f32 v2, -v18, v223, v2
	s_waitcnt lgkmcnt(9)
	v_fma_f32 v2, -v19, v216, v2
	ds_read_b128 v[192:195], v65 offset:61744
	v_fma_f32 v2, -v20, v217, v2
	v_fma_f32 v2, -v21, v218, v2
	v_fma_f32 v2, -v22, v219, v2
	s_waitcnt lgkmcnt(9)
	v_fma_f32 v2, -v23, v212, v2
	ds_read_b128 v[204:207], v65 offset:61760
	v_fma_f32 v2, -v24, v213, v2
	v_fma_f32 v2, -v25, v214, v2
	v_fma_f32 v2, -v26, v215, v2
	s_waitcnt lgkmcnt(9)
	v_fma_f32 v2, -v27, v180, v2
	ds_read_b128 v[184:187], v65 offset:61776
	v_fma_f32 v2, -v28, v181, v2
	v_fma_f32 v2, -v29, v182, v2
	v_fma_f32 v2, -v30, v183, v2
	s_waitcnt lgkmcnt(9)
	v_fma_f32 v2, -v31, v196, v2
	ds_read_b128 v[168:171], v65 offset:61792
	v_fma_f32 v2, -v32, v197, v2
	v_fma_f32 v2, -v33, v198, v2
	v_fma_f32 v2, -v34, v199, v2
	s_waitcnt lgkmcnt(9)
	v_fma_f32 v2, -v35, v208, v2
	ds_read_b128 v[220:223], v65 offset:61808
	v_fma_f32 v2, -v36, v209, v2
	v_fma_f32 v2, -v37, v210, v2
	v_fma_f32 v39, -v38, v211, v2
	v_bfe_u32 v126, v39, 16, 1
	s_waitcnt lgkmcnt(9)
	v_lshlrev_b32_e32 v2, 16, v172
	ds_read_u16 v216, v80 offset:9248
	s_waitcnt lgkmcnt(9)
	v_mul_f32_e32 v40, v7, v164
	ds_read_b128 v[212:215], v65 offset:61952
	v_fma_f32 v2, v201, v2, -v40
	v_fma_f32 v2, -v8, v165, v2
	v_fma_f32 v2, -v9, v166, v2
	v_fma_f32 v2, -v10, v167, v2
	s_waitcnt lgkmcnt(9)
	v_fma_f32 v2, -v11, v160, v2
	ds_read_b128 v[180:183], v65 offset:61968
	v_fma_f32 v2, -v12, v161, v2
	v_fma_f32 v2, -v13, v162, v2
	v_fma_f32 v2, -v14, v163, v2
	s_waitcnt lgkmcnt(8)
	v_fma_f32 v2, -v15, v188, v2
	ds_read_b128 v[196:199], v65 offset:61984
	ds_read_b128 v[208:211], v65 offset:62000
	v_fma_f32 v2, -v16, v189, v2
	v_fma_f32 v2, -v17, v190, v2
	v_fma_f32 v2, -v18, v191, v2
	s_waitcnt lgkmcnt(9)
	v_fma_f32 v2, -v19, v192, v2
	ds_read_b128 v[172:175], v65 offset:62016
	v_fma_f32 v2, -v20, v193, v2
	v_fma_f32 v2, -v21, v194, v2
	v_fma_f32 v2, -v22, v195, v2
	s_waitcnt lgkmcnt(9)
	v_fma_f32 v2, -v23, v204, v2
	ds_read_b128 v[164:167], v65 offset:62032
	v_fma_f32 v2, -v24, v205, v2
	v_fma_f32 v2, -v25, v206, v2
	v_fma_f32 v2, -v26, v207, v2
	s_waitcnt lgkmcnt(9)
	v_fma_f32 v2, -v27, v184, v2
	ds_read_b128 v[160:163], v65 offset:62048
	v_fma_f32 v2, -v28, v185, v2
	v_fma_f32 v2, -v29, v186, v2
	v_fma_f32 v2, -v30, v187, v2
	s_waitcnt lgkmcnt(9)
	v_fma_f32 v2, -v31, v168, v2
	ds_read_b128 v[188:191], v65 offset:62064
	v_fma_f32 v2, -v32, v169, v2
	v_fma_f32 v2, -v33, v170, v2
	v_fma_f32 v2, -v34, v171, v2
	s_waitcnt lgkmcnt(9)
	v_fma_f32 v2, -v35, v220, v2
	ds_read_b64 v[192:193], v65 offset:62080
	v_fma_f32 v2, -v36, v221, v2
	v_fma_f32 v2, -v37, v222, v2
	v_fma_f32 v2, -v38, v223, v2
	v_fma_f32 v40, -v39, v176, v2
	v_bfe_u32 v127, v40, 16, 1
	s_waitcnt lgkmcnt(9)
	v_lshlrev_b32_e32 v2, 16, v216
	ds_read_b128 v[204:207], v65 offset:62208
	s_waitcnt lgkmcnt(9)
	v_mul_f32_e32 v3, v7, v212
	ds_read_u16 v184, v80 offset:9520
	v_fma_f32 v2, v202, v2, -v3
	v_fma_f32 v2, -v8, v213, v2
	v_fma_f32 v2, -v9, v214, v2
	v_fma_f32 v2, -v10, v215, v2
	s_waitcnt lgkmcnt(9)
	v_fma_f32 v2, -v11, v180, v2
	ds_read_b128 v[168:171], v65 offset:62224
	v_fma_f32 v2, -v12, v181, v2
	v_fma_f32 v2, -v13, v182, v2
	v_fma_f32 v2, -v14, v183, v2
	s_waitcnt lgkmcnt(9)
	v_fma_f32 v2, -v15, v196, v2
	ds_read_b128 v[220:223], v65 offset:62240
	v_fma_f32 v2, -v16, v197, v2
	v_fma_f32 v2, -v17, v198, v2
	v_fma_f32 v2, -v18, v199, v2
	s_waitcnt lgkmcnt(9)
	v_fma_f32 v2, -v19, v208, v2
	ds_read_b128 v[176:179], v65 offset:62256
	v_fma_f32 v2, -v20, v209, v2
	v_fma_f32 v2, -v21, v210, v2
	v_fma_f32 v2, -v22, v211, v2
	s_waitcnt lgkmcnt(9)
	v_fma_f32 v2, -v23, v172, v2
	ds_read_b128 v[216:219], v65 offset:62272
	v_fma_f32 v2, -v24, v173, v2
	v_fma_f32 v2, -v25, v174, v2
	v_fma_f32 v2, -v26, v175, v2
	s_waitcnt lgkmcnt(9)
	v_fma_f32 v2, -v27, v164, v2
	ds_read_b128 v[212:215], v65 offset:62288
	v_fma_f32 v2, -v28, v165, v2
	v_fma_f32 v2, -v29, v166, v2
	v_fma_f32 v2, -v30, v167, v2
	s_waitcnt lgkmcnt(9)
	v_fma_f32 v2, -v31, v160, v2
	ds_read_b128 v[180:183], v65 offset:62304
	v_fma_f32 v2, -v32, v161, v2
	v_fma_f32 v2, -v33, v162, v2
	v_fma_f32 v2, -v34, v163, v2
	s_waitcnt lgkmcnt(9)
	v_fma_f32 v2, -v35, v188, v2
	ds_read_b128 v[196:199], v65 offset:62320
	v_fma_f32 v2, -v36, v189, v2
	v_fma_f32 v2, -v37, v190, v2
	v_fma_f32 v4, -v38, v191, v2
	s_waitcnt lgkmcnt(9)
	v_fma_f32 v2, -v39, v192, v4
	ds_read_b96 v[208:210], v65 offset:62336
	v_fma_f32 v41, -v40, v193, v2
	s_waitcnt lgkmcnt(9)
	v_mul_f32_e32 v3, v7, v204
	ds_read_u16 v172, v80 offset:9792
	v_bfe_u32 v128, v41, 16, 1
	s_waitcnt lgkmcnt(9)
	v_lshlrev_b32_e32 v2, 16, v184
	v_fma_f32 v2, v203, v2, -v3
	v_fma_f32 v2, -v8, v205, v2
	v_fma_f32 v2, -v9, v206, v2
	v_fma_f32 v44, -v10, v207, v2
	s_waitcnt lgkmcnt(8)
	v_fma_f32 v2, -v11, v168, v44
	v_fma_f32 v2, -v12, v169, v2
	v_fma_f32 v2, -v13, v170, v2
	v_fma_f32 v44, -v14, v171, v2
	s_waitcnt lgkmcnt(7)
	v_fma_f32 v2, -v15, v220, v44
	v_fma_f32 v2, -v16, v221, v2
	v_fma_f32 v2, -v17, v222, v2
	v_fma_f32 v44, -v18, v223, v2
	s_waitcnt lgkmcnt(6)
	v_fma_f32 v2, -v19, v176, v44
	v_fma_f32 v2, -v20, v177, v2
	v_fma_f32 v2, -v21, v178, v2
	v_fma_f32 v44, -v22, v179, v2
	s_waitcnt lgkmcnt(5)
	v_fma_f32 v2, -v23, v216, v44
	v_fma_f32 v2, -v24, v217, v2
	v_fma_f32 v2, -v25, v218, v2
	v_fma_f32 v44, -v26, v219, v2
	s_waitcnt lgkmcnt(4)
	v_fma_f32 v2, -v27, v212, v44
	v_fma_f32 v2, -v28, v213, v2
	v_fma_f32 v2, -v29, v214, v2
	v_fma_f32 v44, -v30, v215, v2
	s_waitcnt lgkmcnt(3)
	v_fma_f32 v2, -v31, v180, v44
	v_fma_f32 v2, -v32, v181, v2
	v_fma_f32 v2, -v33, v182, v2
	v_fma_f32 v44, -v34, v183, v2
	s_waitcnt lgkmcnt(2)
	v_fma_f32 v2, -v35, v196, v44
	v_fma_f32 v2, -v36, v197, v2
	v_fma_f32 v2, -v37, v198, v2
	v_fma_f32 v5, -v38, v199, v2
	s_waitcnt lgkmcnt(1)
	v_fma_f32 v2, -v39, v208, v5
	v_fma_f32 v2, -v40, v209, v2
	v_fma_f32 v44, -v41, v210, v2
	v_bfe_u32 v129, v44, 16, 1
	s_waitcnt lgkmcnt(0)
	v_lshlrev_b32_e32 v45, 16, v172
	v_mov_b32_e32 v2, s0
	v_readlane_b32 s0, v247, 27
	s_nop 1
	v_mov_b32_e32 v3, s0
	v_cndmask_b32_e32 v2, v2, v3, vcc
	ds_read_b128 v[164:167], v2
	ds_read_b128 v[160:163], v65 offset:62464
	ds_read_b128 v[188:191], v65 offset:62480
	ds_read_b128 v[192:195], v65 offset:62496
	ds_read_b128 v[184:187], v65 offset:62512
	ds_read_b128 v[200:203], v65 offset:62528
	ds_read_b128 v[204:207], v65 offset:62544
	ds_read_b128 v[168:171], v65 offset:62560
	ds_read_b128 v[220:223], v65 offset:62576
	ds_read_b128 v[176:179], v65 offset:62592
	v_readlane_b32 s0, v247, 30
	s_waitcnt lgkmcnt(8)
	v_mul_f32_e32 v46, v7, v160
	ds_read_u16 v216, v80 offset:10064
	ds_read_b128 v[212:215], v65 offset:62720
	v_fma_f32 v2, v164, v45, -v46
	v_fma_f32 v2, -v8, v161, v2
	v_fma_f32 v2, -v9, v162, v2
	v_fma_f32 v2, -v10, v163, v2
	s_waitcnt lgkmcnt(9)
	v_fma_f32 v2, -v11, v188, v2
	ds_read_b128 v[180:183], v65 offset:62736
	v_fma_f32 v2, -v12, v189, v2
	v_fma_f32 v2, -v13, v190, v2
	v_fma_f32 v2, -v14, v191, v2
	s_waitcnt lgkmcnt(9)
	v_fma_f32 v2, -v15, v192, v2
	ds_read_b32 v196, v65 offset:62864
	v_fma_f32 v2, -v16, v193, v2
	v_fma_f32 v2, -v17, v194, v2
	v_fma_f32 v2, -v18, v195, v2
	s_waitcnt lgkmcnt(9)
	v_fma_f32 v2, -v19, v184, v2
	ds_read_b128 v[208:211], v65 offset:62752
	v_fma_f32 v2, -v20, v185, v2
	v_fma_f32 v2, -v21, v186, v2
	v_fma_f32 v2, -v22, v187, v2
	s_waitcnt lgkmcnt(9)
	v_fma_f32 v2, -v23, v200, v2
	ds_read_b128 v[172:175], v65 offset:62768
	v_fma_f32 v2, -v24, v201, v2
	v_fma_f32 v2, -v25, v202, v2
	v_fma_f32 v2, -v26, v203, v2
	s_waitcnt lgkmcnt(9)
	v_fma_f32 v2, -v27, v204, v2
	ds_read_b128 v[160:163], v65 offset:62784
	v_fma_f32 v2, -v28, v205, v2
	v_fma_f32 v2, -v29, v206, v2
	v_fma_f32 v2, -v30, v207, v2
	s_waitcnt lgkmcnt(9)
	v_fma_f32 v2, -v31, v168, v2
	ds_read_b128 v[188:191], v65 offset:62800
	v_fma_f32 v2, -v32, v169, v2
	v_fma_f32 v2, -v33, v170, v2
	v_fma_f32 v2, -v34, v171, v2
	s_waitcnt lgkmcnt(9)
	v_fma_f32 v2, -v35, v220, v2
	ds_read_b128 v[192:195], v65 offset:62816
	v_fma_f32 v2, -v36, v221, v2
	v_fma_f32 v2, -v37, v222, v2
	v_fma_f32 v2, -v38, v223, v2
	s_waitcnt lgkmcnt(9)
	v_fma_f32 v2, -v39, v176, v2
	ds_read_b128 v[184:187], v65 offset:62832
	v_fma_f32 v2, -v40, v177, v2
	v_fma_f32 v2, -v41, v178, v2
	v_fma_f32 v45, -v44, v179, v2
	v_bfe_u32 v130, v45, 16, 1
	s_waitcnt lgkmcnt(9)
	v_lshlrev_b32_e32 v2, 16, v216
	ds_read_b128 v[200:203], v65 offset:62848
	s_waitcnt lgkmcnt(9)
	v_mul_f32_e32 v46, v7, v212
	ds_read_u16 v204, v80 offset:10336
	v_fma_f32 v2, v165, v2, -v46
	v_fma_f32 v2, -v8, v213, v2
	v_fma_f32 v2, -v9, v214, v2
	v_fma_f32 v2, -v10, v215, v2
	s_waitcnt lgkmcnt(9)
	v_fma_f32 v2, -v11, v180, v2
	ds_read_b128 v[168:171], v65 offset:62976
	v_fma_f32 v2, -v12, v181, v2
	v_fma_f32 v2, -v13, v182, v2
	v_fma_f32 v2, -v14, v183, v2
	s_waitcnt lgkmcnt(8)
	v_fma_f32 v2, -v15, v208, v2
	ds_read_b128 v[220:223], v65 offset:62992
	ds_read_b128 v[176:179], v65 offset:63008
	v_fma_f32 v2, -v16, v209, v2
	v_fma_f32 v2, -v17, v210, v2
	v_fma_f32 v2, -v18, v211, v2
	s_waitcnt lgkmcnt(9)
	v_fma_f32 v2, -v19, v172, v2
	ds_read_b128 v[216:219], v65 offset:63024
	v_fma_f32 v2, -v20, v173, v2
	v_fma_f32 v2, -v21, v174, v2
	v_fma_f32 v2, -v22, v175, v2
	s_waitcnt lgkmcnt(9)
	v_fma_f32 v2, -v23, v160, v2
	ds_read_b128 v[212:215], v65 offset:63040
	v_fma_f32 v2, -v24, v161, v2
	v_fma_f32 v2, -v25, v162, v2
	v_fma_f32 v2, -v26, v163, v2
	s_waitcnt lgkmcnt(9)
	v_fma_f32 v2, -v27, v188, v2
	ds_read_b128 v[180:183], v65 offset:63056
	v_fma_f32 v2, -v28, v189, v2
	v_fma_f32 v2, -v29, v190, v2
	v_fma_f32 v2, -v30, v191, v2
	s_waitcnt lgkmcnt(9)
	v_fma_f32 v2, -v31, v192, v2
	ds_read_b128 v[208:211], v65 offset:63072
	v_fma_f32 v2, -v32, v193, v2
	v_fma_f32 v2, -v33, v194, v2
	v_fma_f32 v2, -v34, v195, v2
	s_waitcnt lgkmcnt(9)
	v_fma_f32 v2, -v35, v184, v2
	ds_read_b128 v[172:175], v65 offset:63088
	v_fma_f32 v2, -v36, v185, v2
	v_fma_f32 v2, -v37, v186, v2
	v_fma_f32 v2, -v38, v187, v2
	s_waitcnt lgkmcnt(9)
	v_fma_f32 v2, -v39, v200, v2
	ds_read_b128 v[160:163], v65 offset:63104
	v_fma_f32 v2, -v40, v201, v2
	v_fma_f32 v2, -v41, v202, v2
	v_fma_f32 v2, -v44, v203, v2
	v_fma_f32 v46, -v45, v196, v2
	v_bfe_u32 v131, v46, 16, 1
	s_waitcnt lgkmcnt(9)
	v_lshlrev_b32_e32 v2, 16, v204
	ds_read_b64 v[188:189], v65 offset:63120
	s_waitcnt lgkmcnt(9)
	v_mul_f32_e32 v3, v7, v168
	ds_read_b128 v[192:195], v65 offset:63232
	v_fma_f32 v2, v166, v2, -v3
	v_fma_f32 v2, -v8, v169, v2
	v_fma_f32 v2, -v9, v170, v2
	v_fma_f32 v2, -v10, v171, v2
	s_waitcnt lgkmcnt(9)
	v_fma_f32 v2, -v11, v220, v2
	ds_read_u16 v184, v80 offset:10608
	v_fma_f32 v2, -v12, v221, v2
	v_fma_f32 v2, -v13, v222, v2
	v_fma_f32 v2, -v14, v223, v2
	s_waitcnt lgkmcnt(9)
	v_fma_f32 v2, -v15, v176, v2
	ds_read_b128 v[200:203], v65 offset:63248
	v_fma_f32 v2, -v16, v177, v2
	v_fma_f32 v2, -v17, v178, v2
	v_fma_f32 v2, -v18, v179, v2
	s_waitcnt lgkmcnt(9)
	v_fma_f32 v2, -v19, v216, v2
	ds_read_b128 v[196:199], v65 offset:63264
	v_fma_f32 v2, -v20, v217, v2
	v_fma_f32 v2, -v21, v218, v2
	v_fma_f32 v2, -v22, v219, v2
	s_waitcnt lgkmcnt(9)
	v_fma_f32 v2, -v23, v212, v2
	ds_read_b128 v[204:207], v65 offset:63280
	v_fma_f32 v2, -v24, v213, v2
	v_fma_f32 v2, -v25, v214, v2
	v_fma_f32 v2, -v26, v215, v2
	s_waitcnt lgkmcnt(9)
	v_fma_f32 v2, -v27, v180, v2
	ds_read_b128 v[168:171], v65 offset:63296
	v_fma_f32 v2, -v28, v181, v2
	v_fma_f32 v2, -v29, v182, v2
	v_fma_f32 v2, -v30, v183, v2
	s_waitcnt lgkmcnt(9)
	v_fma_f32 v2, -v31, v208, v2
	ds_read_b128 v[220:223], v65 offset:63312
	v_fma_f32 v2, -v32, v209, v2
	v_fma_f32 v2, -v33, v210, v2
	v_fma_f32 v2, -v34, v211, v2
	s_waitcnt lgkmcnt(9)
	v_fma_f32 v2, -v35, v172, v2
	ds_read_b128 v[176:179], v65 offset:63328
	v_fma_f32 v2, -v36, v173, v2
	v_fma_f32 v2, -v37, v174, v2
	v_fma_f32 v2, -v38, v175, v2
	s_waitcnt lgkmcnt(9)
	v_fma_f32 v2, -v39, v160, v2
	ds_read_b128 v[216:219], v65 offset:63344
	v_fma_f32 v2, -v40, v161, v2
	v_fma_f32 v2, -v41, v162, v2
	v_fma_f32 v4, -v44, v163, v2
	s_waitcnt lgkmcnt(9)
	v_fma_f32 v2, -v45, v188, v4
	ds_read_b128 v[212:215], v65 offset:63360
	v_fma_f32 v47, -v46, v189, v2
	s_waitcnt lgkmcnt(9)
	v_mul_f32_e32 v3, v7, v192
	ds_read_b96 v[180:182], v65 offset:63376
	v_bfe_u32 v132, v47, 16, 1
	s_waitcnt lgkmcnt(9)
	v_lshlrev_b32_e32 v2, 16, v184
	ds_read_u16 v208, v80 offset:10880
	v_fma_f32 v2, v167, v2, -v3
	v_fma_f32 v2, -v8, v193, v2
	v_fma_f32 v2, -v9, v194, v2
	v_fma_f32 v48, -v10, v195, v2
	s_waitcnt lgkmcnt(9)
	v_fma_f32 v2, -v11, v200, v48
	v_fma_f32 v2, -v12, v201, v2
	v_fma_f32 v2, -v13, v202, v2
	v_fma_f32 v48, -v14, v203, v2
	s_waitcnt lgkmcnt(8)
	v_fma_f32 v2, -v15, v196, v48
	v_fma_f32 v2, -v16, v197, v2
	v_fma_f32 v2, -v17, v198, v2
	v_fma_f32 v48, -v18, v199, v2
	s_waitcnt lgkmcnt(7)
	v_fma_f32 v2, -v19, v204, v48
	v_fma_f32 v2, -v20, v205, v2
	v_fma_f32 v2, -v21, v206, v2
	v_fma_f32 v48, -v22, v207, v2
	s_waitcnt lgkmcnt(6)
	v_fma_f32 v2, -v23, v168, v48
	v_fma_f32 v2, -v24, v169, v2
	v_fma_f32 v2, -v25, v170, v2
	v_fma_f32 v48, -v26, v171, v2
	s_waitcnt lgkmcnt(5)
	v_fma_f32 v2, -v27, v220, v48
	v_fma_f32 v2, -v28, v221, v2
	v_fma_f32 v2, -v29, v222, v2
	v_fma_f32 v48, -v30, v223, v2
	s_waitcnt lgkmcnt(4)
	v_fma_f32 v2, -v31, v176, v48
	v_fma_f32 v2, -v32, v177, v2
	v_fma_f32 v2, -v33, v178, v2
	v_fma_f32 v48, -v34, v179, v2
	s_waitcnt lgkmcnt(3)
	v_fma_f32 v2, -v35, v216, v48
	v_fma_f32 v2, -v36, v217, v2
	v_fma_f32 v2, -v37, v218, v2
	v_fma_f32 v48, -v38, v219, v2
	s_waitcnt lgkmcnt(2)
	v_fma_f32 v2, -v39, v212, v48
	v_fma_f32 v2, -v40, v213, v2
	v_fma_f32 v2, -v41, v214, v2
	v_fma_f32 v5, -v44, v215, v2
	s_waitcnt lgkmcnt(1)
	v_fma_f32 v2, -v45, v180, v5
	v_fma_f32 v2, -v46, v181, v2
	v_fma_f32 v48, -v47, v182, v2
	v_bfe_u32 v133, v48, 16, 1
	s_waitcnt lgkmcnt(0)
	v_lshlrev_b32_e32 v49, 16, v208
	v_mov_b32_e32 v2, s0
	v_readlane_b32 s0, v247, 29
	s_nop 1
	v_mov_b32_e32 v3, s0
	v_cndmask_b32_e32 v2, v2, v3, vcc
	ds_read_b128 v[172:175], v2
	ds_read_b128 v[160:163], v65 offset:63488
	ds_read_b128 v[188:191], v65 offset:64000
	ds_read_b128 v[184:187], v65 offset:63504
	ds_read_b128 v[164:167], v65 offset:63520
	ds_read_b128 v[192:195], v65 offset:63536
	ds_read_b128 v[200:203], v65 offset:63552
	ds_read_b128 v[196:199], v65 offset:63568
	ds_read_b128 v[204:207], v65 offset:63584
	ds_read_b128 v[168:171], v65 offset:63600
	v_readlane_b32 s0, v247, 32
	s_waitcnt lgkmcnt(8)
	v_mul_f32_e32 v50, v7, v160
	ds_read_b128 v[220:223], v65 offset:63616
	ds_read_b128 v[176:179], v65 offset:63632
	v_fma_f32 v2, v172, v49, -v50
	v_fma_f32 v2, -v8, v161, v2
	v_fma_f32 v2, -v9, v162, v2
	v_fma_f32 v2, -v10, v163, v2
	s_waitcnt lgkmcnt(8)
	v_fma_f32 v2, -v11, v184, v2
	ds_read_u16 v216, v80 offset:11152
	ds_read_b128 v[212:215], v65 offset:63744
	v_fma_f32 v2, -v12, v185, v2
	v_fma_f32 v2, -v13, v186, v2
	v_fma_f32 v2, -v14, v187, v2
	s_waitcnt lgkmcnt(9)
	v_fma_f32 v2, -v15, v164, v2
	ds_read_b128 v[180:183], v65 offset:63760
	v_fma_f32 v2, -v16, v165, v2
	v_fma_f32 v2, -v17, v166, v2
	v_fma_f32 v2, -v18, v167, v2
	s_waitcnt lgkmcnt(9)
	v_fma_f32 v2, -v19, v192, v2
	ds_read_b32 v208, v65 offset:63904
	v_fma_f32 v2, -v20, v193, v2
	v_fma_f32 v2, -v21, v194, v2
	v_fma_f32 v2, -v22, v195, v2
	s_waitcnt lgkmcnt(9)
	v_fma_f32 v2, -v23, v200, v2
	ds_read_b128 v[160:163], v65 offset:63776
	v_fma_f32 v2, -v24, v201, v2
	v_fma_f32 v2, -v25, v202, v2
	v_fma_f32 v2, -v26, v203, v2
	s_waitcnt lgkmcnt(9)
	v_fma_f32 v2, -v27, v196, v2
	ds_read_b128 v[184:187], v65 offset:63792
	v_fma_f32 v2, -v28, v197, v2
	v_fma_f32 v2, -v29, v198, v2
	v_fma_f32 v2, -v30, v199, v2
	s_waitcnt lgkmcnt(9)
	v_fma_f32 v2, -v31, v204, v2
	ds_read_b128 v[164:167], v65 offset:63808
	v_fma_f32 v2, -v32, v205, v2
	v_fma_f32 v2, -v33, v206, v2
	v_fma_f32 v2, -v34, v207, v2
	s_waitcnt lgkmcnt(9)
	v_fma_f32 v2, -v35, v168, v2
	ds_read_b128 v[192:195], v65 offset:63824
	v_fma_f32 v2, -v36, v169, v2
	v_fma_f32 v2, -v37, v170, v2
	v_fma_f32 v2, -v38, v171, v2
	s_waitcnt lgkmcnt(9)
	v_fma_f32 v2, -v39, v220, v2
	ds_read_b128 v[200:203], v65 offset:63840
	v_fma_f32 v2, -v40, v221, v2
	v_fma_f32 v2, -v41, v222, v2
	v_fma_f32 v2, -v44, v223, v2
	s_waitcnt lgkmcnt(9)
	v_fma_f32 v2, -v45, v176, v2
	ds_read_b128 v[196:199], v65 offset:63856
	v_fma_f32 v2, -v46, v177, v2
	v_fma_f32 v2, -v47, v178, v2
	v_fma_f32 v49, -v48, v179, v2
	v_bfe_u32 v134, v49, 16, 1
	s_waitcnt lgkmcnt(9)
	v_lshlrev_b32_e32 v2, 16, v216
	ds_read_b128 v[204:207], v65 offset:63872
	s_waitcnt lgkmcnt(9)
	v_mul_f32_e32 v50, v7, v212
	ds_read_b128 v[168:171], v65 offset:63888
	v_fma_f32 v2, v173, v2, -v50
	v_fma_f32 v2, -v8, v213, v2
	v_fma_f32 v2, -v9, v214, v2
	v_fma_f32 v2, -v10, v215, v2
	s_waitcnt lgkmcnt(9)
	v_fma_f32 v2, -v11, v180, v2
	ds_read_u16 v220, v80 offset:11424
	v_fma_f32 v2, -v12, v181, v2
	v_fma_f32 v2, -v13, v182, v2
	v_fma_f32 v2, -v14, v183, v2
	s_waitcnt lgkmcnt(8)
	v_fma_f32 v2, -v15, v160, v2
	ds_read_b128 v[176:179], v65 offset:64016
	ds_read_b128 v[216:219], v65 offset:64032
	v_fma_f32 v2, -v16, v161, v2
	v_fma_f32 v2, -v17, v162, v2
	v_fma_f32 v2, -v18, v163, v2
	s_waitcnt lgkmcnt(9)
	v_fma_f32 v2, -v19, v184, v2
	ds_read_b128 v[212:215], v65 offset:64048
	v_fma_f32 v2, -v20, v185, v2
	v_fma_f32 v2, -v21, v186, v2
	v_fma_f32 v2, -v22, v187, v2
	s_waitcnt lgkmcnt(9)
	v_fma_f32 v2, -v23, v164, v2
	ds_read_b128 v[180:183], v65 offset:64064
	v_fma_f32 v2, -v24, v165, v2
	v_fma_f32 v2, -v25, v166, v2
	v_fma_f32 v2, -v26, v167, v2
	s_waitcnt lgkmcnt(9)
	v_fma_f32 v2, -v27, v192, v2
	ds_read_b128 v[160:163], v65 offset:64080
	v_fma_f32 v2, -v28, v193, v2
	v_fma_f32 v2, -v29, v194, v2
	v_fma_f32 v2, -v30, v195, v2
	s_waitcnt lgkmcnt(9)
	v_fma_f32 v2, -v31, v200, v2
	ds_read_b128 v[184:187], v65 offset:64096
	v_fma_f32 v2, -v32, v201, v2
	v_fma_f32 v2, -v33, v202, v2
	v_fma_f32 v2, -v34, v203, v2
	s_waitcnt lgkmcnt(9)
	v_fma_f32 v2, -v35, v196, v2
	ds_read_b128 v[164:167], v65 offset:64112
	v_fma_f32 v2, -v36, v197, v2
	v_fma_f32 v2, -v37, v198, v2
	v_fma_f32 v2, -v38, v199, v2
	s_waitcnt lgkmcnt(9)
	v_fma_f32 v2, -v39, v204, v2
	ds_read_b128 v[192:195], v65 offset:64128
	v_fma_f32 v2, -v40, v205, v2
	v_fma_f32 v2, -v41, v206, v2
	v_fma_f32 v2, -v44, v207, v2
	s_waitcnt lgkmcnt(9)
	v_fma_f32 v2, -v45, v168, v2
	ds_read_b128 v[200:203], v65 offset:64144
	v_fma_f32 v2, -v46, v169, v2
	v_fma_f32 v2, -v47, v170, v2
	v_fma_f32 v2, -v48, v171, v2
	v_fma_f32 v50, -v49, v208, v2
	v_mul_f32_e32 v3, v7, v188
	v_bfe_u32 v135, v50, 16, 1
	s_waitcnt lgkmcnt(9)
	v_lshlrev_b32_e32 v2, 16, v220
	ds_read_b64 v[196:197], v65 offset:64160
	v_fma_f32 v2, v174, v2, -v3
	v_fma_f32 v2, -v8, v189, v2
	v_fma_f32 v2, -v9, v190, v2
	v_fma_f32 v2, -v10, v191, v2
	s_waitcnt lgkmcnt(9)
	v_fma_f32 v2, -v11, v176, v2
	ds_read_b128 v[204:207], v65 offset:64256
	v_fma_f32 v2, -v12, v177, v2
	v_fma_f32 v2, -v13, v178, v2
	v_fma_f32 v2, -v14, v179, v2
	s_waitcnt lgkmcnt(9)
	v_fma_f32 v2, -v15, v216, v2
	ds_read_u16 v168, v80 offset:11696
	v_fma_f32 v2, -v16, v217, v2
	v_fma_f32 v2, -v17, v218, v2
	v_fma_f32 v2, -v18, v219, v2
	s_waitcnt lgkmcnt(9)
	v_fma_f32 v2, -v19, v212, v2
	ds_read_b128 v[208:211], v65 offset:64272
	v_fma_f32 v2, -v20, v213, v2
	v_fma_f32 v2, -v21, v214, v2
	v_fma_f32 v2, -v22, v215, v2
	s_waitcnt lgkmcnt(9)
	v_fma_f32 v2, -v23, v180, v2
	ds_read_b128 v[220:223], v65 offset:64288
	v_fma_f32 v2, -v24, v181, v2
	v_fma_f32 v2, -v25, v182, v2
	v_fma_f32 v2, -v26, v183, v2
	s_waitcnt lgkmcnt(9)
	v_fma_f32 v2, -v27, v160, v2
	ds_read_b128 v[188:191], v65 offset:64304
	v_fma_f32 v2, -v28, v161, v2
	v_fma_f32 v2, -v29, v162, v2
	v_fma_f32 v2, -v30, v163, v2
	s_waitcnt lgkmcnt(9)
	v_fma_f32 v2, -v31, v184, v2
	ds_read_b128 v[176:179], v65 offset:64320
	v_fma_f32 v2, -v32, v185, v2
	v_fma_f32 v2, -v33, v186, v2
	v_fma_f32 v2, -v34, v187, v2
	s_waitcnt lgkmcnt(9)
	v_fma_f32 v2, -v35, v164, v2
	ds_read_b128 v[216:219], v65 offset:64336
	v_fma_f32 v2, -v36, v165, v2
	v_fma_f32 v2, -v37, v166, v2
	v_fma_f32 v2, -v38, v167, v2
	s_waitcnt lgkmcnt(9)
	v_fma_f32 v2, -v39, v192, v2
	ds_read_b128 v[212:215], v65 offset:64352
	v_fma_f32 v2, -v40, v193, v2
	v_fma_f32 v2, -v41, v194, v2
	v_fma_f32 v2, -v44, v195, v2
	s_waitcnt lgkmcnt(9)
	v_fma_f32 v2, -v45, v200, v2
	ds_read_b128 v[180:183], v65 offset:64368
	v_fma_f32 v2, -v46, v201, v2
	v_fma_f32 v2, -v47, v202, v2
	v_fma_f32 v4, -v48, v203, v2
	s_waitcnt lgkmcnt(9)
	v_fma_f32 v2, -v49, v196, v4
	ds_read_b128 v[160:163], v65 offset:64384
	v_fma_f32 v51, -v50, v197, v2
	s_waitcnt lgkmcnt(9)
	v_mul_f32_e32 v3, v7, v204
	ds_read_b128 v[184:187], v65 offset:64400
	v_bfe_u32 v136, v51, 16, 1
	s_waitcnt lgkmcnt(9)
	v_lshlrev_b32_e32 v2, 16, v168
	ds_read_b96 v[164:166], v65 offset:64416
	v_fma_f32 v2, v175, v2, -v3
	v_fma_f32 v2, -v8, v205, v2
	v_fma_f32 v2, -v9, v206, v2
	v_fma_f32 v52, -v10, v207, v2
	s_waitcnt lgkmcnt(9)
	v_fma_f32 v2, -v11, v208, v52
	ds_read_u16 v192, v80 offset:11968
	v_fma_f32 v2, -v12, v209, v2
	v_fma_f32 v2, -v13, v210, v2
	v_fma_f32 v52, -v14, v211, v2
	s_waitcnt lgkmcnt(9)
	v_fma_f32 v2, -v15, v220, v52
	v_fma_f32 v2, -v16, v221, v2
	v_fma_f32 v2, -v17, v222, v2
	v_fma_f32 v52, -v18, v223, v2
	s_waitcnt lgkmcnt(8)
	v_fma_f32 v2, -v19, v188, v52
	v_fma_f32 v2, -v20, v189, v2
	v_fma_f32 v2, -v21, v190, v2
	v_fma_f32 v52, -v22, v191, v2
	s_waitcnt lgkmcnt(7)
	v_fma_f32 v2, -v23, v176, v52
	v_fma_f32 v2, -v24, v177, v2
	v_fma_f32 v2, -v25, v178, v2
	v_fma_f32 v52, -v26, v179, v2
	s_waitcnt lgkmcnt(6)
	v_fma_f32 v2, -v27, v216, v52
	v_fma_f32 v2, -v28, v217, v2
	v_fma_f32 v2, -v29, v218, v2
	v_fma_f32 v52, -v30, v219, v2
	s_waitcnt lgkmcnt(5)
	v_fma_f32 v2, -v31, v212, v52
	v_fma_f32 v2, -v32, v213, v2
	v_fma_f32 v2, -v33, v214, v2
	v_fma_f32 v52, -v34, v215, v2
	s_waitcnt lgkmcnt(4)
	v_fma_f32 v2, -v35, v180, v52
	v_fma_f32 v2, -v36, v181, v2
	v_fma_f32 v2, -v37, v182, v2
	v_fma_f32 v52, -v38, v183, v2
	s_waitcnt lgkmcnt(3)
	v_fma_f32 v2, -v39, v160, v52
	v_fma_f32 v2, -v40, v161, v2
	v_fma_f32 v2, -v41, v162, v2
	v_fma_f32 v52, -v44, v163, v2
	s_waitcnt lgkmcnt(2)
	v_fma_f32 v2, -v45, v184, v52
	v_fma_f32 v2, -v46, v185, v2
	v_fma_f32 v2, -v47, v186, v2
	v_fma_f32 v5, -v48, v187, v2
	s_waitcnt lgkmcnt(1)
	v_fma_f32 v2, -v49, v164, v5
	v_fma_f32 v2, -v50, v165, v2
	v_fma_f32 v52, -v51, v166, v2
	v_bfe_u32 v137, v52, 16, 1
	s_waitcnt lgkmcnt(0)
	v_lshlrev_b32_e32 v53, 16, v192
	v_mov_b32_e32 v2, s0
	v_readlane_b32 s0, v247, 31
	s_nop 1
	v_mov_b32_e32 v3, s0
	v_cndmask_b32_e32 v2, v2, v3, vcc
	ds_read_b128 v[200:203], v2
	ds_read_b128 v[196:199], v65 offset:64512
	ds_read_b128 v[168:171], v65 offset:64528
	ds_read_b128 v[172:175], v65 offset:64544
	ds_read_b128 v[204:207], v65 offset:64560
	ds_read_b128 v[208:211], v65 offset:64576
	ds_read_b128 v[220:223], v65 offset:64592
	ds_read_b128 v[188:191], v65 offset:64608
	ds_read_b128 v[176:179], v65 offset:64624
	ds_read_b128 v[216:219], v65 offset:64640
	v_readlane_b32 s0, v247, 34
	s_waitcnt lgkmcnt(8)
	v_mul_f32_e32 v55, v7, v196
	ds_read_b128 v[212:215], v65 offset:64656
	ds_read_b128 v[180:183], v65 offset:64672
	v_fma_f32 v2, v200, v53, -v55
	v_fma_f32 v2, -v8, v197, v2
	v_fma_f32 v2, -v9, v198, v2
	v_fma_f32 v2, -v10, v199, v2
	s_waitcnt lgkmcnt(9)
	v_fma_f32 v2, -v11, v168, v2
	ds_read_u16 v160, v80 offset:12240
	v_fma_f32 v2, -v12, v169, v2
	v_fma_f32 v2, -v13, v170, v2
	v_fma_f32 v2, -v14, v171, v2
	s_waitcnt lgkmcnt(9)
	v_fma_f32 v2, -v15, v172, v2
	ds_read_b128 v[184:187], v65 offset:64768
	v_fma_f32 v2, -v16, v173, v2
	v_fma_f32 v2, -v17, v174, v2
	v_fma_f32 v2, -v18, v175, v2
	s_waitcnt lgkmcnt(9)
	v_fma_f32 v2, -v19, v204, v2
	ds_read_b128 v[164:167], v65 offset:64784
	v_fma_f32 v2, -v20, v205, v2
	v_fma_f32 v2, -v21, v206, v2
	v_fma_f32 v2, -v22, v207, v2
	s_waitcnt lgkmcnt(9)
	v_fma_f32 v2, -v23, v208, v2
	ds_read_b32 v192, v65 offset:64944
	v_fma_f32 v2, -v24, v209, v2
	v_fma_f32 v2, -v25, v210, v2
	v_fma_f32 v2, -v26, v211, v2
	s_waitcnt lgkmcnt(9)
	v_fma_f32 v2, -v27, v220, v2
	ds_read_b128 v[196:199], v65 offset:64800
	v_fma_f32 v2, -v28, v221, v2
	v_fma_f32 v2, -v29, v222, v2
	v_fma_f32 v2, -v30, v223, v2
	s_waitcnt lgkmcnt(9)
	v_fma_f32 v2, -v31, v188, v2
	ds_read_b128 v[168:171], v65 offset:64816
	v_fma_f32 v2, -v32, v189, v2
	v_fma_f32 v2, -v33, v190, v2
	v_fma_f32 v2, -v34, v191, v2
	s_waitcnt lgkmcnt(9)
	v_fma_f32 v2, -v35, v176, v2
	ds_read_b128 v[172:175], v65 offset:64832
	v_fma_f32 v2, -v36, v177, v2
	v_fma_f32 v2, -v37, v178, v2
	v_fma_f32 v2, -v38, v179, v2
	s_waitcnt lgkmcnt(9)
	v_fma_f32 v2, -v39, v216, v2
	ds_read_b128 v[204:207], v65 offset:64848
	v_fma_f32 v2, -v40, v217, v2
	v_fma_f32 v2, -v41, v218, v2
	v_fma_f32 v2, -v44, v219, v2
	s_waitcnt lgkmcnt(9)
	v_fma_f32 v2, -v45, v212, v2
	ds_read_b128 v[208:211], v65 offset:64864
	v_fma_f32 v2, -v46, v213, v2
	v_fma_f32 v2, -v47, v214, v2
	v_fma_f32 v2, -v48, v215, v2
	s_waitcnt lgkmcnt(9)
	v_fma_f32 v2, -v49, v180, v2
	ds_read_b128 v[220:223], v65 offset:64880
	v_fma_f32 v2, -v50, v181, v2
	v_fma_f32 v2, -v51, v182, v2
	v_fma_f32 v53, -v52, v183, v2
	v_bfe_u32 v138, v53, 16, 1
	s_waitcnt lgkmcnt(9)
	v_lshlrev_b32_e32 v2, 16, v160
	ds_read_b128 v[188:191], v65 offset:64896
	s_waitcnt lgkmcnt(9)
	v_mul_f32_e32 v55, v7, v184
	ds_read_b128 v[176:179], v65 offset:64912
	v_fma_f32 v2, v201, v2, -v55
	v_fma_f32 v2, -v8, v185, v2
	v_fma_f32 v2, -v9, v186, v2
	v_fma_f32 v2, -v10, v187, v2
	s_waitcnt lgkmcnt(9)
	v_fma_f32 v2, -v11, v164, v2
	ds_read_b128 v[216:219], v65 offset:64928
	v_fma_f32 v2, -v12, v165, v2
	v_fma_f32 v2, -v13, v166, v2
	v_fma_f32 v2, -v14, v167, v2
	s_waitcnt lgkmcnt(8)
	v_fma_f32 v2, -v15, v196, v2
	ds_read_u16 v212, v80 offset:12512
	ds_read_b128 v[180:183], v65 offset:65024
	v_fma_f32 v2, -v16, v197, v2
	v_fma_f32 v2, -v17, v198, v2
	v_fma_f32 v2, -v18, v199, v2
	s_waitcnt lgkmcnt(9)
	v_fma_f32 v2, -v19, v168, v2
	ds_read_b128 v[160:163], v65 offset:65040
	v_fma_f32 v2, -v20, v169, v2
	v_fma_f32 v2, -v21, v170, v2
	v_fma_f32 v2, -v22, v171, v2
	s_waitcnt lgkmcnt(9)
	v_fma_f32 v2, -v23, v172, v2
	ds_read_b128 v[184:187], v65 offset:65056
	v_fma_f32 v2, -v24, v173, v2
	v_fma_f32 v2, -v25, v174, v2
	v_fma_f32 v2, -v26, v175, v2
	s_waitcnt lgkmcnt(9)
	v_fma_f32 v2, -v27, v204, v2
	ds_read_b128 v[164:167], v65 offset:65072
	v_fma_f32 v2, -v28, v205, v2
	v_fma_f32 v2, -v29, v206, v2
	v_fma_f32 v2, -v30, v207, v2
	s_waitcnt lgkmcnt(9)
	v_fma_f32 v2, -v31, v208, v2
	ds_read_b128 v[196:199], v65 offset:65088
	v_fma_f32 v2, -v32, v209, v2
	v_fma_f32 v2, -v33, v210, v2
	v_fma_f32 v2, -v34, v211, v2
	s_waitcnt lgkmcnt(9)
	v_fma_f32 v2, -v35, v220, v2
	ds_read_b128 v[168:171], v65 offset:65104
	v_fma_f32 v2, -v36, v221, v2
	v_fma_f32 v2, -v37, v222, v2
	v_fma_f32 v2, -v38, v223, v2
	s_waitcnt lgkmcnt(9)
	v_fma_f32 v2, -v39, v188, v2
	ds_read_b128 v[172:175], v65 offset:65120
	v_fma_f32 v2, -v40, v189, v2
	v_fma_f32 v2, -v41, v190, v2
	v_fma_f32 v2, -v44, v191, v2
	s_waitcnt lgkmcnt(9)
	v_fma_f32 v2, -v45, v176, v2
	ds_read_b128 v[204:207], v65 offset:65136
	v_fma_f32 v2, -v46, v177, v2
	v_fma_f32 v2, -v47, v178, v2
	v_fma_f32 v2, -v48, v179, v2
	s_waitcnt lgkmcnt(9)
	v_fma_f32 v2, -v49, v216, v2
	ds_read_b128 v[208:211], v65 offset:65152
	v_fma_f32 v2, -v50, v217, v2
	v_fma_f32 v2, -v51, v218, v2
	v_fma_f32 v2, -v52, v219, v2
	v_fma_f32 v55, -v53, v192, v2
	v_bfe_u32 v139, v55, 16, 1
	s_waitcnt lgkmcnt(9)
	v_lshlrev_b32_e32 v2, 16, v212
	ds_read_b128 v[220:223], v65 offset:65168
	s_waitcnt lgkmcnt(9)
	v_mul_f32_e32 v3, v7, v180
	ds_read_b128 v[188:191], v65 offset:65184
	v_fma_f32 v2, v202, v2, -v3
	v_fma_f32 v2, -v8, v181, v2
	v_fma_f32 v2, -v9, v182, v2
	v_fma_f32 v2, -v10, v183, v2
	s_waitcnt lgkmcnt(9)
	v_fma_f32 v2, -v11, v160, v2
	ds_read_b64 v[176:177], v65 offset:65200
	v_fma_f32 v2, -v12, v161, v2
	v_fma_f32 v2, -v13, v162, v2
	v_fma_f32 v2, -v14, v163, v2
	s_waitcnt lgkmcnt(9)
	v_fma_f32 v2, -v15, v184, v2
	ds_read_b128 v[216:219], v65 offset:65280
	v_fma_f32 v2, -v16, v185, v2
	v_fma_f32 v2, -v17, v186, v2
	v_fma_f32 v2, -v18, v187, v2
	s_waitcnt lgkmcnt(9)
	v_fma_f32 v2, -v19, v164, v2
	ds_read_u16 v192, v80 offset:12784
	v_fma_f32 v2, -v20, v165, v2
	v_fma_f32 v2, -v21, v166, v2
	v_fma_f32 v2, -v22, v167, v2
	s_waitcnt lgkmcnt(9)
	v_fma_f32 v2, -v23, v196, v2
	ds_read_b128 v[212:215], v65 offset:65296
	v_fma_f32 v2, -v24, v197, v2
	v_fma_f32 v2, -v25, v198, v2
	v_fma_f32 v2, -v26, v199, v2
	s_waitcnt lgkmcnt(9)
	v_fma_f32 v2, -v27, v168, v2
	ds_read_b128 v[180:183], v65 offset:65312
	v_fma_f32 v2, -v28, v169, v2
	v_fma_f32 v2, -v29, v170, v2
	v_fma_f32 v2, -v30, v171, v2
	s_waitcnt lgkmcnt(9)
	v_fma_f32 v2, -v31, v172, v2
	ds_read_b128 v[160:163], v65 offset:65328
	v_fma_f32 v2, -v32, v173, v2
	v_fma_f32 v2, -v33, v174, v2
	v_fma_f32 v2, -v34, v175, v2
	s_waitcnt lgkmcnt(9)
	v_fma_f32 v2, -v35, v204, v2
	ds_read_b128 v[184:187], v65 offset:65344
	v_fma_f32 v2, -v36, v205, v2
	v_fma_f32 v2, -v37, v206, v2
	v_fma_f32 v2, -v38, v207, v2
	s_waitcnt lgkmcnt(9)
	v_fma_f32 v2, -v39, v208, v2
	ds_read_b128 v[164:167], v65 offset:65360
	v_fma_f32 v2, -v40, v209, v2
	v_fma_f32 v2, -v41, v210, v2
	v_fma_f32 v2, -v44, v211, v2
	s_waitcnt lgkmcnt(9)
	v_fma_f32 v2, -v45, v220, v2
	ds_read_b128 v[196:199], v65 offset:65376
	v_fma_f32 v2, -v46, v221, v2
	v_fma_f32 v2, -v47, v222, v2
	v_fma_f32 v2, -v48, v223, v2
	s_waitcnt lgkmcnt(9)
	v_fma_f32 v2, -v49, v188, v2
	ds_read_b128 v[168:171], v65 offset:65392
	v_fma_f32 v2, -v50, v189, v2
	v_fma_f32 v2, -v51, v190, v2
	v_fma_f32 v4, -v52, v191, v2
	s_waitcnt lgkmcnt(9)
	v_fma_f32 v2, -v53, v176, v4
	ds_read_b128 v[172:175], v65 offset:65408
	v_fma_f32 v56, -v55, v177, v2
	s_waitcnt lgkmcnt(9)
	v_mul_f32_e32 v3, v7, v216
	ds_read_b128 v[204:207], v65 offset:65424
	v_bfe_u32 v140, v56, 16, 1
	s_waitcnt lgkmcnt(9)
	v_lshlrev_b32_e32 v2, 16, v192
	ds_read_b128 v[208:211], v65 offset:65440
	v_fma_f32 v2, v203, v2, -v3
	v_fma_f32 v2, -v8, v217, v2
	v_fma_f32 v2, -v9, v218, v2
	v_fma_f32 v57, -v10, v219, v2
	s_waitcnt lgkmcnt(9)
	v_fma_f32 v2, -v11, v212, v57
	ds_read_b96 v[220:222], v65 offset:65456
	v_fma_f32 v2, -v12, v213, v2
	v_fma_f32 v2, -v13, v214, v2
	v_fma_f32 v57, -v14, v215, v2
	s_waitcnt lgkmcnt(9)
	v_fma_f32 v2, -v15, v180, v57
	ds_read_u16 v188, v80 offset:13056
	v_fma_f32 v2, -v16, v181, v2
	v_fma_f32 v2, -v17, v182, v2
	v_fma_f32 v57, -v18, v183, v2
	s_waitcnt lgkmcnt(9)
	v_fma_f32 v2, -v19, v160, v57
	v_fma_f32 v2, -v20, v161, v2
	v_fma_f32 v2, -v21, v162, v2
	v_fma_f32 v57, -v22, v163, v2
	s_waitcnt lgkmcnt(8)
	v_fma_f32 v2, -v23, v184, v57
	v_fma_f32 v2, -v24, v185, v2
	v_fma_f32 v2, -v25, v186, v2
	v_fma_f32 v57, -v26, v187, v2
	s_waitcnt lgkmcnt(7)
	v_fma_f32 v2, -v27, v164, v57
	v_fma_f32 v2, -v28, v165, v2
	v_fma_f32 v2, -v29, v166, v2
	v_fma_f32 v57, -v30, v167, v2
	s_waitcnt lgkmcnt(6)
	v_fma_f32 v2, -v31, v196, v57
	v_fma_f32 v2, -v32, v197, v2
	v_fma_f32 v2, -v33, v198, v2
	v_fma_f32 v57, -v34, v199, v2
	s_waitcnt lgkmcnt(5)
	v_fma_f32 v2, -v35, v168, v57
	v_fma_f32 v2, -v36, v169, v2
	v_fma_f32 v2, -v37, v170, v2
	v_fma_f32 v57, -v38, v171, v2
	s_waitcnt lgkmcnt(4)
	v_fma_f32 v2, -v39, v172, v57
	v_fma_f32 v2, -v40, v173, v2
	v_fma_f32 v2, -v41, v174, v2
	v_fma_f32 v57, -v44, v175, v2
	s_waitcnt lgkmcnt(3)
	v_fma_f32 v2, -v45, v204, v57
	v_fma_f32 v2, -v46, v205, v2
	v_fma_f32 v2, -v47, v206, v2
	v_fma_f32 v57, -v48, v207, v2
	s_waitcnt lgkmcnt(2)
	v_fma_f32 v2, -v49, v208, v57
	v_fma_f32 v2, -v50, v209, v2
	v_fma_f32 v2, -v51, v210, v2
	v_fma_f32 v5, -v52, v211, v2
	s_waitcnt lgkmcnt(1)
	v_fma_f32 v2, -v53, v220, v5
	v_fma_f32 v2, -v55, v221, v2
	v_fma_f32 v57, -v56, v222, v2
	v_bfe_u32 v141, v57, 16, 1
	s_waitcnt lgkmcnt(0)
	v_lshlrev_b32_e32 v64, 16, v188
	v_mov_b32_e32 v2, s0
	v_readlane_b32 s0, v247, 33
	s_nop 1
	v_mov_b32_e32 v3, s0
	v_readlane_b32 s0, v247, 35
	v_cndmask_b32_e32 v2, v2, v3, vcc
	ds_read_b128 v[176:179], v2
	v_mov_b32_e32 v58, s0
	ds_read_b128 v[192:195], v58
	v_readlane_b32 s0, v247, 36
	s_waitcnt lgkmcnt(0)
	v_mul_f32_e32 v58, v7, v192
	v_fma_f32 v2, v176, v64, -v58
	v_fma_f32 v2, -v8, v193, v2
	v_fma_f32 v2, -v9, v194, v2
	v_mov_b32_e32 v58, s0
	ds_read_b128 v[200:203], v58
	v_fma_f32 v2, -v10, v195, v2
	v_readlane_b32 s0, v247, 37
	s_waitcnt lgkmcnt(0)
	v_fma_f32 v2, -v11, v200, v2
	v_fma_f32 v2, -v12, v201, v2
	v_fma_f32 v2, -v13, v202, v2
	v_mov_b32_e32 v58, s0
	ds_read_b128 v[216:219], v58
	v_fma_f32 v2, -v14, v203, v2
	v_readlane_b32 s0, v247, 38
	s_waitcnt lgkmcnt(0)
	v_fma_f32 v2, -v15, v216, v2
	v_fma_f32 v2, -v16, v217, v2
	v_fma_f32 v2, -v17, v218, v2
	v_mov_b32_e32 v58, s0
	ds_read_b128 v[212:215], v58
	v_fma_f32 v2, -v18, v219, v2
	v_readlane_b32 s0, v247, 39
	s_waitcnt lgkmcnt(0)
	v_fma_f32 v2, -v19, v212, v2
	v_fma_f32 v2, -v20, v213, v2
	v_fma_f32 v2, -v21, v214, v2
	v_mov_b32_e32 v58, s0
	ds_read_b128 v[180:183], v58
	v_fma_f32 v2, -v22, v215, v2
	v_readlane_b32 s0, v247, 40
	s_waitcnt lgkmcnt(0)
	v_fma_f32 v2, -v23, v180, v2
	v_fma_f32 v2, -v24, v181, v2
	v_fma_f32 v2, -v25, v182, v2
	v_mov_b32_e32 v58, s0
	ds_read_b128 v[160:163], v58
	v_fma_f32 v2, -v26, v183, v2
	v_readlane_b32 s0, v247, 41
	s_waitcnt lgkmcnt(0)
	v_fma_f32 v2, -v27, v160, v2
	v_fma_f32 v2, -v28, v161, v2
	v_fma_f32 v2, -v29, v162, v2
	v_mov_b32_e32 v58, s0
	ds_read_b128 v[184:187], v58
	v_fma_f32 v2, -v30, v163, v2
	v_readlane_b32 s0, v247, 42
	s_waitcnt lgkmcnt(0)
	v_fma_f32 v2, -v31, v184, v2
	v_fma_f32 v2, -v32, v185, v2
	v_fma_f32 v2, -v33, v186, v2
	v_mov_b32_e32 v58, s0
	ds_read_b128 v[164:167], v58
	v_fma_f32 v2, -v34, v187, v2
	v_readlane_b32 s0, v247, 43
	s_waitcnt lgkmcnt(0)
	v_fma_f32 v2, -v35, v164, v2
	v_fma_f32 v2, -v36, v165, v2
	v_fma_f32 v2, -v37, v166, v2
	v_mov_b32_e32 v58, s0
	ds_read_b128 v[196:199], v58
	v_fma_f32 v2, -v38, v167, v2
	v_readlane_b32 s0, v247, 44
	s_waitcnt lgkmcnt(0)
	v_fma_f32 v2, -v39, v196, v2
	v_fma_f32 v2, -v40, v197, v2
	v_fma_f32 v2, -v41, v198, v2
	v_mov_b32_e32 v58, s0
	ds_read_b128 v[168:171], v58
	v_fma_f32 v2, -v44, v199, v2
	v_readlane_b32 s0, v247, 45
	s_waitcnt lgkmcnt(0)
	v_fma_f32 v2, -v45, v168, v2
	v_fma_f32 v2, -v46, v169, v2
	v_fma_f32 v2, -v47, v170, v2
	v_mov_b32_e32 v58, s0
	ds_read_b128 v[172:175], v58
	v_fma_f32 v2, -v48, v171, v2
	v_readlane_b32 s0, v247, 46
	s_waitcnt lgkmcnt(0)
	v_fma_f32 v2, -v49, v172, v2
	v_fma_f32 v2, -v50, v173, v2
	v_fma_f32 v2, -v51, v174, v2
	v_mov_b32_e32 v58, s0
	ds_read_b128 v[204:207], v58
	ds_read_u16 v208, v80 offset:13328
	v_fma_f32 v2, -v52, v175, v2
	v_readlane_b32 s0, v247, 47
	s_waitcnt lgkmcnt(1)
	v_fma_f32 v2, -v53, v204, v2
	v_fma_f32 v2, -v55, v205, v2
	v_fma_f32 v2, -v56, v206, v2
	v_mov_b32_e32 v59, s0
	ds_read_b128 v[220:223], v59
	v_fma_f32 v58, -v57, v207, v2
	v_readlane_b32 s0, v247, 48
	v_bfe_u32 v142, v58, 16, 1
	s_waitcnt lgkmcnt(1)
	v_lshlrev_b32_e32 v2, 16, v208
	s_waitcnt lgkmcnt(0)
	v_mul_f32_e32 v59, v7, v220
	v_fma_f32 v2, v177, v2, -v59
	v_fma_f32 v2, -v8, v221, v2
	v_fma_f32 v2, -v9, v222, v2
	v_mov_b32_e32 v3, s0
	ds_read_b128 v[188:191], v3
	v_fma_f32 v2, -v10, v223, v2
	v_readlane_b32 s0, v247, 49
	s_waitcnt lgkmcnt(0)
	v_fma_f32 v2, -v11, v188, v2
	v_fma_f32 v2, -v12, v189, v2
	v_fma_f32 v2, -v13, v190, v2
	v_mov_b32_e32 v3, s0
	ds_read_b128 v[192:195], v3
	v_fma_f32 v2, -v14, v191, v2
	v_readlane_b32 s0, v247, 50
	s_waitcnt lgkmcnt(0)
	v_fma_f32 v2, -v15, v192, v2
	v_fma_f32 v2, -v16, v193, v2
	v_fma_f32 v2, -v17, v194, v2
	v_mov_b32_e32 v3, s0
	ds_read_b128 v[200:203], v3
	v_fma_f32 v2, -v18, v195, v2
	v_readlane_b32 s0, v247, 51
	s_waitcnt lgkmcnt(0)
	v_fma_f32 v2, -v19, v200, v2
	v_fma_f32 v2, -v20, v201, v2
	v_fma_f32 v2, -v21, v202, v2
	v_mov_b32_e32 v3, s0
	ds_read_b128 v[216:219], v3
	v_fma_f32 v2, -v22, v203, v2
	v_readlane_b32 s0, v247, 52
	s_waitcnt lgkmcnt(0)
	v_fma_f32 v2, -v23, v216, v2
	v_fma_f32 v2, -v24, v217, v2
	v_fma_f32 v2, -v25, v218, v2
	v_mov_b32_e32 v3, s0
	ds_read_b128 v[212:215], v3
	v_fma_f32 v2, -v26, v219, v2
	v_readlane_b32 s0, v247, 53
	s_waitcnt lgkmcnt(0)
	v_fma_f32 v2, -v27, v212, v2
	v_fma_f32 v2, -v28, v213, v2
	v_fma_f32 v2, -v29, v214, v2
	v_mov_b32_e32 v3, s0
	ds_read_b128 v[180:183], v3
	v_fma_f32 v2, -v30, v215, v2
	v_readlane_b32 s0, v247, 54
	s_waitcnt lgkmcnt(0)
	v_fma_f32 v2, -v31, v180, v2
	v_fma_f32 v2, -v32, v181, v2
	v_fma_f32 v2, -v33, v182, v2
	v_mov_b32_e32 v3, s0
	ds_read_b128 v[160:163], v3
	v_fma_f32 v2, -v34, v183, v2
	v_readlane_b32 s0, v247, 55
	s_waitcnt lgkmcnt(0)
	v_fma_f32 v2, -v35, v160, v2
	v_fma_f32 v2, -v36, v161, v2
	v_fma_f32 v2, -v37, v162, v2
	v_mov_b32_e32 v3, s0
	ds_read_b128 v[184:187], v3
	v_fma_f32 v2, -v38, v163, v2
	v_readlane_b32 s0, v247, 56
	s_waitcnt lgkmcnt(0)
	v_fma_f32 v2, -v39, v184, v2
	v_fma_f32 v2, -v40, v185, v2
	v_fma_f32 v2, -v41, v186, v2
	v_mov_b32_e32 v3, s0
	ds_read_b128 v[164:167], v3
	v_fma_f32 v2, -v44, v187, v2
	v_readlane_b32 s0, v247, 57
	s_waitcnt lgkmcnt(0)
	v_fma_f32 v2, -v45, v164, v2
	v_fma_f32 v2, -v46, v165, v2
	v_fma_f32 v2, -v47, v166, v2
	v_mov_b32_e32 v3, s0
	ds_read_b128 v[196:199], v3
	v_fma_f32 v2, -v48, v167, v2
	v_readlane_b32 s0, v247, 58
	s_waitcnt lgkmcnt(0)
	v_fma_f32 v2, -v49, v196, v2
	v_fma_f32 v2, -v50, v197, v2
	v_fma_f32 v2, -v51, v198, v2
	v_mov_b32_e32 v3, s0
	ds_read_b128 v[168:171], v3
	v_fma_f32 v2, -v52, v199, v2
	v_readlane_b32 s0, v247, 59
	s_waitcnt lgkmcnt(0)
	v_fma_f32 v2, -v53, v168, v2
	v_mov_b32_e32 v3, s0
	ds_read_b32 v172, v3
	ds_read_u16 v204, v80 offset:13600
	v_fma_f32 v2, -v55, v169, v2
	v_fma_f32 v2, -v56, v170, v2
	v_fma_f32 v2, -v57, v171, v2
	v_readlane_b32 s0, v247, 60
	s_waitcnt lgkmcnt(1)
	v_fma_f32 v59, -v58, v172, v2
	v_mov_b32_e32 v3, s0
	ds_read_b128 v[208:211], v3
	v_readlane_b32 s0, v247, 61
	v_bfe_u32 v143, v59, 16, 1
	s_waitcnt lgkmcnt(1)
	v_lshlrev_b32_e32 v2, 16, v204
	s_waitcnt lgkmcnt(0)
	v_mul_f32_e32 v3, v7, v208
	v_fma_f32 v2, v178, v2, -v3
	v_fma_f32 v2, -v8, v209, v2
	v_fma_f32 v2, -v9, v210, v2
	v_mov_b32_e32 v3, s0
	ds_read_b128 v[220:223], v3
	v_fma_f32 v2, -v10, v211, v2
	v_readlane_b32 s0, v247, 62
	s_waitcnt lgkmcnt(0)
	v_fma_f32 v2, -v11, v220, v2
	v_fma_f32 v2, -v12, v221, v2
	v_fma_f32 v2, -v13, v222, v2
	v_mov_b32_e32 v3, s0
	ds_read_b128 v[188:191], v3
	v_fma_f32 v2, -v14, v223, v2
	v_readlane_b32 s0, v247, 63
	s_waitcnt lgkmcnt(0)
	v_fma_f32 v2, -v15, v188, v2
	v_fma_f32 v2, -v16, v189, v2
	v_fma_f32 v2, -v17, v190, v2
	v_mov_b32_e32 v3, s0
	ds_read_b128 v[192:195], v3
	v_fma_f32 v2, -v18, v191, v2
	v_readlane_b32 s0, v245, 0
	s_waitcnt lgkmcnt(0)
	v_fma_f32 v2, -v19, v192, v2
	v_fma_f32 v2, -v20, v193, v2
	v_fma_f32 v2, -v21, v194, v2
	v_mov_b32_e32 v3, s0
	ds_read_b128 v[200:203], v3
	v_fma_f32 v2, -v22, v195, v2
	v_readlane_b32 s0, v245, 1
	s_waitcnt lgkmcnt(0)
	v_fma_f32 v2, -v23, v200, v2
	v_fma_f32 v2, -v24, v201, v2
	v_fma_f32 v2, -v25, v202, v2
	v_mov_b32_e32 v3, s0
	ds_read_b128 v[216:219], v3
	v_fma_f32 v2, -v26, v203, v2
	v_readlane_b32 s0, v245, 2
	s_waitcnt lgkmcnt(0)
	v_fma_f32 v2, -v27, v216, v2
	v_fma_f32 v2, -v28, v217, v2
	v_fma_f32 v2, -v29, v218, v2
	v_mov_b32_e32 v3, s0
	ds_read_b128 v[212:215], v3
	v_fma_f32 v2, -v30, v219, v2
	v_readlane_b32 s0, v245, 3
	s_waitcnt lgkmcnt(0)
	v_fma_f32 v2, -v31, v212, v2
	v_fma_f32 v2, -v32, v213, v2
	v_fma_f32 v2, -v33, v214, v2
	v_mov_b32_e32 v3, s0
	ds_read_b128 v[180:183], v3
	v_fma_f32 v2, -v34, v215, v2
	v_readlane_b32 s0, v245, 4
	s_waitcnt lgkmcnt(0)
	v_fma_f32 v2, -v35, v180, v2
	v_fma_f32 v2, -v36, v181, v2
	v_fma_f32 v2, -v37, v182, v2
	v_mov_b32_e32 v3, s0
	ds_read_b128 v[160:163], v3
	v_fma_f32 v2, -v38, v183, v2
	v_readlane_b32 s0, v245, 5
	s_waitcnt lgkmcnt(0)
	v_fma_f32 v2, -v39, v160, v2
	v_fma_f32 v2, -v40, v161, v2
	v_fma_f32 v2, -v41, v162, v2
	v_mov_b32_e32 v3, s0
	ds_read_b128 v[184:187], v3
	v_fma_f32 v2, -v44, v163, v2
	v_readlane_b32 s0, v245, 6
	s_waitcnt lgkmcnt(0)
	v_fma_f32 v2, -v45, v184, v2
	v_fma_f32 v2, -v46, v185, v2
	v_fma_f32 v2, -v47, v186, v2
	v_mov_b32_e32 v3, s0
	ds_read_b128 v[164:167], v3
	v_fma_f32 v2, -v48, v187, v2
	v_readlane_b32 s0, v245, 7
	s_waitcnt lgkmcnt(0)
	v_fma_f32 v2, -v49, v164, v2
	v_fma_f32 v2, -v50, v165, v2
	v_fma_f32 v2, -v51, v166, v2
	v_mov_b32_e32 v3, s0
	ds_read_b128 v[196:199], v3
	v_fma_f32 v2, -v52, v167, v2
	v_readlane_b32 s0, v245, 8
	s_waitcnt lgkmcnt(0)
	v_fma_f32 v2, -v53, v196, v2
	v_fma_f32 v2, -v55, v197, v2
	v_fma_f32 v2, -v56, v198, v2
	v_fma_f32 v4, -v57, v199, v2
	v_mov_b32_e32 v2, s0
	ds_read_b64 v[168:169], v2
	ds_read_u16 v172, v80 offset:13872
	v_readlane_b32 s0, v245, 9
	s_waitcnt lgkmcnt(1)
	v_fma_f32 v2, -v58, v168, v4
	v_fma_f32 v60, -v59, v169, v2
	v_mov_b32_e32 v3, s0
	ds_read_b128 v[204:207], v3
	v_readlane_b32 s0, v245, 10
	v_bfe_u32 v144, v60, 16, 1
	s_waitcnt lgkmcnt(1)
	v_lshlrev_b32_e32 v2, 16, v172
	s_waitcnt lgkmcnt(0)
	v_mul_f32_e32 v3, v7, v204
	v_fma_f32 v2, v179, v2, -v3
	v_fma_f32 v2, -v8, v205, v2
	v_fma_f32 v2, -v9, v206, v2
	v_fma_f32 v61, -v10, v207, v2
	v_mov_b32_e32 v2, s0
	ds_read_b128 v[208:211], v2
	v_readlane_b32 s0, v245, 11
	s_waitcnt lgkmcnt(0)
	v_fma_f32 v2, -v11, v208, v61
	v_fma_f32 v2, -v12, v209, v2
	v_fma_f32 v2, -v13, v210, v2
	v_fma_f32 v61, -v14, v211, v2
	v_mov_b32_e32 v2, s0
	ds_read_b128 v[220:223], v2
	v_readlane_b32 s0, v245, 12
	s_waitcnt lgkmcnt(0)
	v_fma_f32 v2, -v15, v220, v61
	v_fma_f32 v2, -v16, v221, v2
	v_fma_f32 v2, -v17, v222, v2
	v_fma_f32 v61, -v18, v223, v2
	v_mov_b32_e32 v2, s0
	ds_read_b128 v[188:191], v2
	v_readlane_b32 s0, v245, 13
	s_waitcnt lgkmcnt(0)
	v_fma_f32 v2, -v19, v188, v61
	v_fma_f32 v2, -v20, v189, v2
	v_fma_f32 v2, -v21, v190, v2
	v_fma_f32 v61, -v22, v191, v2
	v_mov_b32_e32 v2, s0
	ds_read_b128 v[192:195], v2
	v_readlane_b32 s0, v245, 14
	s_waitcnt lgkmcnt(0)
	v_fma_f32 v2, -v23, v192, v61
	v_fma_f32 v2, -v24, v193, v2
	v_fma_f32 v2, -v25, v194, v2
	v_fma_f32 v61, -v26, v195, v2
	v_mov_b32_e32 v2, s0
	ds_read_b128 v[200:203], v2
	v_readlane_b32 s0, v245, 15
	s_waitcnt lgkmcnt(0)
	v_fma_f32 v2, -v27, v200, v61
	v_fma_f32 v2, -v28, v201, v2
	v_fma_f32 v2, -v29, v202, v2
	v_fma_f32 v61, -v30, v203, v2
	v_mov_b32_e32 v2, s0
	ds_read_b128 v[216:219], v2
	v_readlane_b32 s0, v245, 16
	s_waitcnt lgkmcnt(0)
	v_fma_f32 v2, -v31, v216, v61
	v_fma_f32 v2, -v32, v217, v2
	v_fma_f32 v2, -v33, v218, v2
	v_fma_f32 v61, -v34, v219, v2
	v_mov_b32_e32 v2, s0
	ds_read_b128 v[212:215], v2
	v_readlane_b32 s0, v245, 17
	s_waitcnt lgkmcnt(0)
	v_fma_f32 v2, -v35, v212, v61
	v_fma_f32 v2, -v36, v213, v2
	v_fma_f32 v2, -v37, v214, v2
	v_fma_f32 v61, -v38, v215, v2
	v_mov_b32_e32 v2, s0
	ds_read_b128 v[180:183], v2
	v_readlane_b32 s0, v245, 18
	s_waitcnt lgkmcnt(0)
	v_fma_f32 v2, -v39, v180, v61
	v_fma_f32 v2, -v40, v181, v2
	v_fma_f32 v2, -v41, v182, v2
	v_fma_f32 v61, -v44, v183, v2
	v_mov_b32_e32 v2, s0
	ds_read_b128 v[160:163], v2
	v_readlane_b32 s0, v245, 19
	s_waitcnt lgkmcnt(0)
	v_fma_f32 v2, -v45, v160, v61
	v_fma_f32 v2, -v46, v161, v2
	v_fma_f32 v2, -v47, v162, v2
	v_fma_f32 v61, -v48, v163, v2
	v_mov_b32_e32 v2, s0
	ds_read_b128 v[184:187], v2
	v_readlane_b32 s0, v245, 20
	s_waitcnt lgkmcnt(0)
	v_fma_f32 v2, -v49, v184, v61
	v_fma_f32 v2, -v50, v185, v2
	v_fma_f32 v2, -v51, v186, v2
	v_fma_f32 v61, -v52, v187, v2
	v_mov_b32_e32 v2, s0
	ds_read_b128 v[164:167], v2
	v_readlane_b32 s0, v245, 21
	s_waitcnt lgkmcnt(0)
	v_fma_f32 v2, -v53, v164, v61
	v_fma_f32 v2, -v55, v165, v2
	v_fma_f32 v2, -v56, v166, v2
	v_fma_f32 v5, -v57, v167, v2
	v_mov_b32_e32 v2, s0
	ds_read_b96 v[196:198], v2
	ds_read_u16 v168, v80 offset:14144
	v_readlane_b32 s0, v245, 23
	s_waitcnt lgkmcnt(1)
	v_fma_f32 v2, -v58, v196, v5
	v_fma_f32 v2, -v59, v197, v2
	v_fma_f32 v61, -v60, v198, v2
	v_bfe_u32 v145, v61, 16, 1
	s_waitcnt lgkmcnt(0)
	v_lshlrev_b32_e32 v64, 16, v168
	v_mov_b32_e32 v2, s0
	v_readlane_b32 s0, v245, 22
	s_nop 1
	v_mov_b32_e32 v3, s0
	v_readlane_b32 s0, v245, 24
	v_cndmask_b32_e32 v2, v2, v3, vcc
	ds_read_b128 v[172:175], v2
	v_mov_b32_e32 v70, s0
	ds_read_b128 v[176:179], v70
	v_readlane_b32 s0, v245, 25
	s_waitcnt lgkmcnt(0)
	v_mul_f32_e32 v70, v7, v176
	v_fma_f32 v2, v172, v64, -v70
	v_fma_f32 v2, -v8, v177, v2
	v_fma_f32 v2, -v9, v178, v2
	v_mov_b32_e32 v64, s0
	ds_read_b128 v[204:207], v64
	v_fma_f32 v2, -v10, v179, v2
	v_readlane_b32 s0, v245, 26
	s_waitcnt lgkmcnt(0)
	v_fma_f32 v2, -v11, v204, v2
	v_fma_f32 v2, -v12, v205, v2
	v_fma_f32 v2, -v13, v206, v2
	v_mov_b32_e32 v64, s0
	ds_read_b128 v[208:211], v64
	v_fma_f32 v2, -v14, v207, v2
	v_readlane_b32 s0, v245, 27
	s_waitcnt lgkmcnt(0)
	v_fma_f32 v2, -v15, v208, v2
	v_fma_f32 v2, -v16, v209, v2
	v_fma_f32 v2, -v17, v210, v2
	v_mov_b32_e32 v64, s0
	ds_read_b128 v[220:223], v64
	v_fma_f32 v2, -v18, v211, v2
	v_readlane_b32 s0, v245, 28
	s_waitcnt lgkmcnt(0)
	v_fma_f32 v2, -v19, v220, v2
	v_fma_f32 v2, -v20, v221, v2
	v_fma_f32 v2, -v21, v222, v2
	v_mov_b32_e32 v64, s0
	ds_read_b128 v[188:191], v64
	v_fma_f32 v2, -v22, v223, v2
	v_readlane_b32 s0, v245, 29
	s_waitcnt lgkmcnt(0)
	v_fma_f32 v2, -v23, v188, v2
	v_fma_f32 v2, -v24, v189, v2
	v_fma_f32 v2, -v25, v190, v2
	v_mov_b32_e32 v64, s0
	ds_read_b128 v[192:195], v64
	v_fma_f32 v2, -v26, v191, v2
	v_readlane_b32 s0, v245, 30
	s_waitcnt lgkmcnt(0)
	v_fma_f32 v2, -v27, v192, v2
	v_fma_f32 v2, -v28, v193, v2
	v_fma_f32 v2, -v29, v194, v2
	v_mov_b32_e32 v64, s0
	ds_read_b128 v[200:203], v64
	v_fma_f32 v2, -v30, v195, v2
	v_readlane_b32 s0, v245, 31
	s_waitcnt lgkmcnt(0)
	v_fma_f32 v2, -v31, v200, v2
	v_fma_f32 v2, -v32, v201, v2
	v_fma_f32 v2, -v33, v202, v2
	v_mov_b32_e32 v64, s0
	ds_read_b128 v[216:219], v64
	v_fma_f32 v2, -v34, v203, v2
	v_readlane_b32 s0, v245, 32
	s_waitcnt lgkmcnt(0)
	v_fma_f32 v2, -v35, v216, v2
	v_fma_f32 v2, -v36, v217, v2
	v_fma_f32 v2, -v37, v218, v2
	v_mov_b32_e32 v64, s0
	ds_read_b128 v[212:215], v64
	v_fma_f32 v2, -v38, v219, v2
	v_readlane_b32 s0, v245, 33
	s_waitcnt lgkmcnt(0)
	v_fma_f32 v2, -v39, v212, v2
	v_fma_f32 v2, -v40, v213, v2
	v_fma_f32 v2, -v41, v214, v2
	v_mov_b32_e32 v64, s0
	ds_read_b128 v[180:183], v64
	v_fma_f32 v2, -v44, v215, v2
	v_readlane_b32 s0, v245, 34
	s_waitcnt lgkmcnt(0)
	v_fma_f32 v2, -v45, v180, v2
	v_fma_f32 v2, -v46, v181, v2
	v_fma_f32 v2, -v47, v182, v2
	v_mov_b32_e32 v64, s0
	ds_read_b128 v[160:163], v64
	v_fma_f32 v2, -v48, v183, v2
	v_readlane_b32 s0, v245, 35
	s_waitcnt lgkmcnt(0)
	v_fma_f32 v2, -v49, v160, v2
	v_fma_f32 v2, -v50, v161, v2
	v_fma_f32 v2, -v51, v162, v2
	v_mov_b32_e32 v64, s0
	ds_read_b128 v[184:187], v64
	v_fma_f32 v2, -v52, v163, v2
	v_readlane_b32 s0, v245, 36
	s_waitcnt lgkmcnt(0)
	v_fma_f32 v2, -v53, v184, v2
	v_fma_f32 v2, -v55, v185, v2
	v_fma_f32 v2, -v56, v186, v2
	v_mov_b32_e32 v64, s0
	ds_read_b128 v[164:167], v64
	ds_read_u16 v196, v80 offset:14416
	v_fma_f32 v2, -v57, v187, v2
	v_readlane_b32 s0, v245, 37
	s_waitcnt lgkmcnt(1)
	v_fma_f32 v2, -v58, v164, v2
	v_fma_f32 v2, -v59, v165, v2
	v_fma_f32 v2, -v60, v166, v2
	v_mov_b32_e32 v70, s0
	ds_read_b128 v[168:171], v70
	v_fma_f32 v64, -v61, v167, v2
	v_readlane_b32 s0, v245, 38
	v_bfe_u32 v146, v64, 16, 1
	s_waitcnt lgkmcnt(1)
	v_lshlrev_b32_e32 v2, 16, v196
	s_waitcnt lgkmcnt(0)
	v_mul_f32_e32 v70, v7, v168
	v_fma_f32 v2, v173, v2, -v70
	v_fma_f32 v2, -v8, v169, v2
	v_fma_f32 v2, -v9, v170, v2
	v_mov_b32_e32 v3, s0
	ds_read_b128 v[176:179], v3
	v_fma_f32 v2, -v10, v171, v2
	v_readlane_b32 s0, v245, 39
	s_waitcnt lgkmcnt(0)
	v_fma_f32 v2, -v11, v176, v2
	v_fma_f32 v2, -v12, v177, v2
	v_fma_f32 v2, -v13, v178, v2
	v_mov_b32_e32 v3, s0
	ds_read_b128 v[204:207], v3
	v_fma_f32 v2, -v14, v179, v2
	v_readlane_b32 s0, v245, 40
	s_waitcnt lgkmcnt(0)
	v_fma_f32 v2, -v15, v204, v2
	v_fma_f32 v2, -v16, v205, v2
	v_fma_f32 v2, -v17, v206, v2
	v_mov_b32_e32 v3, s0
	ds_read_b128 v[208:211], v3
	v_fma_f32 v2, -v18, v207, v2
	v_readlane_b32 s0, v245, 41
	s_waitcnt lgkmcnt(0)
	v_fma_f32 v2, -v19, v208, v2
	v_fma_f32 v2, -v20, v209, v2
	v_fma_f32 v2, -v21, v210, v2
	v_mov_b32_e32 v3, s0
	ds_read_b128 v[220:223], v3
	v_fma_f32 v2, -v22, v211, v2
	v_readlane_b32 s0, v245, 42
	s_waitcnt lgkmcnt(0)
	v_fma_f32 v2, -v23, v220, v2
	v_fma_f32 v2, -v24, v221, v2
	v_fma_f32 v2, -v25, v222, v2
	v_mov_b32_e32 v3, s0
	ds_read_b128 v[188:191], v3
	v_fma_f32 v2, -v26, v223, v2
	v_readlane_b32 s0, v245, 43
	s_waitcnt lgkmcnt(0)
	v_fma_f32 v2, -v27, v188, v2
	v_fma_f32 v2, -v28, v189, v2
	v_fma_f32 v2, -v29, v190, v2
	v_mov_b32_e32 v3, s0
	ds_read_b128 v[192:195], v3
	v_fma_f32 v2, -v30, v191, v2
	v_readlane_b32 s0, v245, 44
	s_waitcnt lgkmcnt(0)
	v_fma_f32 v2, -v31, v192, v2
	v_fma_f32 v2, -v32, v193, v2
	v_fma_f32 v2, -v33, v194, v2
	v_mov_b32_e32 v3, s0
	ds_read_b128 v[200:203], v3
	v_fma_f32 v2, -v34, v195, v2
	v_readlane_b32 s0, v245, 45
	s_waitcnt lgkmcnt(0)
	v_fma_f32 v2, -v35, v200, v2
	v_fma_f32 v2, -v36, v201, v2
	v_fma_f32 v2, -v37, v202, v2
	v_mov_b32_e32 v3, s0
	ds_read_b128 v[216:219], v3
	v_fma_f32 v2, -v38, v203, v2
	v_readlane_b32 s0, v245, 46
	s_waitcnt lgkmcnt(0)
	v_fma_f32 v2, -v39, v216, v2
	v_fma_f32 v2, -v40, v217, v2
	v_fma_f32 v2, -v41, v218, v2
	v_mov_b32_e32 v3, s0
	ds_read_b128 v[212:215], v3
	v_fma_f32 v2, -v44, v219, v2
	v_readlane_b32 s0, v245, 47
	s_waitcnt lgkmcnt(0)
	v_fma_f32 v2, -v45, v212, v2
	v_fma_f32 v2, -v46, v213, v2
	v_fma_f32 v2, -v47, v214, v2
	v_mov_b32_e32 v3, s0
	ds_read_b128 v[180:183], v3
	v_fma_f32 v2, -v48, v215, v2
	v_readlane_b32 s0, v245, 48
	s_waitcnt lgkmcnt(0)
	v_fma_f32 v2, -v49, v180, v2
	v_fma_f32 v2, -v50, v181, v2
	v_fma_f32 v2, -v51, v182, v2
	v_mov_b32_e32 v3, s0
	ds_read_b128 v[160:163], v3
	v_fma_f32 v2, -v52, v183, v2
	v_readlane_b32 s0, v245, 49
	s_waitcnt lgkmcnt(0)
	v_fma_f32 v2, -v53, v160, v2
	v_fma_f32 v2, -v55, v161, v2
	v_fma_f32 v2, -v56, v162, v2
	v_mov_b32_e32 v3, s0
	ds_read_b128 v[184:187], v3
	v_fma_f32 v2, -v57, v163, v2
	v_readlane_b32 s0, v245, 50
	s_waitcnt lgkmcnt(0)
	v_fma_f32 v2, -v58, v184, v2
	v_mov_b32_e32 v3, s0
	ds_read_b32 v164, v3
	ds_read_u16 v196, v80 offset:14688
	v_fma_f32 v2, -v59, v185, v2
	v_fma_f32 v2, -v60, v186, v2
	v_fma_f32 v2, -v61, v187, v2
	v_readlane_b32 s0, v245, 51
	s_waitcnt lgkmcnt(1)
	v_fma_f32 v70, -v64, v164, v2
	v_mov_b32_e32 v3, s0
	ds_read_b128 v[168:171], v3
	v_readlane_b32 s0, v245, 52
	v_bfe_u32 v147, v70, 16, 1
	s_waitcnt lgkmcnt(1)
	v_lshlrev_b32_e32 v2, 16, v196
	s_waitcnt lgkmcnt(0)
	v_mul_f32_e32 v3, v7, v168
	v_fma_f32 v2, v174, v2, -v3
	v_fma_f32 v2, -v8, v169, v2
	v_fma_f32 v2, -v9, v170, v2
	v_mov_b32_e32 v3, s0
	ds_read_b128 v[176:179], v3
	v_fma_f32 v2, -v10, v171, v2
	v_readlane_b32 s0, v245, 53
	s_waitcnt lgkmcnt(0)
	v_fma_f32 v2, -v11, v176, v2
	v_fma_f32 v2, -v12, v177, v2
	v_fma_f32 v2, -v13, v178, v2
	v_mov_b32_e32 v3, s0
	ds_read_b128 v[204:207], v3
	v_fma_f32 v2, -v14, v179, v2
	v_readlane_b32 s0, v245, 54
	s_waitcnt lgkmcnt(0)
	v_fma_f32 v2, -v15, v204, v2
	v_fma_f32 v2, -v16, v205, v2
	v_fma_f32 v2, -v17, v206, v2
	v_mov_b32_e32 v3, s0
	ds_read_b128 v[208:211], v3
	v_fma_f32 v2, -v18, v207, v2
	v_readlane_b32 s0, v245, 55
	s_waitcnt lgkmcnt(0)
	v_fma_f32 v2, -v19, v208, v2
	v_fma_f32 v2, -v20, v209, v2
	v_fma_f32 v2, -v21, v210, v2
	v_mov_b32_e32 v3, s0
	ds_read_b128 v[220:223], v3
	v_fma_f32 v2, -v22, v211, v2
	v_readlane_b32 s0, v245, 56
	s_waitcnt lgkmcnt(0)
	v_fma_f32 v2, -v23, v220, v2
	v_fma_f32 v2, -v24, v221, v2
	v_fma_f32 v2, -v25, v222, v2
	v_mov_b32_e32 v3, s0
	ds_read_b128 v[188:191], v3
	v_fma_f32 v2, -v26, v223, v2
	v_readlane_b32 s0, v245, 57
	s_waitcnt lgkmcnt(0)
	v_fma_f32 v2, -v27, v188, v2
	v_fma_f32 v2, -v28, v189, v2
	v_fma_f32 v2, -v29, v190, v2
	v_mov_b32_e32 v3, s0
	ds_read_b128 v[192:195], v3
	v_fma_f32 v2, -v30, v191, v2
	v_readlane_b32 s0, v245, 58
	s_waitcnt lgkmcnt(0)
	v_fma_f32 v2, -v31, v192, v2
	v_fma_f32 v2, -v32, v193, v2
	v_fma_f32 v2, -v33, v194, v2
	v_mov_b32_e32 v3, s0
	ds_read_b128 v[200:203], v3
	v_fma_f32 v2, -v34, v195, v2
	v_readlane_b32 s0, v245, 59
	s_waitcnt lgkmcnt(0)
	v_fma_f32 v2, -v35, v200, v2
	v_fma_f32 v2, -v36, v201, v2
	v_fma_f32 v2, -v37, v202, v2
	v_mov_b32_e32 v3, s0
	ds_read_b128 v[216:219], v3
	v_fma_f32 v2, -v38, v203, v2
	v_readlane_b32 s0, v245, 60
	s_waitcnt lgkmcnt(0)
	v_fma_f32 v2, -v39, v216, v2
	v_fma_f32 v2, -v40, v217, v2
	v_fma_f32 v2, -v41, v218, v2
	v_mov_b32_e32 v3, s0
	ds_read_b128 v[212:215], v3
	v_fma_f32 v2, -v44, v219, v2
	v_readlane_b32 s0, v245, 61
	s_waitcnt lgkmcnt(0)
	v_fma_f32 v2, -v45, v212, v2
	v_fma_f32 v2, -v46, v213, v2
	v_fma_f32 v2, -v47, v214, v2
	v_mov_b32_e32 v3, s0
	ds_read_b128 v[180:183], v3
	v_fma_f32 v2, -v48, v215, v2
	v_readlane_b32 s0, v245, 62
	s_waitcnt lgkmcnt(0)
	v_fma_f32 v2, -v49, v180, v2
	v_fma_f32 v2, -v50, v181, v2
	v_fma_f32 v2, -v51, v182, v2
	v_mov_b32_e32 v3, s0
	ds_read_b128 v[160:163], v3
	v_fma_f32 v2, -v52, v183, v2
	v_readlane_b32 s0, v245, 63
	s_waitcnt lgkmcnt(0)
	v_fma_f32 v2, -v53, v160, v2
	v_fma_f32 v2, -v55, v161, v2
	v_fma_f32 v2, -v56, v162, v2
	v_mov_b32_e32 v3, s0
	ds_read_b128 v[184:187], v3
	v_fma_f32 v2, -v57, v163, v2
	v_readlane_b32 s0, v244, 0
	s_waitcnt lgkmcnt(0)
	v_fma_f32 v2, -v58, v184, v2
	v_fma_f32 v2, -v59, v185, v2
	v_fma_f32 v2, -v60, v186, v2
	v_fma_f32 v4, -v61, v187, v2
	v_mov_b32_e32 v2, s0
	ds_read_b64 v[164:165], v2
	ds_read_u16 v196, v80 offset:14960
	v_readlane_b32 s0, v244, 1
	s_waitcnt lgkmcnt(1)
	v_fma_f32 v2, -v64, v164, v4
	v_fma_f32 v71, -v70, v165, v2
	v_mov_b32_e32 v3, s0
	ds_read_b128 v[168:171], v3
	v_readlane_b32 s0, v244, 2
	v_bfe_u32 v148, v71, 16, 1
	s_waitcnt lgkmcnt(1)
	v_lshlrev_b32_e32 v2, 16, v196
	s_waitcnt lgkmcnt(0)
	v_mul_f32_e32 v3, v7, v168
	v_fma_f32 v2, v175, v2, -v3
	v_fma_f32 v2, -v8, v169, v2
	v_fma_f32 v2, -v9, v170, v2
	v_fma_f32 v72, -v10, v171, v2
	v_mov_b32_e32 v2, s0
	ds_read_b128 v[176:179], v2
	v_readlane_b32 s0, v244, 3
	s_waitcnt lgkmcnt(0)
	v_fma_f32 v2, -v11, v176, v72
	v_fma_f32 v2, -v12, v177, v2
	v_fma_f32 v2, -v13, v178, v2
	v_fma_f32 v72, -v14, v179, v2
	v_mov_b32_e32 v2, s0
	ds_read_b128 v[204:207], v2
	v_readlane_b32 s0, v244, 4
	s_waitcnt lgkmcnt(0)
	v_fma_f32 v2, -v15, v204, v72
	v_fma_f32 v2, -v16, v205, v2
	v_fma_f32 v2, -v17, v206, v2
	v_fma_f32 v72, -v18, v207, v2
	v_mov_b32_e32 v2, s0
	ds_read_b128 v[208:211], v2
	v_readlane_b32 s0, v244, 5
	s_waitcnt lgkmcnt(0)
	v_fma_f32 v2, -v19, v208, v72
	v_fma_f32 v2, -v20, v209, v2
	v_fma_f32 v2, -v21, v210, v2
	v_fma_f32 v72, -v22, v211, v2
	v_mov_b32_e32 v2, s0
	ds_read_b128 v[220:223], v2
	v_readlane_b32 s0, v244, 6
	s_waitcnt lgkmcnt(0)
	v_fma_f32 v2, -v23, v220, v72
	v_fma_f32 v2, -v24, v221, v2
	v_fma_f32 v2, -v25, v222, v2
	v_fma_f32 v72, -v26, v223, v2
	v_mov_b32_e32 v2, s0
	ds_read_b128 v[188:191], v2
	v_readlane_b32 s0, v244, 7
	s_waitcnt lgkmcnt(0)
	v_fma_f32 v2, -v27, v188, v72
	v_fma_f32 v2, -v28, v189, v2
	v_fma_f32 v2, -v29, v190, v2
	v_fma_f32 v72, -v30, v191, v2
	v_mov_b32_e32 v2, s0
	ds_read_b128 v[192:195], v2
	v_readlane_b32 s0, v244, 8
	s_waitcnt lgkmcnt(0)
	v_fma_f32 v2, -v31, v192, v72
	v_fma_f32 v2, -v32, v193, v2
	v_fma_f32 v2, -v33, v194, v2
	v_fma_f32 v72, -v34, v195, v2
	v_mov_b32_e32 v2, s0
	ds_read_b128 v[200:203], v2
	v_readlane_b32 s0, v244, 9
	s_waitcnt lgkmcnt(0)
	v_fma_f32 v2, -v35, v200, v72
	v_fma_f32 v2, -v36, v201, v2
	v_fma_f32 v2, -v37, v202, v2
	v_fma_f32 v72, -v38, v203, v2
	v_mov_b32_e32 v2, s0
	ds_read_b128 v[216:219], v2
	v_readlane_b32 s0, v244, 10
	s_waitcnt lgkmcnt(0)
	v_fma_f32 v2, -v39, v216, v72
	v_fma_f32 v2, -v40, v217, v2
	v_fma_f32 v2, -v41, v218, v2
	v_fma_f32 v72, -v44, v219, v2
	v_mov_b32_e32 v2, s0
	ds_read_b128 v[212:215], v2
	v_readlane_b32 s0, v244, 11
	s_waitcnt lgkmcnt(0)
	v_fma_f32 v2, -v45, v212, v72
	v_fma_f32 v2, -v46, v213, v2
	v_fma_f32 v2, -v47, v214, v2
	v_fma_f32 v72, -v48, v215, v2
	v_mov_b32_e32 v2, s0
	ds_read_b128 v[180:183], v2
	v_readlane_b32 s0, v244, 12
	s_waitcnt lgkmcnt(0)
	v_fma_f32 v2, -v49, v180, v72
	v_fma_f32 v2, -v50, v181, v2
	v_fma_f32 v2, -v51, v182, v2
	v_fma_f32 v72, -v52, v183, v2
	v_mov_b32_e32 v2, s0
	ds_read_b128 v[160:163], v2
	v_readlane_b32 s0, v244, 13
	s_waitcnt lgkmcnt(0)
	v_fma_f32 v2, -v53, v160, v72
	v_fma_f32 v2, -v55, v161, v2
	v_fma_f32 v2, -v56, v162, v2
	v_fma_f32 v72, -v57, v163, v2
	v_mov_b32_e32 v2, s0
	ds_read_b128 v[184:187], v2
	v_readlane_b32 s0, v244, 14
	s_waitcnt lgkmcnt(0)
	v_fma_f32 v2, -v58, v184, v72
	v_fma_f32 v2, -v59, v185, v2
	v_fma_f32 v2, -v60, v186, v2
	v_fma_f32 v5, -v61, v187, v2
	v_mov_b32_e32 v2, s0
	ds_read_b96 v[164:166], v2
	ds_read_u16 v196, v80 offset:15232
	v_readlane_b32 s0, v244, 16
	s_waitcnt lgkmcnt(1)
	v_fma_f32 v2, -v64, v164, v5
	v_fma_f32 v2, -v70, v165, v2
	v_fma_f32 v72, -v71, v166, v2
	v_bfe_u32 v149, v72, 16, 1
	s_waitcnt lgkmcnt(0)
	v_lshlrev_b32_e32 v73, 16, v196
	v_mov_b32_e32 v2, s0
	v_readlane_b32 s0, v244, 15
	s_nop 1
	v_mov_b32_e32 v3, s0
	v_readlane_b32 s0, v244, 17
	v_cndmask_b32_e32 v2, v2, v3, vcc
	ds_read_b128 v[172:175], v2
	v_mov_b32_e32 v74, s0
	ds_read_b128 v[168:171], v74
	v_readlane_b32 s0, v244, 18
	s_waitcnt lgkmcnt(0)
	v_mul_f32_e32 v74, v7, v168
	v_fma_f32 v2, v172, v73, -v74
	v_fma_f32 v2, -v8, v169, v2
	v_fma_f32 v2, -v9, v170, v2
	v_mov_b32_e32 v73, s0
	ds_read_b128 v[176:179], v73
	v_fma_f32 v2, -v10, v171, v2
	v_readlane_b32 s0, v244, 19
	s_waitcnt lgkmcnt(0)
	v_fma_f32 v2, -v11, v176, v2
	v_fma_f32 v2, -v12, v177, v2
	v_fma_f32 v2, -v13, v178, v2
	v_mov_b32_e32 v73, s0
	ds_read_b128 v[204:207], v73
	v_fma_f32 v2, -v14, v179, v2
	v_readlane_b32 s0, v244, 20
	s_waitcnt lgkmcnt(0)
	v_fma_f32 v2, -v15, v204, v2
	v_fma_f32 v2, -v16, v205, v2
	v_fma_f32 v2, -v17, v206, v2
	v_mov_b32_e32 v73, s0
	ds_read_b128 v[208:211], v73
	v_fma_f32 v2, -v18, v207, v2
	v_readlane_b32 s0, v244, 21
	s_waitcnt lgkmcnt(0)
	v_fma_f32 v2, -v19, v208, v2
	v_fma_f32 v2, -v20, v209, v2
	v_fma_f32 v2, -v21, v210, v2
	v_mov_b32_e32 v73, s0
	ds_read_b128 v[220:223], v73
	v_fma_f32 v2, -v22, v211, v2
	v_readlane_b32 s0, v244, 22
	s_waitcnt lgkmcnt(0)
	v_fma_f32 v2, -v23, v220, v2
	v_fma_f32 v2, -v24, v221, v2
	v_fma_f32 v2, -v25, v222, v2
	v_mov_b32_e32 v73, s0
	ds_read_b128 v[188:191], v73
	v_fma_f32 v2, -v26, v223, v2
	v_readlane_b32 s0, v244, 23
	s_waitcnt lgkmcnt(0)
	v_fma_f32 v2, -v27, v188, v2
	v_fma_f32 v2, -v28, v189, v2
	v_fma_f32 v2, -v29, v190, v2
	v_mov_b32_e32 v73, s0
	ds_read_b128 v[192:195], v73
	v_fma_f32 v2, -v30, v191, v2
	v_readlane_b32 s0, v244, 24
	s_waitcnt lgkmcnt(0)
	v_fma_f32 v2, -v31, v192, v2
	v_fma_f32 v2, -v32, v193, v2
	v_fma_f32 v2, -v33, v194, v2
	v_mov_b32_e32 v73, s0
	ds_read_b128 v[200:203], v73
	v_fma_f32 v2, -v34, v195, v2
	v_readlane_b32 s0, v244, 25
	s_waitcnt lgkmcnt(0)
	v_fma_f32 v2, -v35, v200, v2
	v_fma_f32 v2, -v36, v201, v2
	v_fma_f32 v2, -v37, v202, v2
	v_mov_b32_e32 v73, s0
	ds_read_b128 v[216:219], v73
	v_fma_f32 v2, -v38, v203, v2
	v_readlane_b32 s0, v244, 26
	s_waitcnt lgkmcnt(0)
	v_fma_f32 v2, -v39, v216, v2
	v_fma_f32 v2, -v40, v217, v2
	v_fma_f32 v2, -v41, v218, v2
	v_mov_b32_e32 v73, s0
	ds_read_b128 v[212:215], v73
	v_fma_f32 v2, -v44, v219, v2
	v_readlane_b32 s0, v244, 27
	s_waitcnt lgkmcnt(0)
	v_fma_f32 v2, -v45, v212, v2
	v_fma_f32 v2, -v46, v213, v2
	v_fma_f32 v2, -v47, v214, v2
	v_mov_b32_e32 v73, s0
	ds_read_b128 v[180:183], v73
	v_fma_f32 v2, -v48, v215, v2
	v_readlane_b32 s0, v244, 28
	s_waitcnt lgkmcnt(0)
	v_fma_f32 v2, -v49, v180, v2
	v_fma_f32 v2, -v50, v181, v2
	v_fma_f32 v2, -v51, v182, v2
	v_mov_b32_e32 v73, s0
	ds_read_b128 v[160:163], v73
	v_fma_f32 v2, -v52, v183, v2
	v_readlane_b32 s0, v244, 29
	s_waitcnt lgkmcnt(0)
	v_fma_f32 v2, -v53, v160, v2
	v_fma_f32 v2, -v55, v161, v2
	v_fma_f32 v2, -v56, v162, v2
	v_mov_b32_e32 v73, s0
	ds_read_b128 v[184:187], v73
	v_fma_f32 v2, -v57, v163, v2
	v_readlane_b32 s0, v244, 30
	s_waitcnt lgkmcnt(0)
	v_fma_f32 v2, -v58, v184, v2
	v_fma_f32 v2, -v59, v185, v2
	v_fma_f32 v2, -v60, v186, v2
	v_mov_b32_e32 v73, s0
	ds_read_b128 v[164:167], v73
	ds_read_u16 v196, v80 offset:15504
	v_fma_f32 v2, -v61, v187, v2
	v_readlane_b32 s0, v244, 31
	s_waitcnt lgkmcnt(1)
	v_fma_f32 v2, -v64, v164, v2
	v_fma_f32 v2, -v70, v165, v2
	v_fma_f32 v2, -v71, v166, v2
	v_mov_b32_e32 v74, s0
	ds_read_b128 v[168:171], v74
	v_fma_f32 v73, -v72, v167, v2
	v_readlane_b32 s0, v244, 32
	v_bfe_u32 v150, v73, 16, 1
	s_waitcnt lgkmcnt(1)
	v_lshlrev_b32_e32 v2, 16, v196
	s_waitcnt lgkmcnt(0)
	v_mul_f32_e32 v74, v7, v168
	v_fma_f32 v2, v173, v2, -v74
	v_fma_f32 v2, -v8, v169, v2
	v_fma_f32 v2, -v9, v170, v2
	v_mov_b32_e32 v3, s0
	ds_read_b128 v[176:179], v3
	v_fma_f32 v2, -v10, v171, v2
	v_readlane_b32 s0, v244, 33
	s_waitcnt lgkmcnt(0)
	v_fma_f32 v2, -v11, v176, v2
	v_fma_f32 v2, -v12, v177, v2
	v_fma_f32 v2, -v13, v178, v2
	v_mov_b32_e32 v3, s0
	ds_read_b128 v[204:207], v3
	v_fma_f32 v2, -v14, v179, v2
	v_readlane_b32 s0, v244, 34
	s_waitcnt lgkmcnt(0)
	v_fma_f32 v2, -v15, v204, v2
	v_fma_f32 v2, -v16, v205, v2
	v_fma_f32 v2, -v17, v206, v2
	v_mov_b32_e32 v3, s0
	ds_read_b128 v[208:211], v3
	v_fma_f32 v2, -v18, v207, v2
	v_readlane_b32 s0, v244, 35
	s_waitcnt lgkmcnt(0)
	v_fma_f32 v2, -v19, v208, v2
	v_fma_f32 v2, -v20, v209, v2
	v_fma_f32 v2, -v21, v210, v2
	v_mov_b32_e32 v3, s0
	ds_read_b128 v[220:223], v3
	v_fma_f32 v2, -v22, v211, v2
	v_readlane_b32 s0, v244, 36
	s_waitcnt lgkmcnt(0)
	v_fma_f32 v2, -v23, v220, v2
	v_fma_f32 v2, -v24, v221, v2
	v_fma_f32 v2, -v25, v222, v2
	v_mov_b32_e32 v3, s0
	ds_read_b128 v[188:191], v3
	v_fma_f32 v2, -v26, v223, v2
	v_readlane_b32 s0, v244, 37
	s_waitcnt lgkmcnt(0)
	v_fma_f32 v2, -v27, v188, v2
	v_fma_f32 v2, -v28, v189, v2
	v_fma_f32 v2, -v29, v190, v2
	v_mov_b32_e32 v3, s0
	ds_read_b128 v[192:195], v3
	v_fma_f32 v2, -v30, v191, v2
	v_readlane_b32 s0, v244, 38
	s_waitcnt lgkmcnt(0)
	v_fma_f32 v2, -v31, v192, v2
	v_fma_f32 v2, -v32, v193, v2
	v_fma_f32 v2, -v33, v194, v2
	v_mov_b32_e32 v3, s0
	ds_read_b128 v[200:203], v3
	v_fma_f32 v2, -v34, v195, v2
	v_readlane_b32 s0, v244, 39
	s_waitcnt lgkmcnt(0)
	v_fma_f32 v2, -v35, v200, v2
	v_fma_f32 v2, -v36, v201, v2
	v_fma_f32 v2, -v37, v202, v2
	v_mov_b32_e32 v3, s0
	ds_read_b128 v[216:219], v3
	v_fma_f32 v2, -v38, v203, v2
	v_readlane_b32 s0, v244, 40
	s_waitcnt lgkmcnt(0)
	v_fma_f32 v2, -v39, v216, v2
	v_fma_f32 v2, -v40, v217, v2
	v_fma_f32 v2, -v41, v218, v2
	v_mov_b32_e32 v3, s0
	ds_read_b128 v[212:215], v3
	v_fma_f32 v2, -v44, v219, v2
	v_readlane_b32 s0, v244, 41
	s_waitcnt lgkmcnt(0)
	v_fma_f32 v2, -v45, v212, v2
	v_fma_f32 v2, -v46, v213, v2
	v_fma_f32 v2, -v47, v214, v2
	v_mov_b32_e32 v3, s0
	ds_read_b128 v[180:183], v3
	v_fma_f32 v2, -v48, v215, v2
	v_readlane_b32 s0, v244, 42
	s_waitcnt lgkmcnt(0)
	v_fma_f32 v2, -v49, v180, v2
	v_fma_f32 v2, -v50, v181, v2
	v_fma_f32 v2, -v51, v182, v2
	v_mov_b32_e32 v3, s0
	ds_read_b128 v[160:163], v3
	v_fma_f32 v2, -v52, v183, v2
	v_readlane_b32 s0, v244, 43
	s_waitcnt lgkmcnt(0)
	v_fma_f32 v2, -v53, v160, v2
	v_fma_f32 v2, -v55, v161, v2
	v_fma_f32 v2, -v56, v162, v2
	v_mov_b32_e32 v3, s0
	ds_read_b128 v[184:187], v3
	v_fma_f32 v2, -v57, v163, v2
	v_readlane_b32 s0, v244, 44
	s_waitcnt lgkmcnt(0)
	v_fma_f32 v2, -v58, v184, v2
	v_fma_f32 v2, -v59, v185, v2
	v_fma_f32 v2, -v60, v186, v2
	v_mov_b32_e32 v3, s0
	ds_read_b128 v[164:167], v3
	v_fma_f32 v2, -v61, v187, v2
	v_readlane_b32 s0, v244, 45
	s_waitcnt lgkmcnt(0)
	v_fma_f32 v2, -v64, v164, v2
	v_mov_b32_e32 v3, s0
	ds_read_b32 v196, v3
	ds_read_u16 v168, v80 offset:15776
	v_fma_f32 v2, -v70, v165, v2
	v_fma_f32 v2, -v71, v166, v2
	v_fma_f32 v2, -v72, v167, v2
	v_readlane_b32 s0, v244, 46
	s_waitcnt lgkmcnt(1)
	v_fma_f32 v74, -v73, v196, v2
	v_mov_b32_e32 v3, s0
	ds_read_b128 v[176:179], v3
	v_readlane_b32 s0, v244, 47
	v_bfe_u32 v151, v74, 16, 1
	s_waitcnt lgkmcnt(1)
	v_lshlrev_b32_e32 v2, 16, v168
	s_waitcnt lgkmcnt(0)
	v_mul_f32_e32 v3, v7, v176
	v_fma_f32 v2, v174, v2, -v3
	v_fma_f32 v2, -v8, v177, v2
	v_fma_f32 v2, -v9, v178, v2
	v_mov_b32_e32 v3, s0
	ds_read_b128 v[204:207], v3
	v_fma_f32 v2, -v10, v179, v2
	v_readlane_b32 s0, v244, 48
	s_waitcnt lgkmcnt(0)
	v_fma_f32 v2, -v11, v204, v2
	v_fma_f32 v2, -v12, v205, v2
	v_fma_f32 v2, -v13, v206, v2
	v_mov_b32_e32 v3, s0
	ds_read_b128 v[208:211], v3
	v_fma_f32 v2, -v14, v207, v2
	v_readlane_b32 s0, v244, 49
	s_waitcnt lgkmcnt(0)
	v_fma_f32 v2, -v15, v208, v2
	v_fma_f32 v2, -v16, v209, v2
	v_fma_f32 v2, -v17, v210, v2
	v_mov_b32_e32 v3, s0
	ds_read_b128 v[220:223], v3
	v_fma_f32 v2, -v18, v211, v2
	v_readlane_b32 s0, v244, 50
	s_waitcnt lgkmcnt(0)
	v_fma_f32 v2, -v19, v220, v2
	v_fma_f32 v2, -v20, v221, v2
	v_fma_f32 v2, -v21, v222, v2
	v_mov_b32_e32 v3, s0
	ds_read_b128 v[188:191], v3
	v_fma_f32 v2, -v22, v223, v2
	v_readlane_b32 s0, v244, 51
	s_waitcnt lgkmcnt(0)
	v_fma_f32 v2, -v23, v188, v2
	v_fma_f32 v2, -v24, v189, v2
	v_fma_f32 v2, -v25, v190, v2
	v_mov_b32_e32 v3, s0
	ds_read_b128 v[192:195], v3
	v_fma_f32 v2, -v26, v191, v2
	v_readlane_b32 s0, v244, 52
	s_waitcnt lgkmcnt(0)
	v_fma_f32 v2, -v27, v192, v2
	v_fma_f32 v2, -v28, v193, v2
	v_fma_f32 v2, -v29, v194, v2
	v_mov_b32_e32 v3, s0
	ds_read_b128 v[200:203], v3
	v_fma_f32 v2, -v30, v195, v2
	v_readlane_b32 s0, v244, 53
	s_waitcnt lgkmcnt(0)
	v_fma_f32 v2, -v31, v200, v2
	v_fma_f32 v2, -v32, v201, v2
	v_fma_f32 v2, -v33, v202, v2
	v_mov_b32_e32 v3, s0
	ds_read_b128 v[216:219], v3
	v_fma_f32 v2, -v34, v203, v2
	v_readlane_b32 s0, v244, 54
	s_waitcnt lgkmcnt(0)
	v_fma_f32 v2, -v35, v216, v2
	v_fma_f32 v2, -v36, v217, v2
	v_fma_f32 v2, -v37, v218, v2
	v_mov_b32_e32 v3, s0
	ds_read_b128 v[212:215], v3
	v_fma_f32 v2, -v38, v219, v2
	v_readlane_b32 s0, v244, 55
	s_waitcnt lgkmcnt(0)
	v_fma_f32 v2, -v39, v212, v2
	v_fma_f32 v2, -v40, v213, v2
	v_fma_f32 v2, -v41, v214, v2
	v_mov_b32_e32 v3, s0
	ds_read_b128 v[180:183], v3
	v_fma_f32 v2, -v44, v215, v2
	v_readlane_b32 s0, v244, 56
	s_waitcnt lgkmcnt(0)
	v_fma_f32 v2, -v45, v180, v2
	v_fma_f32 v2, -v46, v181, v2
	v_fma_f32 v2, -v47, v182, v2
	v_mov_b32_e32 v3, s0
	ds_read_b128 v[160:163], v3
	v_fma_f32 v2, -v48, v183, v2
	v_readlane_b32 s0, v244, 57
	s_waitcnt lgkmcnt(0)
	v_fma_f32 v2, -v49, v160, v2
	v_fma_f32 v2, -v50, v161, v2
	v_fma_f32 v2, -v51, v162, v2
	v_mov_b32_e32 v3, s0
	ds_read_b128 v[184:187], v3
	v_fma_f32 v2, -v52, v163, v2
	v_readlane_b32 s0, v244, 58
	s_waitcnt lgkmcnt(0)
	v_fma_f32 v2, -v53, v184, v2
	v_fma_f32 v2, -v55, v185, v2
	v_fma_f32 v2, -v56, v186, v2
	v_mov_b32_e32 v3, s0
	ds_read_b128 v[164:167], v3
	v_fma_f32 v2, -v57, v187, v2
	v_readlane_b32 s0, v244, 59
	s_waitcnt lgkmcnt(0)
	v_fma_f32 v2, -v58, v164, v2
	v_fma_f32 v2, -v59, v165, v2
	v_fma_f32 v2, -v60, v166, v2
	v_mov_b32_e32 v3, s0
	ds_read_b128 v[196:199], v3
	v_fma_f32 v2, -v61, v167, v2
	v_readlane_b32 s0, v244, 60
	s_waitcnt lgkmcnt(0)
	v_fma_f32 v2, -v64, v196, v2
	v_fma_f32 v2, -v70, v197, v2
	v_fma_f32 v2, -v71, v198, v2
	v_fma_f32 v4, -v72, v199, v2
	v_mov_b32_e32 v2, s0
	ds_read_b64 v[168:169], v2
	ds_read_u16 v176, v80 offset:16048
	v_readlane_b32 s0, v244, 61
	s_waitcnt lgkmcnt(1)
	v_fma_f32 v2, -v73, v168, v4
	v_fma_f32 v75, -v74, v169, v2
	v_mov_b32_e32 v3, s0
	ds_read_b128 v[204:207], v3
	v_readlane_b32 s0, v244, 62
	v_bfe_u32 v152, v75, 16, 1
	s_waitcnt lgkmcnt(1)
	v_lshlrev_b32_e32 v2, 16, v176
	s_waitcnt lgkmcnt(0)
	v_mul_f32_e32 v3, v7, v204
	v_fma_f32 v2, v175, v2, -v3
	v_fma_f32 v2, -v8, v205, v2
	v_fma_f32 v2, -v9, v206, v2
	v_fma_f32 v76, -v10, v207, v2
	v_mov_b32_e32 v2, s0
	ds_read_b128 v[208:211], v2
	v_readlane_b32 s0, v244, 63
	s_waitcnt lgkmcnt(0)
	v_fma_f32 v2, -v11, v208, v76
	v_fma_f32 v2, -v12, v209, v2
	v_fma_f32 v2, -v13, v210, v2
	v_fma_f32 v76, -v14, v211, v2
	v_mov_b32_e32 v2, s0
	ds_read_b128 v[220:223], v2
	v_readlane_b32 s0, v246, 0
	s_waitcnt lgkmcnt(0)
	v_fma_f32 v2, -v15, v220, v76
	v_fma_f32 v2, -v16, v221, v2
	v_fma_f32 v2, -v17, v222, v2
	v_fma_f32 v76, -v18, v223, v2
	v_mov_b32_e32 v2, s0
	ds_read_b128 v[188:191], v2
	v_readlane_b32 s0, v246, 1
	s_waitcnt lgkmcnt(0)
	v_fma_f32 v2, -v19, v188, v76
	v_fma_f32 v2, -v20, v189, v2
	v_fma_f32 v2, -v21, v190, v2
	v_fma_f32 v76, -v22, v191, v2
	v_mov_b32_e32 v2, s0
	ds_read_b128 v[192:195], v2
	v_readlane_b32 s0, v246, 2
	s_waitcnt lgkmcnt(0)
	v_fma_f32 v2, -v23, v192, v76
	v_fma_f32 v2, -v24, v193, v2
	v_fma_f32 v2, -v25, v194, v2
	v_fma_f32 v76, -v26, v195, v2
	v_mov_b32_e32 v2, s0
	ds_read_b128 v[200:203], v2
	v_readlane_b32 s0, v246, 3
	s_waitcnt lgkmcnt(0)
	v_fma_f32 v2, -v27, v200, v76
	v_fma_f32 v2, -v28, v201, v2
	v_fma_f32 v2, -v29, v202, v2
	v_fma_f32 v76, -v30, v203, v2
	v_mov_b32_e32 v2, s0
	ds_read_b128 v[216:219], v2
	v_readlane_b32 s0, v246, 4
	s_waitcnt lgkmcnt(0)
	v_fma_f32 v2, -v31, v216, v76
	v_fma_f32 v2, -v32, v217, v2
	v_fma_f32 v2, -v33, v218, v2
	v_fma_f32 v76, -v34, v219, v2
	v_mov_b32_e32 v2, s0
	ds_read_b128 v[212:215], v2
	v_readlane_b32 s0, v246, 5
	s_waitcnt lgkmcnt(0)
	v_fma_f32 v2, -v35, v212, v76
	v_fma_f32 v2, -v36, v213, v2
	v_fma_f32 v2, -v37, v214, v2
	v_fma_f32 v76, -v38, v215, v2
	v_mov_b32_e32 v2, s0
	ds_read_b128 v[180:183], v2
	v_readlane_b32 s0, v246, 6
	s_waitcnt lgkmcnt(0)
	v_fma_f32 v2, -v39, v180, v76
	v_fma_f32 v2, -v40, v181, v2
	v_fma_f32 v2, -v41, v182, v2
	v_fma_f32 v76, -v44, v183, v2
	v_mov_b32_e32 v2, s0
	ds_read_b128 v[160:163], v2
	v_readlane_b32 s0, v246, 7
	s_waitcnt lgkmcnt(0)
	v_fma_f32 v2, -v45, v160, v76
	v_fma_f32 v2, -v46, v161, v2
	v_fma_f32 v2, -v47, v162, v2
	v_fma_f32 v76, -v48, v163, v2
	v_mov_b32_e32 v2, s0
	ds_read_b128 v[184:187], v2
	v_readlane_b32 s0, v246, 8
	s_waitcnt lgkmcnt(0)
	v_fma_f32 v2, -v49, v184, v76
	v_fma_f32 v2, -v50, v185, v2
	v_fma_f32 v2, -v51, v186, v2
	v_fma_f32 v76, -v52, v187, v2
	v_mov_b32_e32 v2, s0
	ds_read_b128 v[164:167], v2
	v_readlane_b32 s0, v246, 9
	s_waitcnt lgkmcnt(0)
	v_fma_f32 v2, -v53, v164, v76
	v_fma_f32 v2, -v55, v165, v2
	v_fma_f32 v2, -v56, v166, v2
	v_fma_f32 v76, -v57, v167, v2
	v_mov_b32_e32 v2, s0
	ds_read_b128 v[196:199], v2
	v_readlane_b32 s0, v246, 10
	s_waitcnt lgkmcnt(0)
	v_fma_f32 v2, -v58, v196, v76
	v_fma_f32 v2, -v59, v197, v2
	v_fma_f32 v2, -v60, v198, v2
	v_fma_f32 v76, -v61, v199, v2
	v_mov_b32_e32 v2, s0
	ds_read_b128 v[168:171], v2
	v_readlane_b32 s0, v246, 11
	s_waitcnt lgkmcnt(0)
	v_fma_f32 v2, -v64, v168, v76
	v_fma_f32 v2, -v70, v169, v2
	v_fma_f32 v2, -v71, v170, v2
	v_fma_f32 v5, -v72, v171, v2
	v_mov_b32_e32 v2, s0
	ds_read_b96 v[176:178], v2
	ds_read_u16 v172, v80 offset:16320
	v_readlane_b32 s0, v246, 13
	s_waitcnt lgkmcnt(1)
	v_fma_f32 v2, -v73, v176, v5
	v_fma_f32 v2, -v74, v177, v2
	v_fma_f32 v76, -v75, v178, v2
	v_bfe_u32 v153, v76, 16, 1
	s_waitcnt lgkmcnt(0)
	v_lshlrev_b32_e32 v77, 16, v172
	v_mov_b32_e32 v2, s0
	v_readlane_b32 s0, v246, 12
	s_nop 1
	v_mov_b32_e32 v3, s0
	v_readlane_b32 s0, v246, 14
	v_cndmask_b32_e32 v2, v2, v3, vcc
	ds_read_b128 v[204:207], v2
	v_mov_b32_e32 v78, s0
	ds_read_b128 v[208:211], v78
	v_readlane_b32 s0, v246, 15
	s_waitcnt lgkmcnt(0)
	v_mul_f32_e32 v78, v7, v208
	v_fma_f32 v2, v204, v77, -v78
	v_fma_f32 v2, -v8, v209, v2
	v_fma_f32 v2, -v9, v210, v2
	v_mov_b32_e32 v77, s0
	ds_read_b128 v[220:223], v77
	v_fma_f32 v2, -v10, v211, v2
	v_readlane_b32 s0, v246, 16
	v_mov_b32_e32 v78, s36
	s_waitcnt lgkmcnt(0)
	v_fma_f32 v2, -v11, v220, v2
	v_fma_f32 v2, -v12, v221, v2
	v_fma_f32 v2, -v13, v222, v2
	v_mov_b32_e32 v77, s0
	ds_read_b128 v[188:191], v77
	v_fma_f32 v2, -v14, v223, v2
	v_readlane_b32 s0, v246, 17
	s_waitcnt lgkmcnt(0)
	v_fma_f32 v2, -v15, v188, v2
	v_fma_f32 v2, -v16, v189, v2
	v_fma_f32 v2, -v17, v190, v2
	v_mov_b32_e32 v77, s0
	ds_read_b128 v[192:195], v77
	v_fma_f32 v2, -v18, v191, v2
	v_readlane_b32 s0, v246, 18
	s_waitcnt lgkmcnt(0)
	v_fma_f32 v2, -v19, v192, v2
	v_fma_f32 v2, -v20, v193, v2
	v_fma_f32 v2, -v21, v194, v2
	v_mov_b32_e32 v77, s0
	ds_read_b128 v[200:203], v77
	v_fma_f32 v2, -v22, v195, v2
	v_readlane_b32 s0, v246, 19
	s_waitcnt lgkmcnt(0)
	v_fma_f32 v2, -v23, v200, v2
	v_fma_f32 v2, -v24, v201, v2
	v_fma_f32 v2, -v25, v202, v2
	v_mov_b32_e32 v77, s0
	ds_read_b128 v[216:219], v77
	v_fma_f32 v2, -v26, v203, v2
	v_readlane_b32 s0, v246, 20
	s_waitcnt lgkmcnt(0)
	v_fma_f32 v2, -v27, v216, v2
	v_fma_f32 v2, -v28, v217, v2
	v_fma_f32 v2, -v29, v218, v2
	v_mov_b32_e32 v77, s0
	ds_read_b128 v[212:215], v77
	v_fma_f32 v2, -v30, v219, v2
	v_readlane_b32 s0, v246, 21
	s_waitcnt lgkmcnt(0)
	v_fma_f32 v2, -v31, v212, v2
	v_fma_f32 v2, -v32, v213, v2
	v_fma_f32 v2, -v33, v214, v2
	v_mov_b32_e32 v77, s0
	ds_read_b128 v[180:183], v77
	v_fma_f32 v2, -v34, v215, v2
	v_readlane_b32 s0, v246, 22
	s_waitcnt lgkmcnt(0)
	v_fma_f32 v2, -v35, v180, v2
	v_fma_f32 v2, -v36, v181, v2
	v_fma_f32 v2, -v37, v182, v2
	v_mov_b32_e32 v77, s0
	ds_read_b128 v[160:163], v77
	v_fma_f32 v2, -v38, v183, v2
	v_readlane_b32 s0, v246, 23
	s_waitcnt lgkmcnt(0)
	v_fma_f32 v2, -v39, v160, v2
	v_fma_f32 v2, -v40, v161, v2
	v_fma_f32 v2, -v41, v162, v2
	v_mov_b32_e32 v77, s0
	ds_read_b128 v[184:187], v77
	v_fma_f32 v2, -v44, v163, v2
	v_readlane_b32 s0, v246, 24
	s_waitcnt lgkmcnt(0)
	v_fma_f32 v2, -v45, v184, v2
	v_fma_f32 v2, -v46, v185, v2
	v_fma_f32 v2, -v47, v186, v2
	v_mov_b32_e32 v77, s0
	ds_read_b128 v[164:167], v77
	v_fma_f32 v2, -v48, v187, v2
	v_readlane_b32 s0, v246, 25
	s_waitcnt lgkmcnt(0)
	v_fma_f32 v2, -v49, v164, v2
	v_fma_f32 v2, -v50, v165, v2
	v_fma_f32 v2, -v51, v166, v2
	v_mov_b32_e32 v77, s0
	ds_read_b128 v[196:199], v77
	v_fma_f32 v2, -v52, v167, v2
	v_mov_b32_e32 v77, s95
	ds_read_b128 v[168:171], v77
	s_movk_i32 s0, 0x7f
	v_cmp_lt_i32_e64 s[0:1], s0, v68
	s_waitcnt lgkmcnt(1)
	v_fma_f32 v2, -v53, v196, v2
	v_fma_f32 v2, -v55, v197, v2
	v_fma_f32 v2, -v56, v198, v2
	v_fma_f32 v2, -v57, v199, v2
	v_mov_b32_e32 v77, s96
	ds_read_b128 v[176:179], v77
	s_waitcnt lgkmcnt(1)
	v_fma_f32 v2, -v58, v168, v2
	v_fma_f32 v2, -v59, v169, v2
	v_fma_f32 v2, -v60, v170, v2
	v_fma_f32 v2, -v61, v171, v2
	v_mov_b32_e32 v77, s97
	ds_read_b128 v[172:175], v77
	ds_read_u16 v208, v80 offset:16592
	ds_read_b128 v[220:223], v78
	s_waitcnt lgkmcnt(3)
	v_fma_f32 v2, -v64, v176, v2
	v_fma_f32 v2, -v70, v177, v2
	v_fma_f32 v2, -v71, v178, v2
	v_fma_f32 v2, -v72, v179, v2
	s_waitcnt lgkmcnt(2)
	v_fma_f32 v2, -v73, v172, v2
	v_fma_f32 v2, -v74, v173, v2
	v_fma_f32 v2, -v75, v174, v2
	v_fma_f32 v77, -v76, v175, v2
	v_bfe_u32 v154, v77, 16, 1
	s_waitcnt lgkmcnt(1)
	v_lshlrev_b32_e32 v2, 16, v208
	s_waitcnt lgkmcnt(0)
	v_mul_f32_e32 v78, v7, v220
	v_fma_f32 v2, v205, v2, -v78
	v_fma_f32 v2, -v8, v221, v2
	v_fma_f32 v2, -v9, v222, v2
	v_mov_b32_e32 v3, s37
	ds_read_b128 v[188:191], v3
	v_fma_f32 v2, -v10, v223, v2
	v_mov_b32_e32 v3, s18
	ds_read_b128 v[192:195], v3
	s_waitcnt lgkmcnt(1)
	v_fma_f32 v2, -v11, v188, v2
	v_fma_f32 v2, -v12, v189, v2
	v_fma_f32 v2, -v13, v190, v2
	v_fma_f32 v2, -v14, v191, v2
	v_mov_b32_e32 v3, s19
	ds_read_b128 v[200:203], v3
	s_waitcnt lgkmcnt(1)
	v_fma_f32 v2, -v15, v192, v2
	v_fma_f32 v2, -v16, v193, v2
	v_fma_f32 v2, -v17, v194, v2
	v_fma_f32 v2, -v18, v195, v2
	v_mov_b32_e32 v3, s42
	ds_read_b128 v[216:219], v3
	s_waitcnt lgkmcnt(1)
	v_fma_f32 v2, -v19, v200, v2
	v_fma_f32 v2, -v20, v201, v2
	v_fma_f32 v2, -v21, v202, v2
	v_fma_f32 v2, -v22, v203, v2
	v_mov_b32_e32 v3, s43
	ds_read_b128 v[212:215], v3
	s_waitcnt lgkmcnt(1)
	v_fma_f32 v2, -v23, v216, v2
	v_fma_f32 v2, -v24, v217, v2
	v_fma_f32 v2, -v25, v218, v2
	v_fma_f32 v2, -v26, v219, v2
	v_mov_b32_e32 v3, s20
	ds_read_b128 v[180:183], v3
	s_waitcnt lgkmcnt(1)
	v_fma_f32 v2, -v27, v212, v2
	v_fma_f32 v2, -v28, v213, v2
	v_fma_f32 v2, -v29, v214, v2
	v_fma_f32 v2, -v30, v215, v2
	v_mov_b32_e32 v3, s21
	ds_read_b128 v[160:163], v3
	s_waitcnt lgkmcnt(1)
	v_fma_f32 v2, -v31, v180, v2
	v_fma_f32 v2, -v32, v181, v2
	v_fma_f32 v2, -v33, v182, v2
	v_fma_f32 v2, -v34, v183, v2
	v_mov_b32_e32 v3, s33
	ds_read_b128 v[184:187], v3
	s_waitcnt lgkmcnt(1)
	v_fma_f32 v2, -v35, v160, v2
	v_fma_f32 v2, -v36, v161, v2
	v_fma_f32 v2, -v37, v162, v2
	v_fma_f32 v2, -v38, v163, v2
	v_mov_b32_e32 v3, s2
	ds_read_b128 v[164:167], v3
	s_waitcnt lgkmcnt(1)
	v_fma_f32 v2, -v39, v184, v2
	v_fma_f32 v2, -v40, v185, v2
	v_fma_f32 v2, -v41, v186, v2
	v_fma_f32 v2, -v44, v187, v2
	v_mov_b32_e32 v3, s53
	ds_read_b128 v[196:199], v3
	s_waitcnt lgkmcnt(1)
	v_fma_f32 v2, -v45, v164, v2
	v_fma_f32 v2, -v46, v165, v2
	v_fma_f32 v2, -v47, v166, v2
	v_fma_f32 v2, -v48, v167, v2
	v_mov_b32_e32 v3, s54
	ds_read_b128 v[168:171], v3
	s_waitcnt lgkmcnt(1)
	v_fma_f32 v2, -v49, v196, v2
	v_fma_f32 v2, -v50, v197, v2
	v_fma_f32 v2, -v51, v198, v2
	v_fma_f32 v2, -v52, v199, v2
	v_mov_b32_e32 v3, s55
	ds_read_b128 v[176:179], v3
	s_waitcnt lgkmcnt(1)
	v_fma_f32 v2, -v53, v168, v2
	v_fma_f32 v2, -v55, v169, v2
	v_fma_f32 v2, -v56, v170, v2
	v_fma_f32 v2, -v57, v171, v2
	v_mov_b32_e32 v3, s56
	ds_read_b128 v[172:175], v3
	s_waitcnt lgkmcnt(1)
	v_fma_f32 v2, -v58, v176, v2
	v_fma_f32 v2, -v59, v177, v2
	v_fma_f32 v2, -v60, v178, v2
	v_fma_f32 v2, -v61, v179, v2
	v_mov_b32_e32 v3, s57
	ds_read_b128 v[208:211], v3
	s_waitcnt lgkmcnt(1)
	v_fma_f32 v2, -v64, v172, v2
	v_fma_f32 v2, -v70, v173, v2
	v_fma_f32 v2, -v71, v174, v2
	v_fma_f32 v2, -v72, v175, v2
	v_mov_b32_e32 v3, s58
	ds_read_b32 v220, v3
	ds_read_u16 v188, v80 offset:16864
	s_waitcnt lgkmcnt(2)
	v_fma_f32 v2, -v73, v208, v2
	v_fma_f32 v2, -v74, v209, v2
	v_fma_f32 v2, -v75, v210, v2
	v_fma_f32 v2, -v76, v211, v2
	s_waitcnt lgkmcnt(1)
	v_fma_f32 v78, -v77, v220, v2
	v_mov_b32_e32 v3, s59
	ds_read_b128 v[192:195], v3
	v_bfe_u32 v155, v78, 16, 1
	s_waitcnt lgkmcnt(1)
	v_lshlrev_b32_e32 v2, 16, v188
	s_waitcnt lgkmcnt(0)
	v_mul_f32_e32 v3, v7, v192
	v_fma_f32 v2, v206, v2, -v3
	v_fma_f32 v2, -v8, v193, v2
	v_fma_f32 v2, -v9, v194, v2
	v_mov_b32_e32 v3, s60
	ds_read_b128 v[200:203], v3
	v_fma_f32 v2, -v10, v195, v2
	v_mov_b32_e32 v3, s61
	ds_read_b128 v[216:219], v3
	s_waitcnt lgkmcnt(1)
	v_fma_f32 v2, -v11, v200, v2
	v_fma_f32 v2, -v12, v201, v2
	v_fma_f32 v2, -v13, v202, v2
	v_fma_f32 v2, -v14, v203, v2
	v_mov_b32_e32 v3, s62
	ds_read_b128 v[212:215], v3
	s_waitcnt lgkmcnt(1)
	v_fma_f32 v2, -v15, v216, v2
	v_fma_f32 v2, -v16, v217, v2
	v_fma_f32 v2, -v17, v218, v2
	v_fma_f32 v2, -v18, v219, v2
	v_mov_b32_e32 v3, s63
	ds_read_b128 v[180:183], v3
	s_waitcnt lgkmcnt(1)
	v_fma_f32 v2, -v19, v212, v2
	v_fma_f32 v2, -v20, v213, v2
	v_fma_f32 v2, -v21, v214, v2
	v_fma_f32 v2, -v22, v215, v2
	v_mov_b32_e32 v3, s64
	ds_read_b128 v[160:163], v3
	s_waitcnt lgkmcnt(1)
	v_fma_f32 v2, -v23, v180, v2
	v_fma_f32 v2, -v24, v181, v2
	v_fma_f32 v2, -v25, v182, v2
	v_fma_f32 v2, -v26, v183, v2
	v_mov_b32_e32 v3, s65
	ds_read_b128 v[184:187], v3
	s_waitcnt lgkmcnt(1)
	v_fma_f32 v2, -v27, v160, v2
	v_fma_f32 v2, -v28, v161, v2
	v_fma_f32 v2, -v29, v162, v2
	v_fma_f32 v2, -v30, v163, v2
	v_mov_b32_e32 v3, s66
	ds_read_b128 v[164:167], v3
	s_waitcnt lgkmcnt(1)
	v_fma_f32 v2, -v31, v184, v2
	v_fma_f32 v2, -v32, v185, v2
	v_fma_f32 v2, -v33, v186, v2
	v_fma_f32 v2, -v34, v187, v2
	v_mov_b32_e32 v3, s67
	ds_read_b128 v[196:199], v3
	s_waitcnt lgkmcnt(1)
	v_fma_f32 v2, -v35, v164, v2
	v_fma_f32 v2, -v36, v165, v2
	v_fma_f32 v2, -v37, v166, v2
	v_fma_f32 v2, -v38, v167, v2
	v_mov_b32_e32 v3, s68
	ds_read_b128 v[168:171], v3
	s_waitcnt lgkmcnt(1)
	v_fma_f32 v2, -v39, v196, v2
	v_fma_f32 v2, -v40, v197, v2
	v_fma_f32 v2, -v41, v198, v2
	v_fma_f32 v2, -v44, v199, v2
	v_mov_b32_e32 v3, s69
	ds_read_b128 v[176:179], v3
	s_waitcnt lgkmcnt(1)
	v_fma_f32 v2, -v45, v168, v2
	v_fma_f32 v2, -v46, v169, v2
	v_fma_f32 v2, -v47, v170, v2
	v_fma_f32 v2, -v48, v171, v2
	v_mov_b32_e32 v3, s70
	ds_read_b128 v[172:175], v3
	s_waitcnt lgkmcnt(1)
	v_fma_f32 v2, -v49, v176, v2
	v_fma_f32 v2, -v50, v177, v2
	v_fma_f32 v2, -v51, v178, v2
	v_fma_f32 v2, -v52, v179, v2
	v_mov_b32_e32 v3, s71
	ds_read_b128 v[208:211], v3
	s_waitcnt lgkmcnt(1)
	v_fma_f32 v2, -v53, v172, v2
	v_fma_f32 v2, -v55, v173, v2
	v_fma_f32 v2, -v56, v174, v2
	v_fma_f32 v2, -v57, v175, v2
	v_mov_b32_e32 v3, s72
	ds_read_b128 v[220:223], v3
	s_waitcnt lgkmcnt(1)
	v_fma_f32 v2, -v58, v208, v2
	v_fma_f32 v2, -v59, v209, v2
	v_fma_f32 v2, -v60, v210, v2
	v_fma_f32 v2, -v61, v211, v2
	v_mov_b32_e32 v3, s73
	ds_read_b128 v[188:191], v3
	s_waitcnt lgkmcnt(1)
	v_fma_f32 v2, -v64, v220, v2
	v_fma_f32 v2, -v70, v221, v2
	v_fma_f32 v2, -v71, v222, v2
	v_fma_f32 v2, -v72, v223, v2
	s_waitcnt lgkmcnt(0)
	v_fma_f32 v2, -v73, v188, v2
	v_fma_f32 v2, -v74, v189, v2
	v_fma_f32 v2, -v75, v190, v2
	v_fma_f32 v4, -v76, v191, v2
	v_mov_b32_e32 v2, s74
	ds_read_b64 v[192:193], v2
	ds_read_u16 v200, v80 offset:17136
	v_bfe_u32 v84, v14, 16, 1
	v_bfe_u32 v85, v15, 16, 1
	s_waitcnt lgkmcnt(1)
	v_fma_f32 v2, -v77, v192, v4
	v_fma_f32 v79, -v78, v193, v2
	v_mov_b32_e32 v3, s75
	ds_read_b128 v[216:219], v3
	v_bfe_u32 v156, v79, 16, 1
	s_waitcnt lgkmcnt(1)
	v_lshlrev_b32_e32 v2, 16, v200
	s_waitcnt lgkmcnt(0)
	v_mul_f32_e32 v3, v7, v216
	v_fma_f32 v2, v207, v2, -v3
	v_fma_f32 v2, -v8, v217, v2
	v_fma_f32 v2, -v9, v218, v2
	v_fma_f32 v80, -v10, v219, v2
	v_mov_b32_e32 v2, s76
	ds_read_b128 v[212:215], v2
	v_bfe_u32 v81, v11, 16, 1
	v_bfe_u32 v82, v12, 16, 1
	v_bfe_u32 v83, v13, 16, 1
	s_waitcnt lgkmcnt(0)
	v_fma_f32 v2, -v11, v212, v80
	v_fma_f32 v2, -v12, v213, v2
	v_fma_f32 v2, -v13, v214, v2
	v_fma_f32 v80, -v14, v215, v2
	v_mov_b32_e32 v2, s77
	ds_read_b128 v[180:183], v2
	v_add3_u32 v11, v11, v81, s52
	v_add3_u32 v12, v12, v82, s52
	v_add3_u32 v13, v13, v83, s52
	v_add3_u32 v14, v14, v84, s52
	s_waitcnt lgkmcnt(0)
	v_fma_f32 v2, -v15, v180, v80
	v_fma_f32 v2, -v16, v181, v2
	v_fma_f32 v2, -v17, v182, v2
	v_fma_f32 v80, -v18, v183, v2
	v_mov_b32_e32 v2, s78
	ds_read_b128 v[160:163], v2
	v_add3_u32 v15, v15, v85, s52
	v_add3_u32 v16, v16, v86, s52
	v_add3_u32 v17, v17, v87, s52
	v_add3_u32 v18, v18, v88, s52
	s_waitcnt lgkmcnt(0)
	v_fma_f32 v2, -v19, v160, v80
	v_fma_f32 v2, -v20, v161, v2
	v_fma_f32 v2, -v21, v162, v2
	v_fma_f32 v80, -v22, v163, v2
	v_mov_b32_e32 v2, s79
	ds_read_b128 v[184:187], v2
	v_add3_u32 v19, v19, v89, s52
	v_add3_u32 v20, v20, v90, s52
	v_add3_u32 v21, v21, v91, s52
	v_add3_u32 v22, v22, v92, s52
	s_waitcnt lgkmcnt(0)
	v_fma_f32 v2, -v23, v184, v80
	v_fma_f32 v2, -v24, v185, v2
	v_fma_f32 v2, -v25, v186, v2
	v_fma_f32 v80, -v26, v187, v2
	v_mov_b32_e32 v2, s80
	ds_read_b128 v[164:167], v2
	v_add3_u32 v23, v23, v93, s52
	v_add3_u32 v24, v24, v94, s52
	v_add3_u32 v25, v25, v95, s52
	v_add3_u32 v26, v26, v96, s52
	s_waitcnt lgkmcnt(0)
	v_fma_f32 v2, -v27, v164, v80
	v_fma_f32 v2, -v28, v165, v2
	v_fma_f32 v2, -v29, v166, v2
	v_fma_f32 v80, -v30, v167, v2
	v_mov_b32_e32 v2, s81
	ds_read_b128 v[196:199], v2
	v_add3_u32 v27, v27, v97, s52
	v_add3_u32 v28, v28, v98, s52
	v_add3_u32 v29, v29, v116, s52
	v_add3_u32 v30, v30, v117, s52
	s_waitcnt lgkmcnt(0)
	v_fma_f32 v2, -v31, v196, v80
	v_fma_f32 v2, -v32, v197, v2
	v_fma_f32 v2, -v33, v198, v2
	v_fma_f32 v80, -v34, v199, v2
	v_mov_b32_e32 v2, s82
	ds_read_b128 v[168:171], v2
	v_add3_u32 v31, v31, v118, s52
	v_add3_u32 v32, v32, v119, s52
	v_add3_u32 v33, v33, v120, s52
	v_add3_u32 v34, v34, v121, s52
	s_waitcnt lgkmcnt(0)
	v_fma_f32 v2, -v35, v168, v80
	v_fma_f32 v2, -v36, v169, v2
	v_fma_f32 v2, -v37, v170, v2
	v_fma_f32 v80, -v38, v171, v2
	v_mov_b32_e32 v2, s83
	ds_read_b128 v[176:179], v2
	v_add3_u32 v35, v35, v122, s52
	v_add3_u32 v36, v36, v123, s52
	v_add3_u32 v37, v37, v124, s52
	v_add3_u32 v38, v38, v125, s52
	s_waitcnt lgkmcnt(0)
	v_fma_f32 v2, -v39, v176, v80
	v_fma_f32 v2, -v40, v177, v2
	v_fma_f32 v2, -v41, v178, v2
	v_fma_f32 v80, -v44, v179, v2
	v_mov_b32_e32 v2, s84
	ds_read_b128 v[172:175], v2
	v_add3_u32 v39, v39, v126, s52
	v_add3_u32 v40, v40, v127, s52
	v_add3_u32 v41, v41, v128, s52
	v_add3_u32 v44, v44, v129, s52
	s_waitcnt lgkmcnt(0)
	v_fma_f32 v2, -v45, v172, v80
	v_fma_f32 v2, -v46, v173, v2
	v_fma_f32 v2, -v47, v174, v2
	v_fma_f32 v80, -v48, v175, v2
	v_mov_b32_e32 v2, s85
	ds_read_b128 v[208:211], v2
	v_add3_u32 v45, v45, v130, s52
	v_add3_u32 v46, v46, v131, s52
	v_add3_u32 v47, v47, v132, s52
	v_add3_u32 v48, v48, v133, s52
	s_waitcnt lgkmcnt(0)
	v_fma_f32 v2, -v49, v208, v80
	v_fma_f32 v2, -v50, v209, v2
	v_fma_f32 v2, -v51, v210, v2
	v_fma_f32 v80, -v52, v211, v2
	v_mov_b32_e32 v2, s86
	ds_read_b128 v[220:223], v2
	v_add3_u32 v49, v49, v134, s52
	v_add3_u32 v50, v50, v135, s52
	v_add3_u32 v51, v51, v136, s52
	v_add3_u32 v52, v52, v137, s52
	s_waitcnt lgkmcnt(0)
	v_fma_f32 v2, -v53, v220, v80
	v_fma_f32 v2, -v55, v221, v2
	v_fma_f32 v2, -v56, v222, v2
	v_fma_f32 v80, -v57, v223, v2
	v_mov_b32_e32 v2, s87
	ds_read_b128 v[188:191], v2
	v_add3_u32 v53, v53, v138, s52
	v_add3_u32 v55, v55, v139, s52
	v_add3_u32 v56, v56, v140, s52
	v_add3_u32 v57, v57, v141, s52
	s_waitcnt lgkmcnt(0)
	v_fma_f32 v2, -v58, v188, v80
	v_fma_f32 v2, -v59, v189, v2
	v_fma_f32 v2, -v60, v190, v2
	v_fma_f32 v80, -v61, v191, v2
	v_mov_b32_e32 v2, s88
	ds_read_b128 v[192:195], v2
	v_add3_u32 v58, v58, v142, s52
	v_add3_u32 v59, v59, v143, s52
	v_add3_u32 v60, v60, v144, s52
	v_add3_u32 v61, v61, v145, s52
	s_waitcnt lgkmcnt(0)
	v_fma_f32 v2, -v64, v192, v80
	v_fma_f32 v2, -v70, v193, v2
	v_fma_f32 v2, -v71, v194, v2
	v_fma_f32 v80, -v72, v195, v2
	v_mov_b32_e32 v2, s89
	ds_read_b128 v[200:203], v2
	v_add3_u32 v64, v64, v146, s52
	v_add3_u32 v70, v70, v147, s52
	v_add3_u32 v71, v71, v148, s52
	v_add3_u32 v72, v72, v149, s52
	s_waitcnt lgkmcnt(0)
	v_fma_f32 v2, -v73, v200, v80
	v_fma_f32 v2, -v74, v201, v2
	v_fma_f32 v2, -v75, v202, v2
	v_fma_f32 v5, -v76, v203, v2
	v_mov_b32_e32 v2, s90
	ds_read_b96 v[204:206], v2
	v_bfe_u32 v80, v10, 16, 1
	v_add3_u32 v10, v10, v80, s52
	v_add3_u32 v73, v73, v150, s52
	v_add3_u32 v74, v74, v151, s52
	s_waitcnt lgkmcnt(0)
	v_fma_f32 v2, -v77, v204, v5
	v_fma_f32 v2, -v78, v205, v2
	v_fma_f32 v2, -v79, v206, v2
	v_bfe_u32 v3, v7, 16, 1
	v_bfe_u32 v4, v8, 16, 1
	v_bfe_u32 v5, v9, 16, 1
	v_bfe_u32 v157, v2, 16, 1
	v_add3_u32 v7, v7, v3, s52
	v_add3_u32 v8, v8, v4, s52
	v_add3_u32 v9, v9, v5, s52
	v_add3_u32 v75, v75, v152, s52
	v_add3_u32 v76, v76, v153, s52
	v_add3_u32 v77, v77, v154, s52
	v_add3_u32 v78, v78, v155, s52
	v_add3_u32 v79, v79, v156, s52
	v_add3_u32 v80, v2, v157, s52
	s_barrier
	s_and_saveexec_b64 s[4:5], s[0:1]
	s_cbranch_execz .LBB0_362
	ds_write_b16_d16_hi v6, v7 offset:34560
	ds_write_b16_d16_hi v6, v8 offset:34832
	ds_write_b16_d16_hi v6, v9 offset:35104
	ds_write_b16_d16_hi v6, v10 offset:35376
	ds_write_b16_d16_hi v6, v11 offset:35648
	ds_write_b16_d16_hi v6, v12 offset:35920
	ds_write_b16_d16_hi v6, v13 offset:36192
	ds_write_b16_d16_hi v6, v14 offset:36464
	ds_write_b16_d16_hi v6, v15 offset:36736
	ds_write_b16_d16_hi v6, v16 offset:37008
	ds_write_b16_d16_hi v6, v17 offset:37280
	ds_write_b16_d16_hi v6, v18 offset:37552
	ds_write_b16_d16_hi v6, v19 offset:37824
	ds_write_b16_d16_hi v6, v20 offset:38096
	ds_write_b16_d16_hi v6, v21 offset:38368
	ds_write_b16_d16_hi v6, v22 offset:38640
	ds_write_b16_d16_hi v6, v23 offset:38912
	ds_write_b16_d16_hi v6, v24 offset:39184
	ds_write_b16_d16_hi v6, v25 offset:39456
	ds_write_b16_d16_hi v6, v26 offset:39728
	ds_write_b16_d16_hi v6, v27 offset:40000
	ds_write_b16_d16_hi v6, v28 offset:40272
	ds_write_b16_d16_hi v6, v29 offset:40544
	ds_write_b16_d16_hi v6, v30 offset:40816
	ds_write_b16_d16_hi v6, v31 offset:41088
	ds_write_b16_d16_hi v6, v32 offset:41360
	ds_write_b16_d16_hi v6, v33 offset:41632
	ds_write_b16_d16_hi v6, v34 offset:41904
	ds_write_b16_d16_hi v6, v35 offset:42176
	ds_write_b16_d16_hi v6, v36 offset:42448
	ds_write_b16_d16_hi v6, v37 offset:42720
	ds_write_b16_d16_hi v6, v38 offset:42992
	ds_write_b16_d16_hi v6, v39 offset:43264
	ds_write_b16_d16_hi v6, v40 offset:43536
	ds_write_b16_d16_hi v6, v41 offset:43808
	ds_write_b16_d16_hi v6, v44 offset:44080
	ds_write_b16_d16_hi v6, v45 offset:44352
	ds_write_b16_d16_hi v6, v46 offset:44624
	ds_write_b16_d16_hi v6, v47 offset:44896
	ds_write_b16_d16_hi v6, v48 offset:45168
	ds_write_b16_d16_hi v6, v49 offset:45440
	ds_write_b16_d16_hi v6, v50 offset:45712
	ds_write_b16_d16_hi v6, v51 offset:45984
	ds_write_b16_d16_hi v6, v52 offset:46256
	ds_write_b16_d16_hi v6, v53 offset:46528
	ds_write_b16_d16_hi v6, v55 offset:46800
	ds_write_b16_d16_hi v6, v56 offset:47072
	ds_write_b16_d16_hi v6, v57 offset:47344
	ds_write_b16_d16_hi v6, v58 offset:47616
	ds_write_b16_d16_hi v6, v59 offset:47888
	ds_write_b16_d16_hi v6, v60 offset:48160
	ds_write_b16_d16_hi v6, v61 offset:48432
	ds_write_b16_d16_hi v6, v64 offset:48704
	ds_write_b16_d16_hi v6, v70 offset:48976
	ds_write_b16_d16_hi v6, v71 offset:49248
	ds_write_b16_d16_hi v6, v72 offset:49520
	ds_write_b16_d16_hi v6, v73 offset:49792
	ds_write_b16_d16_hi v6, v74 offset:50064
	ds_write_b16_d16_hi v6, v75 offset:50336
	ds_write_b16_d16_hi v6, v76 offset:50608
	ds_write_b16_d16_hi v6, v77 offset:50880
	ds_write_b16_d16_hi v6, v78 offset:51152
	ds_write_b16_d16_hi v6, v79 offset:51424
	ds_write_b16_d16_hi v6, v80 offset:51696

.LBB0_487:
	s_and_b64 vcc, exec, s[0:1]
	s_cbranch_vccz .LBB0_397
	v_mov_b32_e32 v76, v198
	v_mov_b64_e32 v[4:5], s[16:17]
	flat_load_dwordx2 v[100:101], v[4:5]
	s_lshl_b32 s4, s75, 6
	s_and_b32 s0, s75, 1
	s_ashr_i32 s1, s75, 3
	s_and_b32 s4, s4, 0xffffff80
	v_add_u32_e32 v78, 0x100, v76
	v_add_u32_e32 v84, 0x200, v76
	v_add_u32_e32 v86, 0x300, v76
	v_add_u32_e32 v88, 0x400, v76
	v_add_u32_e32 v90, 0x500, v76
	v_add_u32_e32 v92, 0x600, v76
	v_add_u32_e32 v94, 0x700, v76
	s_mul_hi_i32 s7, s1, 0x3800000
	s_mul_i32 s8, s1, 0x3800000
	s_lshl_b32 s9, s0, 6
	s_lshl_b32 s18, s0, 13
	v_ashrrev_i32_e32 v77, 31, v76
	v_ashrrev_i32_e32 v79, 31, v78
	v_ashrrev_i32_e32 v85, 31, v84
	v_ashrrev_i32_e32 v87, 31, v86
	v_ashrrev_i32_e32 v89, 31, v88
	v_ashrrev_i32_e32 v91, 31, v90
	v_ashrrev_i32_e32 v93, 31, v92
	v_ashrrev_i32_e32 v95, 31, v94
	v_lshlrev_b64 v[96:97], 4, v[76:77]
	v_lshlrev_b64 v[98:99], 4, v[78:79]
	v_lshlrev_b64 v[110:111], 4, v[84:85]
	v_lshlrev_b64 v[108:109], 4, v[86:87]
	v_lshlrev_b64 v[106:107], 4, v[88:89]
	v_lshlrev_b64 v[104:105], 4, v[90:91]
	v_lshlrev_b64 v[122:123], 4, v[92:93]
	v_lshlrev_b64 v[120:121], 4, v[94:95]
	s_lshl_b32 s5, s75, 7
	s_and_b32 s10, s5, 0x300
	s_ashr_i32 s5, s4, 31
	v_and_b32_e32 v79, 63, v76
	v_bfe_u32 v87, v76, 4, 2
	v_ashrrev_i32_e32 v77, 6, v76
	s_mul_i32 s52, s4, 0x12000
	v_lshlrev_b32_e32 v78, 4, v78
	v_lshlrev_b32_e32 v89, 4, v90
	v_lshlrev_b32_e32 v90, 4, v92
	v_lshl_add_u32 v2, v79, 4, 0
	v_lshlrev_b32_e32 v92, 3, v79
	v_mul_hi_u32_u24_e32 v79, 0x7000, v87
	v_mul_u32_u24_e32 v87, 0x7000, v87
	v_and_b32_e32 v85, 15, v76
	s_mul_hi_i32 s11, s4, 0x12000
	v_lshlrev_b32_e32 v1, 4, v76
	v_lshl_add_u32 v76, v77, 4, s9
	v_add_u32_e32 v124, 0, v78
	v_or_b32_e32 v79, s7, v79
	v_or_b32_e32 v78, s8, v87
	v_mad_i64_i32 v[102:103], s[8:9], s4, v210, v[96:97]
	v_lshl_add_u32 v93, v77, 11, 0
	v_ashrrev_i32_e32 v77, 31, v76
	v_or_b32_e32 v78, s10, v78
	v_mov_b32_e32 v4, 0
	v_lshlrev_b32_e32 v84, 4, v84
	v_lshlrev_b32_e32 v86, 4, v86
	v_lshlrev_b32_e32 v88, 4, v88
	v_lshlrev_b32_e32 v91, 4, v94
	v_lshl_add_u64 v[114:115], v[76:77], 1, v[78:79]
	s_movk_i32 s6, 0x7f
	v_mov_b32_e32 v5, v4
	v_mov_b32_e32 v6, v4
	v_mov_b32_e32 v7, v4
	v_mov_b32_e32 v16, v4
	v_mov_b32_e32 v17, v4
	v_mov_b32_e32 v18, v4
	v_mov_b32_e32 v19, v4
	v_add_u32_e32 v1, 0, v1
	v_add_u32_e32 v125, 0, v84
	v_add_u32_e32 v126, 0, v86
	v_add_u32_e32 v127, 0, v88
	v_add_u32_e32 v128, 0, v89
	v_add_u32_e32 v129, 0, v90
	v_add_u32_e32 v130, 0, v91
	v_add_u32_e32 v131, v93, v92
	s_waitcnt vmcnt(0) lgkmcnt(0)
	v_readfirstlane_b32 s86, v100
	v_readfirstlane_b32 s87, v101
	v_mad_i64_i32 v[8:9], s[0:1], s4, v210, v[100:101]
	v_lshl_add_u64 v[10:11], v[8:9], 0, s[34:35]
	v_lshl_add_u64 v[8:9], v[8:9], 0, s[44:45]
	v_lshl_add_u64 v[12:13], v[10:11], 0, v[96:97]
	v_lshl_add_u64 v[14:15], v[10:11], 0, v[98:99]
	v_lshl_add_u64 v[20:21], v[10:11], 0, v[110:111]
	v_lshl_add_u64 v[24:25], v[10:11], 0, v[108:109]
	v_lshl_add_u64 v[28:29], v[10:11], 0, v[106:107]
	v_lshl_add_u64 v[32:33], v[10:11], 0, v[104:105]
	v_lshl_add_u64 v[36:37], v[10:11], 0, v[122:123]
	v_lshl_add_u64 v[40:41], v[10:11], 0, v[120:121]
	v_lshl_add_u64 v[30:31], v[8:9], 0, v[96:97]
	v_lshl_add_u64 v[34:35], v[8:9], 0, v[98:99]
	v_lshl_add_u64 v[38:39], v[8:9], 0, v[110:111]
	v_lshl_add_u64 v[42:43], v[8:9], 0, v[108:109]
	v_lshl_add_u64 v[44:45], v[8:9], 0, v[106:107]
	v_lshl_add_u64 v[72:73], v[10:11], 0, s[18:19]
	v_lshl_add_u64 v[46:47], v[8:9], 0, v[104:105]
	global_load_dwordx4 v[8:11], v[12:13], off
	s_nop 0
	global_load_dwordx4 v[12:15], v[14:15], off
	s_nop 0
	global_load_dwordx4 v[20:23], v[20:21], off
	s_nop 0
	global_load_dwordx4 v[24:27], v[24:25], off
	s_nop 0
	global_load_dwordx4 v[48:51], v[30:31], off
	global_load_dwordx4 v[52:55], v[34:35], off
	s_nop 0
	global_load_dwordx4 v[28:31], v[28:29], off
	s_nop 0
	global_load_dwordx4 v[32:35], v[32:33], off
	s_nop 0
	global_load_dwordx4 v[56:59], v[38:39], off
	global_load_dwordx4 v[60:63], v[42:43], off
	s_nop 0
	global_load_dwordx4 v[36:39], v[36:37], off
	s_nop 0
	global_load_dwordx4 v[40:43], v[40:41], off
	s_nop 0
	global_load_dwordx4 v[64:67], v[44:45], off
	global_load_dwordx4 v[68:71], v[46:47], off
	v_lshl_add_u64 v[44:45], v[72:73], 0, s[46:47]
	v_lshl_add_u64 v[46:47], v[44:45], 0, v[96:97]
	v_lshl_add_u64 v[44:45], v[44:45], 0, v[98:99]
	global_load_dwordx4 v[72:75], v[46:47], off
	global_load_dwordx4 v[80:83], v[44:45], off
	s_lshl_b64 s[0:1], s[4:5], 2
	s_add_u32 s0, s0, 0x2ce00000
	s_addc_u32 s1, s1, 0
	s_or_b32 s7, s52, s18
	v_mad_i64_i32 v[104:105], s[8:9], s4, v210, v[104:105]
	v_mad_i64_i32 v[106:107], s[8:9], s4, v210, v[106:107]
	v_mad_i64_i32 v[108:109], s[8:9], s4, v210, v[108:109]
	v_mad_i64_i32 v[110:111], s[8:9], s4, v210, v[110:111]
	v_mad_i64_i32 v[112:113], s[4:5], s4, v210, v[98:99]
	s_add_u32 s4, s7, 0x2e020000
	s_addc_u32 s5, s11, 0
	v_lshl_add_u64 v[116:117], s[4:5], 0, v[98:99]
	v_lshl_add_u64 v[118:119], s[4:5], 0, v[96:97]
	s_add_u32 s4, s52, 0x2e012000
	s_addc_u32 s5, s11, 0
	v_mov_b32_e32 v44, v4
	v_mov_b32_e32 v45, v4
	v_mov_b32_e32 v46, v4
	v_mov_b32_e32 v47, v4
	v_lshl_or_b32 v114, v85, 1, v114
	v_lshl_add_u64 v[120:121], s[4:5], 0, v[120:121]
	v_lshl_add_u64 v[122:123], s[4:5], 0, v[122:123]
	v_mov_b32_e32 v76, v4
	v_mov_b32_e32 v77, v4
	v_mov_b32_e32 v78, v4
	v_mov_b32_e32 v79, v4
	v_mov_b32_e32 v84, v4
	v_mov_b32_e32 v85, v4
	v_mov_b32_e32 v86, v4
	v_mov_b32_e32 v87, v4
	v_mov_b32_e32 v88, v4
	v_mov_b32_e32 v89, v4
	v_mov_b32_e32 v90, v4
	v_mov_b32_e32 v91, v4
	v_mov_b32_e32 v92, v4
	v_mov_b32_e32 v93, v4
	v_mov_b32_e32 v94, v4
	v_mov_b32_e32 v95, v4
	v_mov_b32_e32 v96, v4
	v_mov_b32_e32 v97, v4
	v_mov_b32_e32 v98, v4
	v_mov_b32_e32 v99, v4
	s_waitcnt vmcnt(15)
	ds_write_b128 v1, v[8:11]
	s_waitcnt vmcnt(11)
	ds_write_b128 v1, v[48:51] offset:32768
	ds_write_b128 v124, v[12:15]
	s_waitcnt vmcnt(10)
	ds_write_b128 v124, v[52:55] offset:32768
	ds_write_b128 v125, v[20:23]
	s_waitcnt vmcnt(7)
	ds_write_b128 v125, v[56:59] offset:32768
	ds_write_b128 v126, v[24:27]
	s_waitcnt vmcnt(6)
	ds_write_b128 v126, v[60:63] offset:32768
	ds_write_b128 v127, v[28:31]
	s_waitcnt vmcnt(3)
	ds_write_b128 v127, v[64:67] offset:32768
	ds_write_b128 v128, v[32:35]
	s_waitcnt vmcnt(2)
	ds_write_b128 v128, v[68:71] offset:32768
	ds_write_b128 v129, v[36:39]
	ds_write_b128 v130, v[40:43]
	s_waitcnt vmcnt(1)
	ds_write_b128 v129, v[72:75] offset:32768
	s_waitcnt vmcnt(0)
	ds_write_b128 v130, v[80:83] offset:32768
	s_waitcnt lgkmcnt(0)
	s_barrier
	s_branch .LBB0_490

.LBB0_490:
	v_lshl_add_u64 v[196:197], v[100:101], 0, s[0:1]
	global_load_dword v196, v[196:197], off
	s_cmp_lg_u32 s6, 0
	s_cselect_b64 s[4:5], -1, 0
	s_cmp_eq_u32 s6, 0
	s_cbranch_scc1 .LBB0_492
	v_lshl_add_u64 v[48:49], v[100:101], 0, v[102:103]
	v_add_co_u32_e32 v8, vcc, 0x2e012000, v48
	v_lshl_add_u64 v[50:51], v[100:101], 0, v[112:113]
	s_nop 0
	v_addc_co_u32_e32 v9, vcc, 0, v49, vcc
	v_add_co_u32_e32 v12, vcc, 0x2e012000, v50
	v_lshl_add_u64 v[56:57], v[100:101], 0, v[110:111]
	s_nop 0
	v_addc_co_u32_e32 v13, vcc, 0, v51, vcc
	v_add_co_u32_e32 v20, vcc, 0x2e012000, v56
	v_lshl_add_u64 v[58:59], v[100:101], 0, v[108:109]
	s_nop 0
	v_addc_co_u32_e32 v21, vcc, 0, v57, vcc
	v_add_co_u32_e32 v24, vcc, 0x2e012000, v58
	v_lshl_add_u64 v[64:65], v[100:101], 0, v[106:107]
	s_nop 0
	v_addc_co_u32_e32 v25, vcc, 0, v59, vcc
	v_add_co_u32_e32 v28, vcc, 0x2e012000, v64
	v_lshl_add_u64 v[66:67], v[100:101], 0, v[104:105]
	s_nop 0
	v_addc_co_u32_e32 v29, vcc, 0, v65, vcc
	v_add_co_u32_e32 v32, vcc, 0x2e012000, v66
	v_lshl_add_u64 v[36:37], v[100:101], 0, v[122:123]
	s_nop 0
	v_addc_co_u32_e32 v33, vcc, 0, v67, vcc
	v_add_co_u32_e32 v48, vcc, s42, v48
	v_lshl_add_u64 v[40:41], v[100:101], 0, v[120:121]
	s_nop 0
	v_addc_co_u32_e32 v49, vcc, 0, v49, vcc
	v_add_co_u32_e32 v52, vcc, s42, v50
	v_lshl_add_u64 v[72:73], v[100:101], 0, v[118:119]
	s_nop 0
	v_addc_co_u32_e32 v53, vcc, 0, v51, vcc
	v_add_co_u32_e32 v56, vcc, s42, v56
	v_lshl_add_u64 v[80:81], v[100:101], 0, v[116:117]
	s_nop 0
	v_addc_co_u32_e32 v57, vcc, 0, v57, vcc
	v_add_co_u32_e32 v60, vcc, s42, v58
	global_load_dwordx4 v[8:11], v[8:9], off
	s_nop 0
	global_load_dwordx4 v[12:15], v[12:13], off
	v_addc_co_u32_e32 v61, vcc, 0, v59, vcc
	v_add_co_u32_e32 v64, vcc, s42, v64
	global_load_dwordx4 v[20:23], v[20:21], off
	s_nop 0
	global_load_dwordx4 v[24:27], v[24:25], off
	v_addc_co_u32_e32 v65, vcc, 0, v65, vcc
	v_add_co_u32_e32 v68, vcc, s42, v66
	global_load_dwordx4 v[28:31], v[28:29], off
	s_nop 0
	global_load_dwordx4 v[32:35], v[32:33], off
	v_addc_co_u32_e32 v69, vcc, 0, v67, vcc
	global_load_dwordx4 v[36:39], v[36:37], off
	s_nop 0
	global_load_dwordx4 v[40:43], v[40:41], off
	s_nop 0
	global_load_dwordx4 v[48:51], v[48:49], off
	s_nop 0
	global_load_dwordx4 v[52:55], v[52:53], off
	s_nop 0
	global_load_dwordx4 v[56:59], v[56:57], off
	s_nop 0
	global_load_dwordx4 v[60:63], v[60:61], off
	s_nop 0
	global_load_dwordx4 v[64:67], v[64:65], off
	s_nop 0
	global_load_dwordx4 v[68:71], v[68:69], off
	s_nop 0
	global_load_dwordx4 v[72:75], v[72:73], off
	s_nop 0
	global_load_dwordx4 v[80:83], v[80:81], off
.LBB0_492:
	ds_read_b128 v[212:215], v2
	ds_read_b128 v[216:219], v2 offset:4096
	ds_read_b128 v[220:223], v2 offset:8192
	ds_read_b128 v[224:227], v2 offset:12288
	ds_read_b128 v[228:231], v2 offset:1024
	ds_read2st64_b64 v[188:191], v131 offset0:112 offset1:113
	ds_read2st64_b64 v[192:195], v131 offset0:114 offset1:115
	v_cvt_pk_bf16_f32 v132, v16, v17
	v_cvt_pk_bf16_f32 v133, v18, v19
	v_cvt_pk_bf16_f32 v134, v4, v5
	v_cvt_pk_bf16_f32 v135, v6, v7
	v_cvt_pk_bf16_f32 v136, v44, v45
	v_cvt_pk_bf16_f32 v137, v46, v47
	v_cvt_pk_bf16_f32 v138, v76, v77
	v_cvt_pk_bf16_f32 v139, v78, v79
	v_cvt_pk_bf16_f32 v140, v84, v85
	v_cvt_pk_bf16_f32 v141, v86, v87
	v_cvt_pk_bf16_f32 v142, v88, v89
	v_cvt_pk_bf16_f32 v143, v90, v91
	v_cvt_pk_bf16_f32 v144, v92, v93
	v_cvt_pk_bf16_f32 v145, v94, v95
	v_cvt_pk_bf16_f32 v146, v96, v97
	v_cvt_pk_bf16_f32 v147, v98, v99
	v_add_u32_e32 v197, 0x4000c00, v114
	s_waitcnt lgkmcnt(6)
	v_mfma_f32_16x16x32_bf16 v[156:159], v[212:215], v[132:135], 0
	ds_read_b128 v[232:235], v2 offset:5120
	s_waitcnt lgkmcnt(6)
	v_mfma_f32_16x16x32_bf16 v[160:163], v[216:219], v[132:135], 0
	ds_read_b128 v[236:239], v2 offset:9216
	s_waitcnt lgkmcnt(6)
	v_mfma_f32_16x16x32_bf16 v[164:167], v[220:223], v[132:135], 0
	ds_read_b128 v[212:215], v2 offset:13312
	s_waitcnt lgkmcnt(6)
	v_mfma_f32_16x16x32_bf16 v[168:171], v[224:227], v[132:135], 0
	ds_read_b128 v[216:219], v2 offset:2048
	s_waitcnt lgkmcnt(6)
	v_mfma_f32_16x16x32_bf16 v[156:159], v[228:231], v[136:139], v[156:159]
	ds_read_b128 v[220:223], v2 offset:6144
	s_waitcnt lgkmcnt(4)
	v_mfma_f32_16x16x32_bf16 v[160:163], v[232:235], v[136:139], v[160:163]
	ds_read_b128 v[224:227], v2 offset:10240
	s_waitcnt lgkmcnt(4)
	v_mfma_f32_16x16x32_bf16 v[164:167], v[236:239], v[136:139], v[164:167]
	ds_read_b128 v[228:231], v2 offset:14336
	s_waitcnt lgkmcnt(4)
	v_mfma_f32_16x16x32_bf16 v[168:171], v[212:215], v[136:139], v[168:171]
	ds_read_b128 v[232:235], v2 offset:3072
	s_waitcnt lgkmcnt(4)
	v_mfma_f32_16x16x32_bf16 v[156:159], v[216:219], v[140:143], v[156:159]
	ds_read_b128 v[236:239], v2 offset:7168
	s_waitcnt lgkmcnt(4)
	v_mfma_f32_16x16x32_bf16 v[160:163], v[220:223], v[140:143], v[160:163]
	ds_read_b128 v[212:215], v2 offset:11264
	s_waitcnt lgkmcnt(4)
	v_mfma_f32_16x16x32_bf16 v[164:167], v[224:227], v[140:143], v[164:167]
	ds_read_b128 v[216:219], v2 offset:15360
	s_waitcnt lgkmcnt(4)
	v_mfma_f32_16x16x32_bf16 v[168:171], v[228:231], v[140:143], v[168:171]
	ds_read_b128 v[220:223], v2 offset:16384
	s_waitcnt lgkmcnt(4)
	v_mfma_f32_16x16x32_bf16 v[156:159], v[232:235], v[144:147], v[156:159]
	ds_read_b128 v[224:227], v2 offset:20480
	s_waitcnt lgkmcnt(4)
	v_mfma_f32_16x16x32_bf16 v[160:163], v[236:239], v[144:147], v[160:163]
	ds_read_b128 v[228:231], v2 offset:24576
	s_waitcnt lgkmcnt(4)
	v_mfma_f32_16x16x32_bf16 v[164:167], v[212:215], v[144:147], v[164:167]
	ds_read_b128 v[232:235], v2 offset:28672
	s_waitcnt lgkmcnt(4)
	v_mfma_f32_16x16x32_bf16 v[168:171], v[216:219], v[144:147], v[168:171]
	ds_read_b128 v[236:239], v2 offset:17408
	s_waitcnt lgkmcnt(4)
	v_mfma_f32_16x16x32_bf16 v[172:175], v[220:223], v[132:135], 0
	ds_read_b128 v[212:215], v2 offset:21504
	s_cmp_eq_u32 s6, 0
	s_cbranch_scc1 .Lscan_w0
	s_waitcnt vmcnt(16)
	s_branch .Lscan_w1

.Lscan_w1:
	v_pk_mul_f32 v[16:17], v[16:17], v[196:197] op_sel_hi:[1,0]
	v_pk_mul_f32 v[18:19], v[18:19], v[196:197] op_sel_hi:[1,0]
	s_waitcnt lgkmcnt(4)
	v_mfma_f32_16x16x32_bf16 v[176:179], v[224:227], v[132:135], 0
	ds_read_b128 v[216:219], v2 offset:25600
	v_pk_mul_f32 v[4:5], v[4:5], v[196:197] op_sel_hi:[1,0]
	v_pk_mul_f32 v[6:7], v[6:7], v[196:197] op_sel_hi:[1,0]
	s_waitcnt lgkmcnt(4)
	v_mfma_f32_16x16x32_bf16 v[180:183], v[228:231], v[132:135], 0
	ds_read_b128 v[220:223], v2 offset:29696
	v_pk_mul_f32 v[44:45], v[44:45], v[196:197] op_sel_hi:[1,0]
	v_pk_mul_f32 v[46:47], v[46:47], v[196:197] op_sel_hi:[1,0]
	v_lshlrev_b32_e32 v240, 16, v188
	v_and_b32_e32 v241, 0xffff0000, v188
	v_lshlrev_b32_e32 v242, 16, v189
	v_and_b32_e32 v243, 0xffff0000, v189
	s_waitcnt lgkmcnt(4)
	v_mfma_f32_16x16x32_bf16 v[184:187], v[232:235], v[132:135], 0
	ds_read_b128 v[224:227], v2 offset:18432
	v_pk_mul_f32 v[76:77], v[76:77], v[196:197] op_sel_hi:[1,0]
	v_pk_mul_f32 v[78:79], v[78:79], v[196:197] op_sel_hi:[1,0]
	v_sub_f32_e32 v156, v240, v156
	v_sub_f32_e32 v157, v241, v157
	v_sub_f32_e32 v158, v242, v158
	v_sub_f32_e32 v159, v243, v159
	s_waitcnt lgkmcnt(4)
	v_mfma_f32_16x16x32_bf16 v[172:175], v[236:239], v[136:139], v[172:175]
	ds_read_b128 v[228:231], v2 offset:22528
	v_pk_mul_f32 v[84:85], v[84:85], v[196:197] op_sel_hi:[1,0]
	v_pk_mul_f32 v[86:87], v[86:87], v[196:197] op_sel_hi:[1,0]
	v_lshlrev_b32_e32 v240, 16, v190
	v_and_b32_e32 v241, 0xffff0000, v190
	v_lshlrev_b32_e32 v242, 16, v191
	v_and_b32_e32 v243, 0xffff0000, v191
	s_waitcnt lgkmcnt(4)
	v_mfma_f32_16x16x32_bf16 v[176:179], v[212:215], v[136:139], v[176:179]
	ds_read_b128 v[232:235], v2 offset:26624
	v_pk_mul_f32 v[88:89], v[88:89], v[196:197] op_sel_hi:[1,0]
	v_pk_mul_f32 v[90:91], v[90:91], v[196:197] op_sel_hi:[1,0]
	v_sub_f32_e32 v160, v240, v160
	v_sub_f32_e32 v161, v241, v161
	v_sub_f32_e32 v162, v242, v162
	v_sub_f32_e32 v163, v243, v163
	s_waitcnt lgkmcnt(4)
	v_mfma_f32_16x16x32_bf16 v[180:183], v[216:219], v[136:139], v[180:183]
	ds_read_b128 v[236:239], v2 offset:30720
	v_pk_mul_f32 v[92:93], v[92:93], v[196:197] op_sel_hi:[1,0]
	v_pk_mul_f32 v[94:95], v[94:95], v[196:197] op_sel_hi:[1,0]
	v_lshlrev_b32_e32 v240, 16, v192
	v_and_b32_e32 v241, 0xffff0000, v192
	v_lshlrev_b32_e32 v242, 16, v193
	v_and_b32_e32 v243, 0xffff0000, v193
	v_cvt_pk_bf16_f32 v148, v156, v157
	v_cvt_pk_bf16_f32 v149, v158, v159
	v_cvt_pk_bf16_f32 v150, v160, v161
	v_cvt_pk_bf16_f32 v151, v162, v163
	s_waitcnt lgkmcnt(4)
	v_mfma_f32_16x16x32_bf16 v[184:187], v[220:223], v[136:139], v[184:187]
	ds_read_b128 v[212:215], v2 offset:19456
	v_pk_mul_f32 v[96:97], v[96:97], v[196:197] op_sel_hi:[1,0]
	v_pk_mul_f32 v[98:99], v[98:99], v[196:197] op_sel_hi:[1,0]
	v_sub_f32_e32 v164, v240, v164
	v_sub_f32_e32 v165, v241, v165
	v_sub_f32_e32 v166, v242, v166
	v_sub_f32_e32 v167, v243, v167
	s_waitcnt lgkmcnt(4)
	v_mfma_f32_16x16x32_bf16 v[172:175], v[224:227], v[140:143], v[172:175]
	ds_read_b128 v[216:219], v2 offset:23552
	v_lshlrev_b32_e32 v240, 16, v194
	v_and_b32_e32 v241, 0xffff0000, v194
	v_lshlrev_b32_e32 v242, 16, v195
	v_and_b32_e32 v243, 0xffff0000, v195
	s_waitcnt lgkmcnt(4)
	v_mfma_f32_16x16x32_bf16 v[176:179], v[228:231], v[140:143], v[176:179]
	ds_read_b128 v[220:223], v2 offset:27648
	v_sub_f32_e32 v168, v240, v168
	v_sub_f32_e32 v169, v241, v169
	v_sub_f32_e32 v170, v242, v170
	v_sub_f32_e32 v171, v243, v171
	s_waitcnt lgkmcnt(4)
	v_mfma_f32_16x16x32_bf16 v[180:183], v[232:235], v[140:143], v[180:183]
	ds_read_b128 v[224:227], v2 offset:31744
	v_cvt_pk_bf16_f32 v152, v164, v165
	v_cvt_pk_bf16_f32 v153, v166, v167
	v_cvt_pk_bf16_f32 v154, v168, v169
	v_cvt_pk_bf16_f32 v155, v170, v171
	s_waitcnt lgkmcnt(4)
	v_mfma_f32_16x16x32_bf16 v[184:187], v[236:239], v[140:143], v[184:187]
	ds_read_b128 v[228:231], v2 offset:49152
	s_waitcnt lgkmcnt(4)
	v_mfma_f32_16x16x32_bf16 v[172:175], v[212:215], v[144:147], v[172:175]
	ds_read_b128 v[232:235], v2 offset:51200
	s_waitcnt lgkmcnt(4)
	v_mfma_f32_16x16x32_bf16 v[176:179], v[216:219], v[144:147], v[176:179]
	ds_read_b128 v[236:239], v2 offset:53248
	s_waitcnt lgkmcnt(4)
	v_mfma_f32_16x16x32_bf16 v[180:183], v[220:223], v[144:147], v[180:183]
	ds_read_b128 v[212:215], v2 offset:55296
	s_waitcnt lgkmcnt(4)
	v_mfma_f32_16x16x32_bf16 v[184:187], v[224:227], v[144:147], v[184:187]
	ds_read_b128 v[216:219], v2 offset:50176
	s_waitcnt lgkmcnt(4)
	v_mfma_f32_16x16x32_bf16 v[172:175], v[228:231], v[148:151], v[172:175]
	ds_read_b128 v[220:223], v2 offset:52224
	s_waitcnt lgkmcnt(4)
	v_mfma_f32_16x16x32_bf16 v[176:179], v[232:235], v[148:151], v[176:179]
	ds_read_b128 v[224:227], v2 offset:54272
	s_waitcnt lgkmcnt(4)
	v_mfma_f32_16x16x32_bf16 v[180:183], v[236:239], v[148:151], v[180:183]
	ds_read_b128 v[228:231], v2 offset:56320
	s_waitcnt lgkmcnt(4)
	v_mfma_f32_16x16x32_bf16 v[184:187], v[212:215], v[148:151], v[184:187]
	ds_read_b128 v[232:235], v2 offset:32768
	s_waitcnt lgkmcnt(4)
	v_mfma_f32_16x16x32_bf16 v[172:175], v[216:219], v[152:155], v[172:175]
	ds_read_b128 v[236:239], v2 offset:34816
	s_waitcnt lgkmcnt(4)
	v_mfma_f32_16x16x32_bf16 v[176:179], v[220:223], v[152:155], v[176:179]
	ds_read_b128 v[212:215], v2 offset:36864
	s_waitcnt lgkmcnt(4)
	v_mfma_f32_16x16x32_bf16 v[180:183], v[224:227], v[152:155], v[180:183]
	ds_read_b128 v[216:219], v2 offset:38912
	s_waitcnt lgkmcnt(4)
	v_mfma_f32_16x16x32_bf16 v[184:187], v[228:231], v[152:155], v[184:187]
	ds_read_b128 v[220:223], v2 offset:40960
	s_waitcnt lgkmcnt(4)
	v_mfma_f32_16x16x32_bf16 v[16:19], v[232:235], v[148:151], v[16:19]
	ds_read_b128 v[224:227], v2 offset:43008
	s_waitcnt lgkmcnt(4)
	v_mfma_f32_16x16x32_bf16 v[4:7], v[236:239], v[148:151], v[4:7]
	ds_read_b128 v[228:231], v2 offset:45056
	v_bfe_u32 v156, v172, 16, 1
	v_add3_u32 v156, v172, v156, s43
	global_store_short_d16_hi v197, v156, s[86:87]
	v_bfe_u32 v157, v173, 16, 1
	v_add3_u32 v157, v173, v157, s43
	v_add_u32_e32 v189, 0x1c00, v197
	global_store_short_d16_hi v189, v157, s[86:87]
	s_waitcnt lgkmcnt(4)
	v_mfma_f32_16x16x32_bf16 v[44:47], v[212:215], v[148:151], v[44:47]
	ds_read_b128 v[232:235], v2 offset:47104
	v_bfe_u32 v158, v174, 16, 1
	v_add3_u32 v158, v174, v158, s43
	v_add_u32_e32 v190, 0x3800, v197
	global_store_short_d16_hi v190, v158, s[86:87]
	v_bfe_u32 v159, v175, 16, 1
	v_add3_u32 v159, v175, v159, s43
	v_add_u32_e32 v191, 0x5400, v197
	global_store_short_d16_hi v191, v159, s[86:87]
	s_waitcnt lgkmcnt(4)
	v_mfma_f32_16x16x32_bf16 v[76:79], v[216:219], v[148:151], v[76:79]
	ds_read_b128 v[236:239], v2 offset:33792
	s_waitcnt lgkmcnt(4)
	v_mfma_f32_16x16x32_bf16 v[84:87], v[220:223], v[148:151], v[84:87]
	ds_read_b128 v[212:215], v2 offset:35840
	v_bfe_u32 v160, v176, 16, 1
	v_add3_u32 v160, v176, v160, s43
	v_add_u32_e32 v192, 0x1c000, v197
	global_store_short_d16_hi v192, v160, s[86:87]
	v_bfe_u32 v161, v177, 16, 1
	v_add3_u32 v161, v177, v161, s43
	v_add_u32_e32 v193, 0x1dc00, v197
	global_store_short_d16_hi v193, v161, s[86:87]
	s_waitcnt lgkmcnt(4)
	v_mfma_f32_16x16x32_bf16 v[88:91], v[224:227], v[148:151], v[88:91]
	ds_read_b128 v[216:219], v2 offset:37888
	v_bfe_u32 v162, v178, 16, 1
	v_add3_u32 v162, v178, v162, s43
	v_add_u32_e32 v194, 0x1f800, v197
	global_store_short_d16_hi v194, v162, s[86:87]
	v_bfe_u32 v163, v179, 16, 1
	v_add3_u32 v163, v179, v163, s43
	v_add_u32_e32 v195, 0x21400, v197
	global_store_short_d16_hi v195, v163, s[86:87]
	s_waitcnt lgkmcnt(4)
	v_mfma_f32_16x16x32_bf16 v[92:95], v[228:231], v[148:151], v[92:95]
	ds_read_b128 v[220:223], v2 offset:39936
	s_waitcnt lgkmcnt(4)
	v_mfma_f32_16x16x32_bf16 v[96:99], v[232:235], v[148:151], v[96:99]
	ds_read_b128 v[224:227], v2 offset:41984
	v_bfe_u32 v156, v180, 16, 1
	v_add3_u32 v156, v180, v156, s43
	v_add_u32_e32 v188, 0x38000, v197
	global_store_short_d16_hi v188, v156, s[86:87]
	v_bfe_u32 v157, v181, 16, 1
	v_add3_u32 v157, v181, v157, s43
	v_add_u32_e32 v189, 0x39c00, v197
	global_store_short_d16_hi v189, v157, s[86:87]
	s_waitcnt lgkmcnt(4)
	v_mfma_f32_16x16x32_bf16 v[16:19], v[236:239], v[152:155], v[16:19]
	ds_read_b128 v[228:231], v2 offset:44032
	v_bfe_u32 v158, v182, 16, 1
	v_add3_u32 v158, v182, v158, s43
	v_add_u32_e32 v190, 0x3b800, v197
	global_store_short_d16_hi v190, v158, s[86:87]
	v_bfe_u32 v159, v183, 16, 1
	v_add3_u32 v159, v183, v159, s43
	v_add_u32_e32 v191, 0x3d400, v197
	global_store_short_d16_hi v191, v159, s[86:87]
	s_waitcnt lgkmcnt(4)
	v_mfma_f32_16x16x32_bf16 v[4:7], v[212:215], v[152:155], v[4:7]
	ds_read_b128 v[232:235], v2 offset:46080
	s_waitcnt lgkmcnt(4)
	v_mfma_f32_16x16x32_bf16 v[44:47], v[216:219], v[152:155], v[44:47]
	ds_read_b128 v[236:239], v2 offset:48128
	v_bfe_u32 v160, v184, 16, 1
	v_add3_u32 v160, v184, v160, s43
	v_add_u32_e32 v192, 0x54000, v197
	global_store_short_d16_hi v192, v160, s[86:87]
	v_bfe_u32 v161, v185, 16, 1
	v_add3_u32 v161, v185, v161, s43
	v_add_u32_e32 v193, 0x55c00, v197
	global_store_short_d16_hi v193, v161, s[86:87]
	s_waitcnt lgkmcnt(4)
	v_mfma_f32_16x16x32_bf16 v[76:79], v[220:223], v[152:155], v[76:79]
	v_bfe_u32 v162, v186, 16, 1
	v_add3_u32 v162, v186, v162, s43
	v_add_u32_e32 v194, 0x57800, v197
	global_store_short_d16_hi v194, v162, s[86:87]
	v_bfe_u32 v163, v187, 16, 1
	v_add3_u32 v163, v187, v163, s43
	v_add_u32_e32 v195, 0x59400, v197
	global_store_short_d16_hi v195, v163, s[86:87]
	s_waitcnt lgkmcnt(3)
	v_mfma_f32_16x16x32_bf16 v[84:87], v[224:227], v[152:155], v[84:87]
	s_waitcnt lgkmcnt(2)
	v_mfma_f32_16x16x32_bf16 v[88:91], v[228:231], v[152:155], v[88:91]
	s_waitcnt lgkmcnt(1)
	v_mfma_f32_16x16x32_bf16 v[92:95], v[232:235], v[152:155], v[92:95]
	s_waitcnt lgkmcnt(0)
	v_mfma_f32_16x16x32_bf16 v[96:99], v[236:239], v[152:155], v[96:99]
	s_andn2_b64 vcc, exec, s[4:5]
	s_waitcnt lgkmcnt(0)
	s_barrier
	s_cbranch_vccnz .LBB0_489
	s_waitcnt vmcnt(16)
	ds_write_b128 v1, v[8:11]
	ds_write_b128 v1, v[48:51] offset:32768
	ds_write_b128 v124, v[12:15]
	ds_write_b128 v124, v[52:55] offset:32768
	ds_write_b128 v125, v[20:23]
	ds_write_b128 v125, v[56:59] offset:32768
	ds_write_b128 v126, v[24:27]
	ds_write_b128 v126, v[60:63] offset:32768
	ds_write_b128 v127, v[28:31]
	ds_write_b128 v127, v[64:67] offset:32768
	ds_write_b128 v128, v[32:35]
	ds_write_b128 v128, v[68:71] offset:32768
	ds_write_b128 v129, v[36:39]
	ds_write_b128 v129, v[72:75] offset:32768
	ds_write_b128 v130, v[40:43]
	ds_write_b128 v130, v[80:83] offset:32768
	s_branch .LBB0_489

.LBB0_563:
	s_and_b32 s101, s50, 0xffffff07
	s_and_b32 s100, s50, 0xc0
	s_lshr_b32 s100, s100, 3
	s_or_b32 s101, s101, s100
	s_and_b32 s100, s50, 56
	s_lshl_b32 s100, s100, 2
	s_or_b32 s101, s101, s100
	s_ashr_i32 s44, s101, 31
	v_mov_b32_e32 v10, v1
	s_lshr_b32 s44, s44, 27
	s_add_i32 s44, s101, s44
	v_lshrrev_b32_e32 v2, 2, v10
	v_and_b32_e32 v2, 12, v2
	s_ashr_i32 s46, s44, 5
	v_lshrrev_b32_e64 v2, v2, s41
	s_andn2_b32 s44, s44, 31
	s_ashr_i32 s47, s46, 31
	v_xor_b32_e32 v2, v2, v10
	v_lshlrev_b32_e32 v3, 8, v10
	s_sub_i32 s44, s101, s44
	s_lshl_b64 s[48:49], s[46:47], 19
	v_and_b32_e32 v3, 0xfffffc00, v3
	v_lshlrev_b32_e32 v2, 3, v2
	s_add_u32 s52, s3, s48
	v_and_or_b32 v2, v2, 24, v3
	v_and_b32_e32 v3, 12, v10
	s_addc_u32 s53, s33, s49
	s_ashr_i32 s45, s44, 31
	v_lshl_add_u32 v138, v10, 4, 0
	v_lshrrev_b32_e64 v11, v3, s42
	v_ashrrev_i32_e32 v3, 31, v2
	s_lshl_b64 s[54:55], s[44:45], 18
	v_lshlrev_b64 v[2:3], 1, v[2:3]
	v_readfirstlane_b32 s45, v138
	v_add_u32_e32 v9, 0x1000, v138
	v_lshl_add_u64 v[4:5], s[52:53], 0, v[2:3]
	s_mov_b32 m0, s45
	v_readfirstlane_b32 s45, v9
	v_add_u32_e32 v9, 0x2000, v138
	v_lshlrev_b32_e32 v8, 6, v10
	global_load_lds_dwordx4 v[4:5], off
	v_lshl_add_u64 v[6:7], v[4:5], 0, s[10:11]
	s_mov_b32 m0, s45
	v_readfirstlane_b32 s45, v9
	v_add_u32_e32 v9, 0x3000, v138
	s_add_u32 s56, s36, s54
	v_and_b32_e32 v139, 0x13c0, v8
	global_load_lds_dwordx4 v[6:7], off
	v_lshl_add_u64 v[6:7], v[4:5], 0, s[12:13]
	s_mov_b32 m0, s45
	v_readfirstlane_b32 s45, v9
	v_and_b32_e32 v140, 0xffffe3c0, v8
	v_add_u32_e32 v8, 0x4000, v138
	s_addc_u32 s57, s37, s55
	global_load_lds_dwordx4 v[6:7], off
	v_lshl_add_u64 v[6:7], v[4:5], 0, s[14:15]
	s_mov_b32 m0, s45
	v_readfirstlane_b32 s45, v8
	v_add_u32_e32 v12, 0x5000, v138
	global_load_lds_dwordx4 v[6:7], off
	v_lshl_add_u64 v[6:7], s[56:57], 0, v[2:3]
	s_mov_b32 m0, s45
	v_readfirstlane_b32 s45, v12
	v_bitop3_b32 v141, v11, 48, v10 bitop3:0x48
	v_add_u32_e32 v10, 0x6000, v138
	global_load_lds_dwordx4 v[6:7], off
	v_lshl_add_u64 v[8:9], v[6:7], 0, s[10:11]
	s_mov_b32 m0, s45
	v_readfirstlane_b32 s45, v10
	v_add_u32_e32 v10, 0x7000, v138
	global_load_lds_dwordx4 v[8:9], off
	v_lshl_add_u64 v[8:9], v[4:5], 0, 64
	s_mov_b32 m0, s45
	v_readfirstlane_b32 s45, v10
	v_add_u32_e32 v10, 0x8000, v138
	global_load_lds_dwordx4 v[8:9], off
	v_lshl_add_u64 v[8:9], v[4:5], 0, s[16:17]
	s_mov_b32 m0, s45
	v_readfirstlane_b32 s45, v10
	global_load_lds_dwordx4 v[8:9], off
	v_lshl_add_u64 v[8:9], v[4:5], 0, s[18:19]
	s_mov_b32 m0, s45
	v_lshl_add_u64 v[4:5], v[4:5], 0, s[20:21]
	global_load_lds_dwordx4 v[8:9], off
	v_add_u32_e32 v8, 0x9000, v138
	s_add_u32 s52, s4, s54
	v_readfirstlane_b32 s45, v8
	v_add_u32_e32 v8, 0xa000, v138
	s_mov_b32 m0, s45
	v_readfirstlane_b32 s45, v8
	global_load_lds_dwordx4 v[4:5], off
	v_lshl_add_u64 v[4:5], v[6:7], 0, 64
	s_mov_b32 m0, s45
	s_addc_u32 s53, s5, s55
	global_load_lds_dwordx4 v[4:5], off
	v_lshl_add_u64 v[4:5], v[6:7], 0, s[16:17]
	v_add_u32_e32 v6, 0xb000, v138
	s_add_u32 s48, s4, s48
	v_readfirstlane_b32 s45, v6
	s_mov_b32 m0, s45
	s_addc_u32 s49, s5, s49
	global_load_lds_dwordx4 v[4:5], off
	v_lshl_add_u64 v[132:133], s[52:53], 0, v[2:3]
	v_lshl_add_u64 v[134:135], s[48:49], 0, v[2:3]
	v_mov_b32_e32 v2, 0
	s_mov_b64 s[48:49], 0
	s_mov_b32 s45, 0
	v_mov_b32_e32 v3, v2
	v_mov_b32_e32 v4, v2
	v_mov_b32_e32 v5, v2
	v_mov_b32_e32 v6, v2
	v_mov_b32_e32 v7, v2
	v_mov_b32_e32 v8, v2
	v_mov_b32_e32 v9, v2
	v_mov_b32_e32 v10, v2
	v_mov_b32_e32 v11, v2
	v_mov_b32_e32 v12, v2
	v_mov_b32_e32 v13, v2
	v_mov_b32_e32 v14, v2
	v_mov_b32_e32 v15, v2
	v_mov_b32_e32 v16, v2
	v_mov_b32_e32 v17, v2
	v_mov_b32_e32 v18, v2
	v_mov_b32_e32 v19, v2
	v_mov_b32_e32 v20, v2
	v_mov_b32_e32 v21, v2
	v_mov_b32_e32 v22, v2
	v_mov_b32_e32 v23, v2
	v_mov_b32_e32 v24, v2
	v_mov_b32_e32 v25, v2
	v_mov_b32_e32 v26, v2
	v_mov_b32_e32 v27, v2
	v_mov_b32_e32 v28, v2
	v_mov_b32_e32 v29, v2
	v_mov_b32_e32 v30, v2
	v_mov_b32_e32 v31, v2
	v_mov_b32_e32 v32, v2
	v_mov_b32_e32 v33, v2
	v_mov_b32_e32 v34, v2
	v_mov_b32_e32 v35, v2
	v_mov_b32_e32 v36, v2
	v_mov_b32_e32 v37, v2
	v_mov_b32_e32 v38, v2
	v_mov_b32_e32 v39, v2
	v_mov_b32_e32 v40, v2
	v_mov_b32_e32 v41, v2
	v_mov_b32_e32 v42, v2
	v_mov_b32_e32 v43, v2
	v_mov_b32_e32 v44, v2
	v_mov_b32_e32 v45, v2
	v_mov_b32_e32 v46, v2
	v_mov_b32_e32 v47, v2
	v_mov_b32_e32 v48, v2
	v_mov_b32_e32 v49, v2
	v_mov_b32_e32 v50, v2
	v_mov_b32_e32 v51, v2
	v_mov_b32_e32 v52, v2
	v_mov_b32_e32 v53, v2
	v_mov_b32_e32 v54, v2
	v_mov_b32_e32 v55, v2
	v_mov_b32_e32 v56, v2
	v_mov_b32_e32 v57, v2
	v_mov_b32_e32 v58, v2
	v_mov_b32_e32 v59, v2
	v_mov_b32_e32 v60, v2
	v_mov_b32_e32 v61, v2
	v_mov_b32_e32 v62, v2
	v_mov_b32_e32 v63, v2
	v_mov_b32_e32 v64, v2
	v_mov_b32_e32 v65, v2
	v_mov_b32_e32 v66, v2
	v_mov_b32_e32 v67, v2
	v_mov_b32_e32 v68, v2
	v_mov_b32_e32 v69, v2
	v_mov_b32_e32 v70, v2
	v_mov_b32_e32 v71, v2
	v_mov_b32_e32 v72, v2
	v_mov_b32_e32 v73, v2
	v_mov_b32_e32 v74, v2
	v_mov_b32_e32 v75, v2
	v_mov_b32_e32 v76, v2
	v_mov_b32_e32 v77, v2
	v_mov_b32_e32 v78, v2
	v_mov_b32_e32 v79, v2
	v_mov_b32_e32 v80, v2
	v_mov_b32_e32 v81, v2
	v_mov_b32_e32 v82, v2
	v_mov_b32_e32 v83, v2
	v_mov_b32_e32 v84, v2
	v_mov_b32_e32 v85, v2
	v_mov_b32_e32 v86, v2
	v_mov_b32_e32 v87, v2
	v_mov_b32_e32 v88, v2
	v_mov_b32_e32 v89, v2
	v_mov_b32_e32 v90, v2
	v_mov_b32_e32 v91, v2
	v_mov_b32_e32 v92, v2
	v_mov_b32_e32 v93, v2
	v_mov_b32_e32 v94, v2
	v_mov_b32_e32 v95, v2
	v_mov_b32_e32 v96, v2
	v_mov_b32_e32 v97, v2
	v_mov_b32_e32 v98, v2
	v_mov_b32_e32 v99, v2
	v_mov_b32_e32 v100, v2
	v_mov_b32_e32 v101, v2
	v_mov_b32_e32 v102, v2
	v_mov_b32_e32 v103, v2
	v_mov_b32_e32 v104, v2
	v_mov_b32_e32 v105, v2
	v_mov_b32_e32 v106, v2
	v_mov_b32_e32 v107, v2
	v_mov_b32_e32 v108, v2
	v_mov_b32_e32 v109, v2
	v_mov_b32_e32 v110, v2
	v_mov_b32_e32 v111, v2
	v_mov_b32_e32 v112, v2
	v_mov_b32_e32 v113, v2
	v_mov_b32_e32 v114, v2
	v_mov_b32_e32 v115, v2
	v_mov_b32_e32 v116, v2
	v_mov_b32_e32 v117, v2
	v_mov_b32_e32 v118, v2
	v_mov_b32_e32 v119, v2
	v_mov_b32_e32 v120, v2
	v_mov_b32_e32 v121, v2
	v_mov_b32_e32 v122, v2
	v_mov_b32_e32 v123, v2
	v_mov_b32_e32 v124, v2
	v_mov_b32_e32 v125, v2
	v_mov_b32_e32 v126, v2
	v_mov_b32_e32 v127, v2
	v_mov_b32_e32 v128, v2
	v_mov_b32_e32 v129, v2
